# nt hint on the row1 adaLN-output (hx) stores, which are full-line writes
# baseline (speedup 1.0000x reference)
; DI void row1_phase(const Params& P, int combine_l, int norm_l, int r_begin) {
;     ...
;     if (combine_l < 0) {
;       const float* src = r < TC ? P.ctx + (size_t)r * D : P.x + (size_t)(r - TC) * D;
; #pragma unroll
;       for (int i = 0; i < 4; i++) xv[i] = *(const float4*)(src + i * 256 + lane * 4);
;     } else {
;       const float* xm = r < TC ? P.xcbuf + (size_t)r * D : P.out + (size_t)(r - TC) * D;
;       const half_t* y0 = P.yA + (size_t)(2 * r) * D; const half_t* y1 = y0 + D;
; #pragma unroll
;       for (int i = 0; i < 4; i++) { int c = i * 256 + lane * 4; xv[i] = *(const float4*)(xm + c); ya[i] = *(const h4*)(y0 + c); yb[i] = *(const h4*)(y1 + c); }
;     }
;   };
;   auto process = [&](int r, float4 (&xv)[4], h4 (&ya)[4], h4 (&yb)[4]) {
;     const int n = row_mod(r);
;     if (combine_l >= 0) {
;       float* xm = r < TC ? P.xcbuf + (size_t)r * D : P.out + (size_t)(r - TC) * D;
;       const float* g2 = P.mod + (size_t)(combine_l * 9 + n) * 6144 + 5 * 1024;
; #pragma unroll
;       for (int i = 0; i < 4; i++) {
;         int c = i * 256 + lane * 4;
;         float4 g = *(const float4*)(g2 + c); float4 t = xv[i];
;         t.x += g.x * ((float)ya[i][0] + (float)yb[i][0]); t.y += g.y * ((float)ya[i][1] + (float)yb[i][1]);
;         t.z += g.z * ((float)ya[i][2] + (float)yb[i][2]); t.w += g.w * ((float)ya[i][3] + (float)yb[i][3]);
;         *(float4*)(xm + c) = t; xv[i] = t;
;       }
;     }
;     if (norm_l >= 0) {
;       float ss = 0.f;
; #pragma unroll
;       for (int i = 0; i < 4; i++) ss += xv[i].x * xv[i].x + xv[i].y * xv[i].y + xv[i].z * xv[i].z + xv[i].w * xv[i].w;
.Lr1b_nr1:
	s_waitcnt vmcnt(44)
	v_accvgpr_read_b32 v54, a0
	v_accvgpr_read_b32 v55, a1
	v_accvgpr_read_b32 v56, a2
	v_accvgpr_read_b32 v57, a3
	v_accvgpr_read_b32 v58, a4
	v_accvgpr_read_b32 v59, a5
	v_accvgpr_read_b32 v60, a6
	v_accvgpr_read_b32 v61, a7
	v_accvgpr_read_b32 v62, a8
	v_accvgpr_read_b32 v63, a9
	v_accvgpr_read_b32 v64, a10
	v_accvgpr_read_b32 v65, a11
	v_accvgpr_read_b32 v66, a12
	v_accvgpr_read_b32 v67, a13
	v_accvgpr_read_b32 v68, a14
	v_accvgpr_read_b32 v69, a15
	v_accvgpr_read_b32 v70, a16
	v_accvgpr_read_b32 v71, a17
	v_accvgpr_read_b32 v72, a18
	v_accvgpr_read_b32 v73, a19
	v_accvgpr_read_b32 v74, a20
	v_accvgpr_read_b32 v75, a21
	v_accvgpr_read_b32 v76, a22
	v_accvgpr_read_b32 v77, a23
	v_accvgpr_read_b32 v78, a24
	v_accvgpr_read_b32 v79, a25
	v_accvgpr_read_b32 v80, a26
	v_accvgpr_read_b32 v81, a27
	v_accvgpr_read_b32 v82, a28
	v_accvgpr_read_b32 v83, a29
	v_accvgpr_read_b32 v84, a30
	v_accvgpr_read_b32 v85, a31
	s_lshl_b32 s10, s5, 12
	s_cmp_lt_u32 s5, 0x800
	s_cselect_b64 s[34:35], s[48:49], s[50:51]
	s_add_u32 s34, s34, s10
	s_addc_u32 s35, s35, 0
	s_lshr_b32 s10, s10, 1
	s_add_u32 s36, s54, s10
	s_addc_u32 s37, s55, 0
	s_cmp_lt_u32 s7, 0x800
	s_cselect_b64 s[60:61], s[48:49], s[50:51]
	s_lshl_b32 s10, s7, 12
	s_add_u32 s60, s60, s10
	s_addc_u32 s61, s61, 0
	global_load_dwordx4 a[0:3], v150, s[60:61] offset:0 nt
	global_load_dwordx4 a[4:7], v150, s[60:61] offset:1024 nt
	global_load_dwordx4 a[8:11], v150, s[60:61] offset:2048 nt
	global_load_dwordx4 a[12:15], v150, s[60:61] offset:3072 nt
	s_add_u32 s62, s52, s10
	s_addc_u32 s63, s53, 0
	global_load_dwordx2 a[16:17], v151, s[62:63] offset:0 nt
	global_load_dwordx2 a[18:19], v151, s[62:63] offset:512 nt
	global_load_dwordx2 a[20:21], v151, s[62:63] offset:1024 nt
	global_load_dwordx2 a[22:23], v151, s[62:63] offset:1536 nt
	global_load_dwordx2 a[24:25], v151, s[62:63] offset:2048 nt
	global_load_dwordx2 a[26:27], v151, s[62:63] offset:2560 nt
	global_load_dwordx2 a[28:29], v151, s[62:63] offset:3072 nt
	global_load_dwordx2 a[30:31], v151, s[62:63] offset:3584 nt
	s_add_u32 s7, s7, 1
	v_cvt_f32_f16_e32 v154, v70
	v_cvt_f32_f16_e32 v155, v78
	v_add_f32_e32 v154, v154, v155
	v_fmac_f32_e32 v54, v32, v154
	v_cvt_f32_f16_sdwa v156, v70 dst_sel:DWORD dst_unused:UNUSED_PAD src0_sel:WORD_1
	v_cvt_f32_f16_sdwa v157, v78 dst_sel:DWORD dst_unused:UNUSED_PAD src0_sel:WORD_1
	v_add_f32_e32 v156, v156, v157
	v_fmac_f32_e32 v55, v33, v156
	v_cvt_f32_f16_e32 v154, v71
	v_cvt_f32_f16_e32 v155, v79
	v_add_f32_e32 v154, v154, v155
	v_fmac_f32_e32 v56, v34, v154
	v_cvt_f32_f16_sdwa v156, v71 dst_sel:DWORD dst_unused:UNUSED_PAD src0_sel:WORD_1
	v_cvt_f32_f16_sdwa v157, v79 dst_sel:DWORD dst_unused:UNUSED_PAD src0_sel:WORD_1
	v_add_f32_e32 v156, v156, v157
	v_fmac_f32_e32 v57, v35, v156
	v_cvt_f32_f16_e32 v154, v72
	v_cvt_f32_f16_e32 v155, v80
	v_add_f32_e32 v154, v154, v155
	v_fmac_f32_e32 v58, v36, v154
	v_cvt_f32_f16_sdwa v156, v72 dst_sel:DWORD dst_unused:UNUSED_PAD src0_sel:WORD_1
	v_cvt_f32_f16_sdwa v157, v80 dst_sel:DWORD dst_unused:UNUSED_PAD src0_sel:WORD_1
	v_add_f32_e32 v156, v156, v157
	v_fmac_f32_e32 v59, v37, v156
	v_cvt_f32_f16_e32 v154, v73
	v_cvt_f32_f16_e32 v155, v81
	v_add_f32_e32 v154, v154, v155
	v_fmac_f32_e32 v60, v38, v154
	v_cvt_f32_f16_sdwa v156, v73 dst_sel:DWORD dst_unused:UNUSED_PAD src0_sel:WORD_1
	v_cvt_f32_f16_sdwa v157, v81 dst_sel:DWORD dst_unused:UNUSED_PAD src0_sel:WORD_1
	v_add_f32_e32 v156, v156, v157
	v_fmac_f32_e32 v61, v39, v156
	v_cvt_f32_f16_e32 v154, v74
	v_cvt_f32_f16_e32 v155, v82
	v_add_f32_e32 v154, v154, v155
	v_fmac_f32_e32 v62, v40, v154
	v_cvt_f32_f16_sdwa v156, v74 dst_sel:DWORD dst_unused:UNUSED_PAD src0_sel:WORD_1
	v_cvt_f32_f16_sdwa v157, v82 dst_sel:DWORD dst_unused:UNUSED_PAD src0_sel:WORD_1
	v_add_f32_e32 v156, v156, v157
	v_fmac_f32_e32 v63, v41, v156
	v_cvt_f32_f16_e32 v154, v75
	v_cvt_f32_f16_e32 v155, v83
	v_add_f32_e32 v154, v154, v155
	v_fmac_f32_e32 v64, v42, v154
	v_cvt_f32_f16_sdwa v156, v75 dst_sel:DWORD dst_unused:UNUSED_PAD src0_sel:WORD_1
	v_cvt_f32_f16_sdwa v157, v83 dst_sel:DWORD dst_unused:UNUSED_PAD src0_sel:WORD_1
	v_add_f32_e32 v156, v156, v157
	v_fmac_f32_e32 v65, v43, v156
	v_cvt_f32_f16_e32 v154, v76
	v_cvt_f32_f16_e32 v155, v84
	v_add_f32_e32 v154, v154, v155
	v_fmac_f32_e32 v66, v44, v154
	v_cvt_f32_f16_sdwa v156, v76 dst_sel:DWORD dst_unused:UNUSED_PAD src0_sel:WORD_1
	v_cvt_f32_f16_sdwa v157, v84 dst_sel:DWORD dst_unused:UNUSED_PAD src0_sel:WORD_1
	v_add_f32_e32 v156, v156, v157
	v_fmac_f32_e32 v67, v45, v156
	v_cvt_f32_f16_e32 v154, v77
	v_cvt_f32_f16_e32 v155, v85
	v_add_f32_e32 v154, v154, v155
	v_fmac_f32_e32 v68, v46, v154
	v_cvt_f32_f16_sdwa v156, v77 dst_sel:DWORD dst_unused:UNUSED_PAD src0_sel:WORD_1
	v_cvt_f32_f16_sdwa v157, v85 dst_sel:DWORD dst_unused:UNUSED_PAD src0_sel:WORD_1
	v_add_f32_e32 v156, v156, v157
	v_fmac_f32_e32 v69, v47, v156
	global_store_dwordx4 v150, v[54:57], s[34:35] offset:0
	global_store_dwordx4 v150, v[58:61], s[34:35] offset:1024
	global_store_dwordx4 v150, v[62:65], s[34:35] offset:2048
	global_store_dwordx4 v150, v[66:69], s[34:35] offset:3072
	v_mul_f32_e32 v152, v54, v54
	v_mul_f32_e32 v153, v55, v55
	v_fmac_f32_e32 v152, v56, v56
	v_fmac_f32_e32 v153, v57, v57
	v_fmac_f32_e32 v152, v58, v58
	v_fmac_f32_e32 v153, v59, v59
	v_fmac_f32_e32 v152, v60, v60
	v_fmac_f32_e32 v153, v61, v61
	v_fmac_f32_e32 v152, v62, v62
	v_fmac_f32_e32 v153, v63, v63
	v_fmac_f32_e32 v152, v64, v64
	v_fmac_f32_e32 v153, v65, v65
	v_fmac_f32_e32 v152, v66, v66
	v_fmac_f32_e32 v153, v67, v67
	v_fmac_f32_e32 v152, v68, v68
	v_fmac_f32_e32 v153, v69, v69
	v_add_f32_e32 v152, v152, v153
; DI void row1_phase(const Params& P, int combine_l, int norm_l, int r_begin) {
;     ...
;       float ss = 0.f;
; #pragma unroll
;       for (int i = 0; i < 4; i++) ss += xv[i].x * xv[i].x + xv[i].y * xv[i].y + xv[i].z * xv[i].z + xv[i].w * xv[i].w;
;       ss = wave_sum(ss);
;       const float rstd = rsqrtf(ss * (1.f / 1024.f) + EPS);
;       const float* g = P.norm1_g + norm_l * 1024;
;       const float* sh = P.mod + (size_t)(norm_l * 9 + n) * 6144; const float* sc = sh + 1024;
; #pragma unroll
;       for (int i = 0; i < 4; i++) {
;         int c = i * 256 + lane * 4;
;         float4 gg = *(const float4*)(g + c), s1 = *(const float4*)(sc + c), s0 = *(const float4*)(sh + c);
;         h4 o;
;         o[0] = (half_t)(xv[i].x * rstd * gg.x * (1.f + s1.x) + s0.x); o[1] = (half_t)(xv[i].y * rstd * gg.y * (1.f + s1.y) + s0.y);
;         o[2] = (half_t)(xv[i].z * rstd * gg.z * (1.f + s1.z) + s0.z); o[3] = (half_t)(xv[i].w * rstd * gg.w * (1.f + s1.w) + s0.w);
;         *(h4*)(P.hx + (size_t)r * D + c) = o;
;       }
	s_nop 1
	v_add_f32_dpp v152, v152, v152 row_ror:8 row_mask:0xf bank_mask:0xf
	s_nop 1
	v_add_f32_dpp v152, v152, v152 row_ror:4 row_mask:0xf bank_mask:0xf
	s_nop 1
	v_add_f32_dpp v152, v152, v152 row_ror:2 row_mask:0xf bank_mask:0xf
	s_nop 1
	v_add_f32_dpp v152, v152, v152 row_ror:1 row_mask:0xf bank_mask:0xf
	s_nop 1
	v_readlane_b32 s22, v152, 0
	v_readlane_b32 s23, v152, 16
	v_readlane_b32 s32, v152, 32
	v_readlane_b32 s99, v152, 48
	v_mov_b32_e32 v152, s22
	v_add_f32_e32 v152, s23, v152
	v_add_f32_e32 v152, s32, v152
	v_add_f32_e32 v152, s99, v152
	v_mov_b32_e32 v153, 0x358637bd
	v_fmamk_f32 v152, v152, 0x3a800000, v153
	v_rsq_f32_e32 v152, v152
	s_nop 1
	v_mul_f32_e32 v54, v54, v152
	v_mul_f32_e32 v55, v55, v152
	v_mul_f32_e32 v56, v56, v152
	v_mul_f32_e32 v57, v57, v152
	v_mul_f32_e32 v58, v58, v152
	v_mul_f32_e32 v59, v59, v152
	v_mul_f32_e32 v60, v60, v152
	v_mul_f32_e32 v61, v61, v152
	v_mul_f32_e32 v62, v62, v152
	v_mul_f32_e32 v63, v63, v152
	v_mul_f32_e32 v64, v64, v152
	v_mul_f32_e32 v65, v65, v152
	v_mul_f32_e32 v66, v66, v152
	v_mul_f32_e32 v67, v67, v152
	v_mul_f32_e32 v68, v68, v152
	v_mul_f32_e32 v69, v69, v152
	v_fma_f32 v54, v54, v0, v16
	v_fma_f32 v55, v55, v1, v17
	v_fma_f32 v56, v56, v2, v18
	v_fma_f32 v57, v57, v3, v19
	v_fma_f32 v58, v58, v4, v20
	v_fma_f32 v59, v59, v5, v21
	v_fma_f32 v60, v60, v6, v22
	v_fma_f32 v61, v61, v7, v23
	v_fma_f32 v62, v62, v8, v24
	v_fma_f32 v63, v63, v9, v25
	v_fma_f32 v64, v64, v10, v26
	v_fma_f32 v65, v65, v11, v27
	v_fma_f32 v66, v66, v12, v28
	v_fma_f32 v67, v67, v13, v29
	v_fma_f32 v68, v68, v14, v30
	v_fma_f32 v69, v69, v15, v31
	v_cvt_pk_f16_f32 v70, v54, v55
	v_cvt_pk_f16_f32 v71, v56, v57
	v_cvt_pk_f16_f32 v72, v58, v59
	v_cvt_pk_f16_f32 v73, v60, v61
	v_cvt_pk_f16_f32 v74, v62, v63
	v_cvt_pk_f16_f32 v75, v64, v65
	v_cvt_pk_f16_f32 v76, v66, v67
	v_cvt_pk_f16_f32 v77, v68, v69
	global_store_dwordx2 v151, v[70:71], s[36:37] offset:0 nt
	global_store_dwordx2 v151, v[72:73], s[36:37] offset:512 nt
	global_store_dwordx2 v151, v[74:75], s[36:37] offset:1024 nt
	global_store_dwordx2 v151, v[76:77], s[36:37] offset:1536 nt
	s_add_u32 s5, s5, 1
	s_sub_u32 s9, s5, 0x800
	s_lshr_b32 s9, s9, 13
	s_cmp_lt_u32 s5, 0x800
	s_cselect_b32 s9, 8, s9
	s_cmp_eq_u32 s9, s8
	s_cbranch_scc1 .Lr1b_nr2
	s_mov_b32 s8, s9
	s_waitcnt vmcnt(0)
	s_add_u32 s10, s9, 9
	s_mul_i32 s10, s10, 0x6000
	s_add_u32 s38, s56, s10
	s_addc_u32 s39, s57, 0
	global_load_dwordx4 v[54:57], v150, s[58:59] offset:0
	global_load_dwordx4 v[58:61], v150, s[58:59] offset:1024
	global_load_dwordx4 v[62:65], v150, s[58:59] offset:2048
	global_load_dwordx4 v[66:69], v150, s[58:59] offset:3072
	s_add_u32 s44, s38, 0x1000
	s_addc_u32 s45, s39, 0
	global_load_dwordx4 v[70:73], v150, s[44:45] offset:0
	global_load_dwordx4 v[74:77], v150, s[44:45] offset:1024
	global_load_dwordx4 v[78:81], v150, s[44:45] offset:2048
	global_load_dwordx4 v[82:85], v150, s[44:45] offset:3072
	global_load_dwordx4 v[16:19], v150, s[38:39] offset:0
	global_load_dwordx4 v[20:23], v150, s[38:39] offset:1024
	global_load_dwordx4 v[24:27], v150, s[38:39] offset:2048
	global_load_dwordx4 v[28:31], v150, s[38:39] offset:3072
	s_add_u32 s10, s9, 0
	s_mul_i32 s10, s10, 0x6000
	s_add_u32 s10, s10, 0x5000
	s_add_u32 s38, s56, s10
	s_addc_u32 s39, s57, 0
	global_load_dwordx4 v[32:35], v150, s[38:39] offset:0
	global_load_dwordx4 v[36:39], v150, s[38:39] offset:1024
	global_load_dwordx4 v[40:43], v150, s[38:39] offset:2048
	global_load_dwordx4 v[44:47], v150, s[38:39] offset:3072
	s_waitcnt vmcnt(0)
	v_add_f32_e32 v70, 1.0, v70
	v_add_f32_e32 v71, 1.0, v71
	v_add_f32_e32 v72, 1.0, v72
	v_add_f32_e32 v73, 1.0, v73
	v_add_f32_e32 v74, 1.0, v74
	v_add_f32_e32 v75, 1.0, v75
	v_add_f32_e32 v76, 1.0, v76
	v_add_f32_e32 v77, 1.0, v77
	v_add_f32_e32 v78, 1.0, v78
	v_add_f32_e32 v79, 1.0, v79
	v_add_f32_e32 v80, 1.0, v80
	v_add_f32_e32 v81, 1.0, v81
	v_add_f32_e32 v82, 1.0, v82
	v_add_f32_e32 v83, 1.0, v83
	v_add_f32_e32 v84, 1.0, v84
	v_add_f32_e32 v85, 1.0, v85
	v_mul_f32_e32 v0, v54, v70
	v_mul_f32_e32 v1, v55, v71
	v_mul_f32_e32 v2, v56, v72
	v_mul_f32_e32 v3, v57, v73
	v_mul_f32_e32 v4, v58, v74
	v_mul_f32_e32 v5, v59, v75
	v_mul_f32_e32 v6, v60, v76
	v_mul_f32_e32 v7, v61, v77
	v_mul_f32_e32 v8, v62, v78
	v_mul_f32_e32 v9, v63, v79
	v_mul_f32_e32 v10, v64, v80
	v_mul_f32_e32 v11, v65, v81
	v_mul_f32_e32 v12, v66, v82
	v_mul_f32_e32 v13, v67, v83
	v_mul_f32_e32 v14, v68, v84
	v_mul_f32_e32 v15, v69, v85
; DI void row1_phase(const Params& P, int combine_l, int norm_l, int r_begin) {
;     ...
;     if (combine_l < 0) {
;       const float* src = r < TC ? P.ctx + (size_t)r * D : P.x + (size_t)(r - TC) * D;
; #pragma unroll
;       for (int i = 0; i < 4; i++) xv[i] = *(const float4*)(src + i * 256 + lane * 4);
;     } else {
;       const float* xm = r < TC ? P.xcbuf + (size_t)r * D : P.out + (size_t)(r - TC) * D;
;       const half_t* y0 = P.yA + (size_t)(2 * r) * D; const half_t* y1 = y0 + D;
; #pragma unroll
;       for (int i = 0; i < 4; i++) { int c = i * 256 + lane * 4; xv[i] = *(const float4*)(xm + c); ya[i] = *(const h4*)(y0 + c); yb[i] = *(const h4*)(y1 + c); }
;     }
;   };
;   auto process = [&](int r, float4 (&xv)[4], h4 (&ya)[4], h4 (&yb)[4]) {
;     const int n = row_mod(r);
;     if (combine_l >= 0) {
;       float* xm = r < TC ? P.xcbuf + (size_t)r * D : P.out + (size_t)(r - TC) * D;
;       const float* g2 = P.mod + (size_t)(combine_l * 9 + n) * 6144 + 5 * 1024;
; #pragma unroll
;       for (int i = 0; i < 4; i++) {
;         int c = i * 256 + lane * 4;
;         float4 g = *(const float4*)(g2 + c); float4 t = xv[i];
;         t.x += g.x * ((float)ya[i][0] + (float)yb[i][0]); t.y += g.y * ((float)ya[i][1] + (float)yb[i][1]);
;         t.z += g.z * ((float)ya[i][2] + (float)yb[i][2]); t.w += g.w * ((float)ya[i][3] + (float)yb[i][3]);
;         *(float4*)(xm + c) = t; xv[i] = t;
;       }
;     }
;     if (norm_l >= 0) {
;       float ss = 0.f;
; #pragma unroll
;       for (int i = 0; i < 4; i++) ss += xv[i].x * xv[i].x + xv[i].y * xv[i].y + xv[i].z * xv[i].z + xv[i].w * xv[i].w;
.Lr1b_nr2:
	s_waitcnt vmcnt(44)
	v_accvgpr_read_b32 v54, a32
	v_accvgpr_read_b32 v55, a33
	v_accvgpr_read_b32 v56, a34
	v_accvgpr_read_b32 v57, a35
	v_accvgpr_read_b32 v58, a36
	v_accvgpr_read_b32 v59, a37
	v_accvgpr_read_b32 v60, a38
	v_accvgpr_read_b32 v61, a39
	v_accvgpr_read_b32 v62, a40
	v_accvgpr_read_b32 v63, a41
	v_accvgpr_read_b32 v64, a42
	v_accvgpr_read_b32 v65, a43
	v_accvgpr_read_b32 v66, a44
	v_accvgpr_read_b32 v67, a45
	v_accvgpr_read_b32 v68, a46
	v_accvgpr_read_b32 v69, a47
	v_accvgpr_read_b32 v70, a48
	v_accvgpr_read_b32 v71, a49
	v_accvgpr_read_b32 v72, a50
	v_accvgpr_read_b32 v73, a51
	v_accvgpr_read_b32 v74, a52
	v_accvgpr_read_b32 v75, a53
	v_accvgpr_read_b32 v76, a54
	v_accvgpr_read_b32 v77, a55
	v_accvgpr_read_b32 v78, a56
	v_accvgpr_read_b32 v79, a57
	v_accvgpr_read_b32 v80, a58
	v_accvgpr_read_b32 v81, a59
	v_accvgpr_read_b32 v82, a60
	v_accvgpr_read_b32 v83, a61
	v_accvgpr_read_b32 v84, a62
	v_accvgpr_read_b32 v85, a63
	s_lshl_b32 s10, s5, 12
	s_cmp_lt_u32 s5, 0x800
	s_cselect_b64 s[34:35], s[48:49], s[50:51]
	s_add_u32 s34, s34, s10
	s_addc_u32 s35, s35, 0
	s_lshr_b32 s10, s10, 1
	s_add_u32 s36, s54, s10
	s_addc_u32 s37, s55, 0
	s_cmp_lt_u32 s7, 0x800
	s_cselect_b64 s[60:61], s[48:49], s[50:51]
	s_lshl_b32 s10, s7, 12
	s_add_u32 s60, s60, s10
	s_addc_u32 s61, s61, 0
	global_load_dwordx4 a[32:35], v150, s[60:61] offset:0 nt
	global_load_dwordx4 a[36:39], v150, s[60:61] offset:1024 nt
	global_load_dwordx4 a[40:43], v150, s[60:61] offset:2048 nt
	global_load_dwordx4 a[44:47], v150, s[60:61] offset:3072 nt
	s_add_u32 s62, s52, s10
	s_addc_u32 s63, s53, 0
	global_load_dwordx2 a[48:49], v151, s[62:63] offset:0 nt
	global_load_dwordx2 a[50:51], v151, s[62:63] offset:512 nt
	global_load_dwordx2 a[52:53], v151, s[62:63] offset:1024 nt
	global_load_dwordx2 a[54:55], v151, s[62:63] offset:1536 nt
	global_load_dwordx2 a[56:57], v151, s[62:63] offset:2048 nt
	global_load_dwordx2 a[58:59], v151, s[62:63] offset:2560 nt
	global_load_dwordx2 a[60:61], v151, s[62:63] offset:3072 nt
	global_load_dwordx2 a[62:63], v151, s[62:63] offset:3584 nt
	s_add_u32 s7, s7, 1
	v_cvt_f32_f16_e32 v154, v70
	v_cvt_f32_f16_e32 v155, v78
	v_add_f32_e32 v154, v154, v155
	v_fmac_f32_e32 v54, v32, v154
	v_cvt_f32_f16_sdwa v156, v70 dst_sel:DWORD dst_unused:UNUSED_PAD src0_sel:WORD_1
	v_cvt_f32_f16_sdwa v157, v78 dst_sel:DWORD dst_unused:UNUSED_PAD src0_sel:WORD_1
	v_add_f32_e32 v156, v156, v157
	v_fmac_f32_e32 v55, v33, v156
	v_cvt_f32_f16_e32 v154, v71
	v_cvt_f32_f16_e32 v155, v79
	v_add_f32_e32 v154, v154, v155
	v_fmac_f32_e32 v56, v34, v154
	v_cvt_f32_f16_sdwa v156, v71 dst_sel:DWORD dst_unused:UNUSED_PAD src0_sel:WORD_1
	v_cvt_f32_f16_sdwa v157, v79 dst_sel:DWORD dst_unused:UNUSED_PAD src0_sel:WORD_1
	v_add_f32_e32 v156, v156, v157
	v_fmac_f32_e32 v57, v35, v156
	v_cvt_f32_f16_e32 v154, v72
	v_cvt_f32_f16_e32 v155, v80
	v_add_f32_e32 v154, v154, v155
	v_fmac_f32_e32 v58, v36, v154
	v_cvt_f32_f16_sdwa v156, v72 dst_sel:DWORD dst_unused:UNUSED_PAD src0_sel:WORD_1
	v_cvt_f32_f16_sdwa v157, v80 dst_sel:DWORD dst_unused:UNUSED_PAD src0_sel:WORD_1
	v_add_f32_e32 v156, v156, v157
	v_fmac_f32_e32 v59, v37, v156
	v_cvt_f32_f16_e32 v154, v73
	v_cvt_f32_f16_e32 v155, v81
	v_add_f32_e32 v154, v154, v155
	v_fmac_f32_e32 v60, v38, v154
	v_cvt_f32_f16_sdwa v156, v73 dst_sel:DWORD dst_unused:UNUSED_PAD src0_sel:WORD_1
	v_cvt_f32_f16_sdwa v157, v81 dst_sel:DWORD dst_unused:UNUSED_PAD src0_sel:WORD_1
	v_add_f32_e32 v156, v156, v157
	v_fmac_f32_e32 v61, v39, v156
	v_cvt_f32_f16_e32 v154, v74
	v_cvt_f32_f16_e32 v155, v82
	v_add_f32_e32 v154, v154, v155
	v_fmac_f32_e32 v62, v40, v154
	v_cvt_f32_f16_sdwa v156, v74 dst_sel:DWORD dst_unused:UNUSED_PAD src0_sel:WORD_1
	v_cvt_f32_f16_sdwa v157, v82 dst_sel:DWORD dst_unused:UNUSED_PAD src0_sel:WORD_1
	v_add_f32_e32 v156, v156, v157
	v_fmac_f32_e32 v63, v41, v156
	v_cvt_f32_f16_e32 v154, v75
	v_cvt_f32_f16_e32 v155, v83
	v_add_f32_e32 v154, v154, v155
	v_fmac_f32_e32 v64, v42, v154
	v_cvt_f32_f16_sdwa v156, v75 dst_sel:DWORD dst_unused:UNUSED_PAD src0_sel:WORD_1
	v_cvt_f32_f16_sdwa v157, v83 dst_sel:DWORD dst_unused:UNUSED_PAD src0_sel:WORD_1
	v_add_f32_e32 v156, v156, v157
	v_fmac_f32_e32 v65, v43, v156
	v_cvt_f32_f16_e32 v154, v76
	v_cvt_f32_f16_e32 v155, v84
	v_add_f32_e32 v154, v154, v155
	v_fmac_f32_e32 v66, v44, v154
	v_cvt_f32_f16_sdwa v156, v76 dst_sel:DWORD dst_unused:UNUSED_PAD src0_sel:WORD_1
	v_cvt_f32_f16_sdwa v157, v84 dst_sel:DWORD dst_unused:UNUSED_PAD src0_sel:WORD_1
	v_add_f32_e32 v156, v156, v157
	v_fmac_f32_e32 v67, v45, v156
	v_cvt_f32_f16_e32 v154, v77
	v_cvt_f32_f16_e32 v155, v85
	v_add_f32_e32 v154, v154, v155
	v_fmac_f32_e32 v68, v46, v154
	v_cvt_f32_f16_sdwa v156, v77 dst_sel:DWORD dst_unused:UNUSED_PAD src0_sel:WORD_1
	v_cvt_f32_f16_sdwa v157, v85 dst_sel:DWORD dst_unused:UNUSED_PAD src0_sel:WORD_1
	v_add_f32_e32 v156, v156, v157
	v_fmac_f32_e32 v69, v47, v156
	global_store_dwordx4 v150, v[54:57], s[34:35] offset:0
	global_store_dwordx4 v150, v[58:61], s[34:35] offset:1024
	global_store_dwordx4 v150, v[62:65], s[34:35] offset:2048
	global_store_dwordx4 v150, v[66:69], s[34:35] offset:3072
	v_mul_f32_e32 v152, v54, v54
	v_mul_f32_e32 v153, v55, v55
	v_fmac_f32_e32 v152, v56, v56
	v_fmac_f32_e32 v153, v57, v57
	v_fmac_f32_e32 v152, v58, v58
	v_fmac_f32_e32 v153, v59, v59
	v_fmac_f32_e32 v152, v60, v60
	v_fmac_f32_e32 v153, v61, v61
	v_fmac_f32_e32 v152, v62, v62
	v_fmac_f32_e32 v153, v63, v63
	v_fmac_f32_e32 v152, v64, v64
	v_fmac_f32_e32 v153, v65, v65
	v_fmac_f32_e32 v152, v66, v66
	v_fmac_f32_e32 v153, v67, v67
	v_fmac_f32_e32 v152, v68, v68
	v_fmac_f32_e32 v153, v69, v69
	v_add_f32_e32 v152, v152, v153
; DI void row1_phase(const Params& P, int combine_l, int norm_l, int r_begin) {
;     ...
;       float ss = 0.f;
; #pragma unroll
;       for (int i = 0; i < 4; i++) ss += xv[i].x * xv[i].x + xv[i].y * xv[i].y + xv[i].z * xv[i].z + xv[i].w * xv[i].w;
;       ss = wave_sum(ss);
;       const float rstd = rsqrtf(ss * (1.f / 1024.f) + EPS);
;       const float* g = P.norm1_g + norm_l * 1024;
;       const float* sh = P.mod + (size_t)(norm_l * 9 + n) * 6144; const float* sc = sh + 1024;
; #pragma unroll
;       for (int i = 0; i < 4; i++) {
;         int c = i * 256 + lane * 4;
;         float4 gg = *(const float4*)(g + c), s1 = *(const float4*)(sc + c), s0 = *(const float4*)(sh + c);
;         h4 o;
;         o[0] = (half_t)(xv[i].x * rstd * gg.x * (1.f + s1.x) + s0.x); o[1] = (half_t)(xv[i].y * rstd * gg.y * (1.f + s1.y) + s0.y);
;         o[2] = (half_t)(xv[i].z * rstd * gg.z * (1.f + s1.z) + s0.z); o[3] = (half_t)(xv[i].w * rstd * gg.w * (1.f + s1.w) + s0.w);
;         *(h4*)(P.hx + (size_t)r * D + c) = o;
;       }
	s_nop 1
	v_add_f32_dpp v152, v152, v152 row_ror:8 row_mask:0xf bank_mask:0xf
	s_nop 1
	v_add_f32_dpp v152, v152, v152 row_ror:4 row_mask:0xf bank_mask:0xf
	s_nop 1
	v_add_f32_dpp v152, v152, v152 row_ror:2 row_mask:0xf bank_mask:0xf
	s_nop 1
	v_add_f32_dpp v152, v152, v152 row_ror:1 row_mask:0xf bank_mask:0xf
	s_nop 1
	v_readlane_b32 s22, v152, 0
	v_readlane_b32 s23, v152, 16
	v_readlane_b32 s32, v152, 32
	v_readlane_b32 s99, v152, 48
	v_mov_b32_e32 v152, s22
	v_add_f32_e32 v152, s23, v152
	v_add_f32_e32 v152, s32, v152
	v_add_f32_e32 v152, s99, v152
	v_mov_b32_e32 v153, 0x358637bd
	v_fmamk_f32 v152, v152, 0x3a800000, v153
	v_rsq_f32_e32 v152, v152
	s_nop 1
	v_mul_f32_e32 v54, v54, v152
	v_mul_f32_e32 v55, v55, v152
	v_mul_f32_e32 v56, v56, v152
	v_mul_f32_e32 v57, v57, v152
	v_mul_f32_e32 v58, v58, v152
	v_mul_f32_e32 v59, v59, v152
	v_mul_f32_e32 v60, v60, v152
	v_mul_f32_e32 v61, v61, v152
	v_mul_f32_e32 v62, v62, v152
	v_mul_f32_e32 v63, v63, v152
	v_mul_f32_e32 v64, v64, v152
	v_mul_f32_e32 v65, v65, v152
	v_mul_f32_e32 v66, v66, v152
	v_mul_f32_e32 v67, v67, v152
	v_mul_f32_e32 v68, v68, v152
	v_mul_f32_e32 v69, v69, v152
	v_fma_f32 v54, v54, v0, v16
	v_fma_f32 v55, v55, v1, v17
	v_fma_f32 v56, v56, v2, v18
	v_fma_f32 v57, v57, v3, v19
	v_fma_f32 v58, v58, v4, v20
	v_fma_f32 v59, v59, v5, v21
	v_fma_f32 v60, v60, v6, v22
	v_fma_f32 v61, v61, v7, v23
	v_fma_f32 v62, v62, v8, v24
	v_fma_f32 v63, v63, v9, v25
	v_fma_f32 v64, v64, v10, v26
	v_fma_f32 v65, v65, v11, v27
	v_fma_f32 v66, v66, v12, v28
	v_fma_f32 v67, v67, v13, v29
	v_fma_f32 v68, v68, v14, v30
	v_fma_f32 v69, v69, v15, v31
	v_cvt_pk_f16_f32 v70, v54, v55
	v_cvt_pk_f16_f32 v71, v56, v57
	v_cvt_pk_f16_f32 v72, v58, v59
	v_cvt_pk_f16_f32 v73, v60, v61
	v_cvt_pk_f16_f32 v74, v62, v63
	v_cvt_pk_f16_f32 v75, v64, v65
	v_cvt_pk_f16_f32 v76, v66, v67
	v_cvt_pk_f16_f32 v77, v68, v69
	global_store_dwordx2 v151, v[70:71], s[36:37] offset:0 nt
	global_store_dwordx2 v151, v[72:73], s[36:37] offset:512 nt
	global_store_dwordx2 v151, v[74:75], s[36:37] offset:1024 nt
	global_store_dwordx2 v151, v[76:77], s[36:37] offset:1536 nt
	s_add_u32 s5, s5, 1
	s_sub_u32 s9, s5, 0x800
	s_lshr_b32 s9, s9, 13
	s_cmp_lt_u32 s5, 0x800
	s_cselect_b32 s9, 8, s9
	s_cmp_eq_u32 s9, s8
	s_cbranch_scc1 .Lr1b_nr3
	s_mov_b32 s8, s9
	s_waitcnt vmcnt(0)
	s_add_u32 s10, s9, 9
	s_mul_i32 s10, s10, 0x6000
	s_add_u32 s38, s56, s10
	s_addc_u32 s39, s57, 0
	global_load_dwordx4 v[54:57], v150, s[58:59] offset:0
	global_load_dwordx4 v[58:61], v150, s[58:59] offset:1024
	global_load_dwordx4 v[62:65], v150, s[58:59] offset:2048
	global_load_dwordx4 v[66:69], v150, s[58:59] offset:3072
	s_add_u32 s44, s38, 0x1000
	s_addc_u32 s45, s39, 0
	global_load_dwordx4 v[70:73], v150, s[44:45] offset:0
	global_load_dwordx4 v[74:77], v150, s[44:45] offset:1024
	global_load_dwordx4 v[78:81], v150, s[44:45] offset:2048
	global_load_dwordx4 v[82:85], v150, s[44:45] offset:3072
	global_load_dwordx4 v[16:19], v150, s[38:39] offset:0
	global_load_dwordx4 v[20:23], v150, s[38:39] offset:1024
	global_load_dwordx4 v[24:27], v150, s[38:39] offset:2048
	global_load_dwordx4 v[28:31], v150, s[38:39] offset:3072
	s_add_u32 s10, s9, 0
	s_mul_i32 s10, s10, 0x6000
	s_add_u32 s10, s10, 0x5000
	s_add_u32 s38, s56, s10
	s_addc_u32 s39, s57, 0
	global_load_dwordx4 v[32:35], v150, s[38:39] offset:0
	global_load_dwordx4 v[36:39], v150, s[38:39] offset:1024
	global_load_dwordx4 v[40:43], v150, s[38:39] offset:2048
	global_load_dwordx4 v[44:47], v150, s[38:39] offset:3072
	s_waitcnt vmcnt(0)
	v_add_f32_e32 v70, 1.0, v70
	v_add_f32_e32 v71, 1.0, v71
	v_add_f32_e32 v72, 1.0, v72
	v_add_f32_e32 v73, 1.0, v73
	v_add_f32_e32 v74, 1.0, v74
	v_add_f32_e32 v75, 1.0, v75
	v_add_f32_e32 v76, 1.0, v76
	v_add_f32_e32 v77, 1.0, v77
	v_add_f32_e32 v78, 1.0, v78
	v_add_f32_e32 v79, 1.0, v79
	v_add_f32_e32 v80, 1.0, v80
	v_add_f32_e32 v81, 1.0, v81
	v_add_f32_e32 v82, 1.0, v82
	v_add_f32_e32 v83, 1.0, v83
	v_add_f32_e32 v84, 1.0, v84
	v_add_f32_e32 v85, 1.0, v85
	v_mul_f32_e32 v0, v54, v70
	v_mul_f32_e32 v1, v55, v71
	v_mul_f32_e32 v2, v56, v72
	v_mul_f32_e32 v3, v57, v73
	v_mul_f32_e32 v4, v58, v74
	v_mul_f32_e32 v5, v59, v75
	v_mul_f32_e32 v6, v60, v76
	v_mul_f32_e32 v7, v61, v77
	v_mul_f32_e32 v8, v62, v78
	v_mul_f32_e32 v9, v63, v79
	v_mul_f32_e32 v10, v64, v80
	v_mul_f32_e32 v11, v65, v81
	v_mul_f32_e32 v12, v66, v82
	v_mul_f32_e32 v13, v67, v83
	v_mul_f32_e32 v14, v68, v84
	v_mul_f32_e32 v15, v69, v85
; DI void row1_phase(const Params& P, int combine_l, int norm_l, int r_begin) {
;     ...
;     if (combine_l < 0) {
;       const float* src = r < TC ? P.ctx + (size_t)r * D : P.x + (size_t)(r - TC) * D;
; #pragma unroll
;       for (int i = 0; i < 4; i++) xv[i] = *(const float4*)(src + i * 256 + lane * 4);
;     } else {
;       const float* xm = r < TC ? P.xcbuf + (size_t)r * D : P.out + (size_t)(r - TC) * D;
;       const half_t* y0 = P.yA + (size_t)(2 * r) * D; const half_t* y1 = y0 + D;
; #pragma unroll
;       for (int i = 0; i < 4; i++) { int c = i * 256 + lane * 4; xv[i] = *(const float4*)(xm + c); ya[i] = *(const h4*)(y0 + c); yb[i] = *(const h4*)(y1 + c); }
;     }
;   };
;   auto process = [&](int r, float4 (&xv)[4], h4 (&ya)[4], h4 (&yb)[4]) {
;     const int n = row_mod(r);
;     if (combine_l >= 0) {
;       float* xm = r < TC ? P.xcbuf + (size_t)r * D : P.out + (size_t)(r - TC) * D;
;       const float* g2 = P.mod + (size_t)(combine_l * 9 + n) * 6144 + 5 * 1024;
; #pragma unroll
;       for (int i = 0; i < 4; i++) {
;         int c = i * 256 + lane * 4;
;         float4 g = *(const float4*)(g2 + c); float4 t = xv[i];
;         t.x += g.x * ((float)ya[i][0] + (float)yb[i][0]); t.y += g.y * ((float)ya[i][1] + (float)yb[i][1]);
;         t.z += g.z * ((float)ya[i][2] + (float)yb[i][2]); t.w += g.w * ((float)ya[i][3] + (float)yb[i][3]);
;         *(float4*)(xm + c) = t; xv[i] = t;
;       }
;     }
;     if (norm_l >= 0) {
;       float ss = 0.f;
; #pragma unroll
;       for (int i = 0; i < 4; i++) ss += xv[i].x * xv[i].x + xv[i].y * xv[i].y + xv[i].z * xv[i].z + xv[i].w * xv[i].w;
.Lr1b_nr3:
	s_waitcnt vmcnt(44)
	v_accvgpr_read_b32 v54, a64
	v_accvgpr_read_b32 v55, a65
	v_accvgpr_read_b32 v56, a66
	v_accvgpr_read_b32 v57, a67
	v_accvgpr_read_b32 v58, a68
	v_accvgpr_read_b32 v59, a69
	v_accvgpr_read_b32 v60, a70
	v_accvgpr_read_b32 v61, a71
	v_accvgpr_read_b32 v62, a72
	v_accvgpr_read_b32 v63, a73
	v_accvgpr_read_b32 v64, a74
	v_accvgpr_read_b32 v65, a75
	v_accvgpr_read_b32 v66, a76
	v_accvgpr_read_b32 v67, a77
	v_accvgpr_read_b32 v68, a78
	v_accvgpr_read_b32 v69, a79
	v_accvgpr_read_b32 v70, a80
	v_accvgpr_read_b32 v71, a81
	v_accvgpr_read_b32 v72, a82
	v_accvgpr_read_b32 v73, a83
	v_accvgpr_read_b32 v74, a84
	v_accvgpr_read_b32 v75, a85
	v_accvgpr_read_b32 v76, a86
	v_accvgpr_read_b32 v77, a87
	v_accvgpr_read_b32 v78, a88
	v_accvgpr_read_b32 v79, a89
	v_accvgpr_read_b32 v80, a90
	v_accvgpr_read_b32 v81, a91
	v_accvgpr_read_b32 v82, a92
	v_accvgpr_read_b32 v83, a93
	v_accvgpr_read_b32 v84, a94
	v_accvgpr_read_b32 v85, a95
	s_lshl_b32 s10, s5, 12
	s_cmp_lt_u32 s5, 0x800
	s_cselect_b64 s[34:35], s[48:49], s[50:51]
	s_add_u32 s34, s34, s10
	s_addc_u32 s35, s35, 0
	s_lshr_b32 s10, s10, 1
	s_add_u32 s36, s54, s10
	s_addc_u32 s37, s55, 0
	s_cmp_lt_u32 s7, 0x800
	s_cselect_b64 s[60:61], s[48:49], s[50:51]
	s_lshl_b32 s10, s7, 12
	s_add_u32 s60, s60, s10
	s_addc_u32 s61, s61, 0
	global_load_dwordx4 a[64:67], v150, s[60:61] offset:0 nt
	global_load_dwordx4 a[68:71], v150, s[60:61] offset:1024 nt
	global_load_dwordx4 a[72:75], v150, s[60:61] offset:2048 nt
	global_load_dwordx4 a[76:79], v150, s[60:61] offset:3072 nt
	s_add_u32 s62, s52, s10
	s_addc_u32 s63, s53, 0
	global_load_dwordx2 a[80:81], v151, s[62:63] offset:0 nt
	global_load_dwordx2 a[82:83], v151, s[62:63] offset:512 nt
	global_load_dwordx2 a[84:85], v151, s[62:63] offset:1024 nt
	global_load_dwordx2 a[86:87], v151, s[62:63] offset:1536 nt
	global_load_dwordx2 a[88:89], v151, s[62:63] offset:2048 nt
	global_load_dwordx2 a[90:91], v151, s[62:63] offset:2560 nt
	global_load_dwordx2 a[92:93], v151, s[62:63] offset:3072 nt
	global_load_dwordx2 a[94:95], v151, s[62:63] offset:3584 nt
	s_add_u32 s7, s7, 1
	v_cvt_f32_f16_e32 v154, v70
	v_cvt_f32_f16_e32 v155, v78
	v_add_f32_e32 v154, v154, v155
	v_fmac_f32_e32 v54, v32, v154
	v_cvt_f32_f16_sdwa v156, v70 dst_sel:DWORD dst_unused:UNUSED_PAD src0_sel:WORD_1
	v_cvt_f32_f16_sdwa v157, v78 dst_sel:DWORD dst_unused:UNUSED_PAD src0_sel:WORD_1
	v_add_f32_e32 v156, v156, v157
	v_fmac_f32_e32 v55, v33, v156
	v_cvt_f32_f16_e32 v154, v71
	v_cvt_f32_f16_e32 v155, v79
	v_add_f32_e32 v154, v154, v155
	v_fmac_f32_e32 v56, v34, v154
	v_cvt_f32_f16_sdwa v156, v71 dst_sel:DWORD dst_unused:UNUSED_PAD src0_sel:WORD_1
	v_cvt_f32_f16_sdwa v157, v79 dst_sel:DWORD dst_unused:UNUSED_PAD src0_sel:WORD_1
	v_add_f32_e32 v156, v156, v157
	v_fmac_f32_e32 v57, v35, v156
	v_cvt_f32_f16_e32 v154, v72
	v_cvt_f32_f16_e32 v155, v80
	v_add_f32_e32 v154, v154, v155
	v_fmac_f32_e32 v58, v36, v154
	v_cvt_f32_f16_sdwa v156, v72 dst_sel:DWORD dst_unused:UNUSED_PAD src0_sel:WORD_1
	v_cvt_f32_f16_sdwa v157, v80 dst_sel:DWORD dst_unused:UNUSED_PAD src0_sel:WORD_1
	v_add_f32_e32 v156, v156, v157
	v_fmac_f32_e32 v59, v37, v156
	v_cvt_f32_f16_e32 v154, v73
	v_cvt_f32_f16_e32 v155, v81
	v_add_f32_e32 v154, v154, v155
	v_fmac_f32_e32 v60, v38, v154
	v_cvt_f32_f16_sdwa v156, v73 dst_sel:DWORD dst_unused:UNUSED_PAD src0_sel:WORD_1
	v_cvt_f32_f16_sdwa v157, v81 dst_sel:DWORD dst_unused:UNUSED_PAD src0_sel:WORD_1
	v_add_f32_e32 v156, v156, v157
	v_fmac_f32_e32 v61, v39, v156
	v_cvt_f32_f16_e32 v154, v74
	v_cvt_f32_f16_e32 v155, v82
	v_add_f32_e32 v154, v154, v155
	v_fmac_f32_e32 v62, v40, v154
	v_cvt_f32_f16_sdwa v156, v74 dst_sel:DWORD dst_unused:UNUSED_PAD src0_sel:WORD_1
	v_cvt_f32_f16_sdwa v157, v82 dst_sel:DWORD dst_unused:UNUSED_PAD src0_sel:WORD_1
	v_add_f32_e32 v156, v156, v157
	v_fmac_f32_e32 v63, v41, v156
	v_cvt_f32_f16_e32 v154, v75
	v_cvt_f32_f16_e32 v155, v83
	v_add_f32_e32 v154, v154, v155
	v_fmac_f32_e32 v64, v42, v154
	v_cvt_f32_f16_sdwa v156, v75 dst_sel:DWORD dst_unused:UNUSED_PAD src0_sel:WORD_1
	v_cvt_f32_f16_sdwa v157, v83 dst_sel:DWORD dst_unused:UNUSED_PAD src0_sel:WORD_1
	v_add_f32_e32 v156, v156, v157
	v_fmac_f32_e32 v65, v43, v156
	v_cvt_f32_f16_e32 v154, v76
	v_cvt_f32_f16_e32 v155, v84
	v_add_f32_e32 v154, v154, v155
	v_fmac_f32_e32 v66, v44, v154
	v_cvt_f32_f16_sdwa v156, v76 dst_sel:DWORD dst_unused:UNUSED_PAD src0_sel:WORD_1
	v_cvt_f32_f16_sdwa v157, v84 dst_sel:DWORD dst_unused:UNUSED_PAD src0_sel:WORD_1
	v_add_f32_e32 v156, v156, v157
	v_fmac_f32_e32 v67, v45, v156
	v_cvt_f32_f16_e32 v154, v77
	v_cvt_f32_f16_e32 v155, v85
	v_add_f32_e32 v154, v154, v155
	v_fmac_f32_e32 v68, v46, v154
	v_cvt_f32_f16_sdwa v156, v77 dst_sel:DWORD dst_unused:UNUSED_PAD src0_sel:WORD_1
	v_cvt_f32_f16_sdwa v157, v85 dst_sel:DWORD dst_unused:UNUSED_PAD src0_sel:WORD_1
	v_add_f32_e32 v156, v156, v157
	v_fmac_f32_e32 v69, v47, v156
	global_store_dwordx4 v150, v[54:57], s[34:35] offset:0
	global_store_dwordx4 v150, v[58:61], s[34:35] offset:1024
	global_store_dwordx4 v150, v[62:65], s[34:35] offset:2048
	global_store_dwordx4 v150, v[66:69], s[34:35] offset:3072
	v_mul_f32_e32 v152, v54, v54
	v_mul_f32_e32 v153, v55, v55
	v_fmac_f32_e32 v152, v56, v56
	v_fmac_f32_e32 v153, v57, v57
	v_fmac_f32_e32 v152, v58, v58
	v_fmac_f32_e32 v153, v59, v59
	v_fmac_f32_e32 v152, v60, v60
	v_fmac_f32_e32 v153, v61, v61
	v_fmac_f32_e32 v152, v62, v62
	v_fmac_f32_e32 v153, v63, v63
	v_fmac_f32_e32 v152, v64, v64
	v_fmac_f32_e32 v153, v65, v65
	v_fmac_f32_e32 v152, v66, v66
	v_fmac_f32_e32 v153, v67, v67
	v_fmac_f32_e32 v152, v68, v68
	v_fmac_f32_e32 v153, v69, v69
	v_add_f32_e32 v152, v152, v153
; DI void row1_phase(const Params& P, int combine_l, int norm_l, int r_begin) {
;     ...
;       float ss = 0.f;
; #pragma unroll
;       for (int i = 0; i < 4; i++) ss += xv[i].x * xv[i].x + xv[i].y * xv[i].y + xv[i].z * xv[i].z + xv[i].w * xv[i].w;
;       ss = wave_sum(ss);
;       const float rstd = rsqrtf(ss * (1.f / 1024.f) + EPS);
;       const float* g = P.norm1_g + norm_l * 1024;
;       const float* sh = P.mod + (size_t)(norm_l * 9 + n) * 6144; const float* sc = sh + 1024;
; #pragma unroll
;       for (int i = 0; i < 4; i++) {
;         int c = i * 256 + lane * 4;
;         float4 gg = *(const float4*)(g + c), s1 = *(const float4*)(sc + c), s0 = *(const float4*)(sh + c);
;         h4 o;
;         o[0] = (half_t)(xv[i].x * rstd * gg.x * (1.f + s1.x) + s0.x); o[1] = (half_t)(xv[i].y * rstd * gg.y * (1.f + s1.y) + s0.y);
;         o[2] = (half_t)(xv[i].z * rstd * gg.z * (1.f + s1.z) + s0.z); o[3] = (half_t)(xv[i].w * rstd * gg.w * (1.f + s1.w) + s0.w);
;         *(h4*)(P.hx + (size_t)r * D + c) = o;
;       }
	s_nop 1
	v_add_f32_dpp v152, v152, v152 row_ror:8 row_mask:0xf bank_mask:0xf
	s_nop 1
	v_add_f32_dpp v152, v152, v152 row_ror:4 row_mask:0xf bank_mask:0xf
	s_nop 1
	v_add_f32_dpp v152, v152, v152 row_ror:2 row_mask:0xf bank_mask:0xf
	s_nop 1
	v_add_f32_dpp v152, v152, v152 row_ror:1 row_mask:0xf bank_mask:0xf
	s_nop 1
	v_readlane_b32 s22, v152, 0
	v_readlane_b32 s23, v152, 16
	v_readlane_b32 s32, v152, 32
	v_readlane_b32 s99, v152, 48
	v_mov_b32_e32 v152, s22
	v_add_f32_e32 v152, s23, v152
	v_add_f32_e32 v152, s32, v152
	v_add_f32_e32 v152, s99, v152
	v_mov_b32_e32 v153, 0x358637bd
	v_fmamk_f32 v152, v152, 0x3a800000, v153
	v_rsq_f32_e32 v152, v152
	s_nop 1
	v_mul_f32_e32 v54, v54, v152
	v_mul_f32_e32 v55, v55, v152
	v_mul_f32_e32 v56, v56, v152
	v_mul_f32_e32 v57, v57, v152
	v_mul_f32_e32 v58, v58, v152
	v_mul_f32_e32 v59, v59, v152
	v_mul_f32_e32 v60, v60, v152
	v_mul_f32_e32 v61, v61, v152
	v_mul_f32_e32 v62, v62, v152
	v_mul_f32_e32 v63, v63, v152
	v_mul_f32_e32 v64, v64, v152
	v_mul_f32_e32 v65, v65, v152
	v_mul_f32_e32 v66, v66, v152
	v_mul_f32_e32 v67, v67, v152
	v_mul_f32_e32 v68, v68, v152
	v_mul_f32_e32 v69, v69, v152
	v_fma_f32 v54, v54, v0, v16
	v_fma_f32 v55, v55, v1, v17
	v_fma_f32 v56, v56, v2, v18
	v_fma_f32 v57, v57, v3, v19
	v_fma_f32 v58, v58, v4, v20
	v_fma_f32 v59, v59, v5, v21
	v_fma_f32 v60, v60, v6, v22
	v_fma_f32 v61, v61, v7, v23
	v_fma_f32 v62, v62, v8, v24
	v_fma_f32 v63, v63, v9, v25
	v_fma_f32 v64, v64, v10, v26
	v_fma_f32 v65, v65, v11, v27
	v_fma_f32 v66, v66, v12, v28
	v_fma_f32 v67, v67, v13, v29
	v_fma_f32 v68, v68, v14, v30
	v_fma_f32 v69, v69, v15, v31
	v_cvt_pk_f16_f32 v70, v54, v55
	v_cvt_pk_f16_f32 v71, v56, v57
	v_cvt_pk_f16_f32 v72, v58, v59
	v_cvt_pk_f16_f32 v73, v60, v61
	v_cvt_pk_f16_f32 v74, v62, v63
	v_cvt_pk_f16_f32 v75, v64, v65
	v_cvt_pk_f16_f32 v76, v66, v67
	v_cvt_pk_f16_f32 v77, v68, v69
	global_store_dwordx2 v151, v[70:71], s[36:37] offset:0 nt
	global_store_dwordx2 v151, v[72:73], s[36:37] offset:512 nt
	global_store_dwordx2 v151, v[74:75], s[36:37] offset:1024 nt
	global_store_dwordx2 v151, v[76:77], s[36:37] offset:1536 nt
	s_add_u32 s5, s5, 1
	s_sub_u32 s9, s5, 0x800
	s_lshr_b32 s9, s9, 13
	s_cmp_lt_u32 s5, 0x800
	s_cselect_b32 s9, 8, s9
	s_cmp_eq_u32 s9, s8
	s_cbranch_scc1 .Lr1b_nr4
	s_mov_b32 s8, s9
	s_waitcnt vmcnt(0)
	s_add_u32 s10, s9, 9
	s_mul_i32 s10, s10, 0x6000
	s_add_u32 s38, s56, s10
	s_addc_u32 s39, s57, 0
	global_load_dwordx4 v[54:57], v150, s[58:59] offset:0
	global_load_dwordx4 v[58:61], v150, s[58:59] offset:1024
	global_load_dwordx4 v[62:65], v150, s[58:59] offset:2048
	global_load_dwordx4 v[66:69], v150, s[58:59] offset:3072
	s_add_u32 s44, s38, 0x1000
	s_addc_u32 s45, s39, 0
	global_load_dwordx4 v[70:73], v150, s[44:45] offset:0
	global_load_dwordx4 v[74:77], v150, s[44:45] offset:1024
	global_load_dwordx4 v[78:81], v150, s[44:45] offset:2048
	global_load_dwordx4 v[82:85], v150, s[44:45] offset:3072
	global_load_dwordx4 v[16:19], v150, s[38:39] offset:0
	global_load_dwordx4 v[20:23], v150, s[38:39] offset:1024
	global_load_dwordx4 v[24:27], v150, s[38:39] offset:2048
	global_load_dwordx4 v[28:31], v150, s[38:39] offset:3072
	s_add_u32 s10, s9, 0
	s_mul_i32 s10, s10, 0x6000
	s_add_u32 s10, s10, 0x5000
	s_add_u32 s38, s56, s10
	s_addc_u32 s39, s57, 0
	global_load_dwordx4 v[32:35], v150, s[38:39] offset:0
	global_load_dwordx4 v[36:39], v150, s[38:39] offset:1024
	global_load_dwordx4 v[40:43], v150, s[38:39] offset:2048
	global_load_dwordx4 v[44:47], v150, s[38:39] offset:3072
	s_waitcnt vmcnt(0)
	v_add_f32_e32 v70, 1.0, v70
	v_add_f32_e32 v71, 1.0, v71
	v_add_f32_e32 v72, 1.0, v72
	v_add_f32_e32 v73, 1.0, v73
	v_add_f32_e32 v74, 1.0, v74
	v_add_f32_e32 v75, 1.0, v75
	v_add_f32_e32 v76, 1.0, v76
	v_add_f32_e32 v77, 1.0, v77
	v_add_f32_e32 v78, 1.0, v78
	v_add_f32_e32 v79, 1.0, v79
	v_add_f32_e32 v80, 1.0, v80
	v_add_f32_e32 v81, 1.0, v81
	v_add_f32_e32 v82, 1.0, v82
	v_add_f32_e32 v83, 1.0, v83
	v_add_f32_e32 v84, 1.0, v84
	v_add_f32_e32 v85, 1.0, v85
	v_mul_f32_e32 v0, v54, v70
	v_mul_f32_e32 v1, v55, v71
	v_mul_f32_e32 v2, v56, v72
	v_mul_f32_e32 v3, v57, v73
	v_mul_f32_e32 v4, v58, v74
	v_mul_f32_e32 v5, v59, v75
	v_mul_f32_e32 v6, v60, v76
	v_mul_f32_e32 v7, v61, v77
	v_mul_f32_e32 v8, v62, v78
	v_mul_f32_e32 v9, v63, v79
	v_mul_f32_e32 v10, v64, v80
	v_mul_f32_e32 v11, v65, v81
	v_mul_f32_e32 v12, v66, v82
	v_mul_f32_e32 v13, v67, v83
	v_mul_f32_e32 v14, v68, v84
	v_mul_f32_e32 v15, v69, v85
; DI void row1_phase(const Params& P, int combine_l, int norm_l, int r_begin) {
;     ...
;     if (combine_l < 0) {
;       const float* src = r < TC ? P.ctx + (size_t)r * D : P.x + (size_t)(r - TC) * D;
; #pragma unroll
;       for (int i = 0; i < 4; i++) xv[i] = *(const float4*)(src + i * 256 + lane * 4);
;     } else {
;       const float* xm = r < TC ? P.xcbuf + (size_t)r * D : P.out + (size_t)(r - TC) * D;
;       const half_t* y0 = P.yA + (size_t)(2 * r) * D; const half_t* y1 = y0 + D;
; #pragma unroll
;       for (int i = 0; i < 4; i++) { int c = i * 256 + lane * 4; xv[i] = *(const float4*)(xm + c); ya[i] = *(const h4*)(y0 + c); yb[i] = *(const h4*)(y1 + c); }
;     }
;   };
;   auto process = [&](int r, float4 (&xv)[4], h4 (&ya)[4], h4 (&yb)[4]) {
;     const int n = row_mod(r);
;     if (combine_l >= 0) {
;       float* xm = r < TC ? P.xcbuf + (size_t)r * D : P.out + (size_t)(r - TC) * D;
;       const float* g2 = P.mod + (size_t)(combine_l * 9 + n) * 6144 + 5 * 1024;
; #pragma unroll
;       for (int i = 0; i < 4; i++) {
;         int c = i * 256 + lane * 4;
;         float4 g = *(const float4*)(g2 + c); float4 t = xv[i];
;         t.x += g.x * ((float)ya[i][0] + (float)yb[i][0]); t.y += g.y * ((float)ya[i][1] + (float)yb[i][1]);
;         t.z += g.z * ((float)ya[i][2] + (float)yb[i][2]); t.w += g.w * ((float)ya[i][3] + (float)yb[i][3]);
;         *(float4*)(xm + c) = t; xv[i] = t;
.Lr1b_nr4:
	s_waitcnt vmcnt(44)
	v_accvgpr_read_b32 v54, a96
	v_accvgpr_read_b32 v55, a97
	v_accvgpr_read_b32 v56, a98
	v_accvgpr_read_b32 v57, a99
	v_accvgpr_read_b32 v58, a100
	v_accvgpr_read_b32 v59, a101
	v_accvgpr_read_b32 v60, a102
	v_accvgpr_read_b32 v61, a103
	v_accvgpr_read_b32 v62, a104
	v_accvgpr_read_b32 v63, a105
	v_accvgpr_read_b32 v64, a106
	v_accvgpr_read_b32 v65, a107
	v_accvgpr_read_b32 v66, a108
	v_accvgpr_read_b32 v67, a109
	v_accvgpr_read_b32 v68, a110
	v_accvgpr_read_b32 v69, a111
	v_accvgpr_read_b32 v70, a112
	v_accvgpr_read_b32 v71, a113
	v_accvgpr_read_b32 v72, a114
	v_accvgpr_read_b32 v73, a115
	v_accvgpr_read_b32 v74, a116
	v_accvgpr_read_b32 v75, a117
	v_accvgpr_read_b32 v76, a118
	v_accvgpr_read_b32 v77, a119
	v_accvgpr_read_b32 v78, a120
	v_accvgpr_read_b32 v79, a121
	v_accvgpr_read_b32 v80, a122
	v_accvgpr_read_b32 v81, a123
	v_accvgpr_read_b32 v82, a124
	v_accvgpr_read_b32 v83, a125
	v_accvgpr_read_b32 v84, a126
	v_accvgpr_read_b32 v85, a127
	s_lshl_b32 s10, s5, 12
	s_cmp_lt_u32 s5, 0x800
	s_cselect_b64 s[34:35], s[48:49], s[50:51]
	s_add_u32 s34, s34, s10
	s_addc_u32 s35, s35, 0
	s_lshr_b32 s10, s10, 1
	s_add_u32 s36, s54, s10
	s_addc_u32 s37, s55, 0
	s_cmp_lt_u32 s7, 0x800
	s_cselect_b64 s[60:61], s[48:49], s[50:51]
	s_lshl_b32 s10, s7, 12
	s_add_u32 s60, s60, s10
	s_addc_u32 s61, s61, 0
	global_load_dwordx4 a[96:99], v150, s[60:61] offset:0 nt
	global_load_dwordx4 a[100:103], v150, s[60:61] offset:1024 nt
	global_load_dwordx4 a[104:107], v150, s[60:61] offset:2048 nt
	global_load_dwordx4 a[108:111], v150, s[60:61] offset:3072 nt
	s_add_u32 s62, s52, s10
	s_addc_u32 s63, s53, 0
	global_load_dwordx2 a[112:113], v151, s[62:63] offset:0 nt
	global_load_dwordx2 a[114:115], v151, s[62:63] offset:512 nt
	global_load_dwordx2 a[116:117], v151, s[62:63] offset:1024 nt
	global_load_dwordx2 a[118:119], v151, s[62:63] offset:1536 nt
	global_load_dwordx2 a[120:121], v151, s[62:63] offset:2048 nt
	global_load_dwordx2 a[122:123], v151, s[62:63] offset:2560 nt
	global_load_dwordx2 a[124:125], v151, s[62:63] offset:3072 nt
	global_load_dwordx2 a[126:127], v151, s[62:63] offset:3584 nt
	s_add_u32 s7, s7, 1
	v_cvt_f32_f16_e32 v154, v70
	v_cvt_f32_f16_e32 v155, v78
	v_add_f32_e32 v154, v154, v155
	v_fmac_f32_e32 v54, v32, v154
	v_cvt_f32_f16_sdwa v156, v70 dst_sel:DWORD dst_unused:UNUSED_PAD src0_sel:WORD_1
	v_cvt_f32_f16_sdwa v157, v78 dst_sel:DWORD dst_unused:UNUSED_PAD src0_sel:WORD_1
	v_add_f32_e32 v156, v156, v157
	v_fmac_f32_e32 v55, v33, v156
	v_cvt_f32_f16_e32 v154, v71
	v_cvt_f32_f16_e32 v155, v79
	v_add_f32_e32 v154, v154, v155
	v_fmac_f32_e32 v56, v34, v154
	v_cvt_f32_f16_sdwa v156, v71 dst_sel:DWORD dst_unused:UNUSED_PAD src0_sel:WORD_1
	v_cvt_f32_f16_sdwa v157, v79 dst_sel:DWORD dst_unused:UNUSED_PAD src0_sel:WORD_1
	v_add_f32_e32 v156, v156, v157
	v_fmac_f32_e32 v57, v35, v156
	v_cvt_f32_f16_e32 v154, v72
	v_cvt_f32_f16_e32 v155, v80
	v_add_f32_e32 v154, v154, v155
	v_fmac_f32_e32 v58, v36, v154
	v_cvt_f32_f16_sdwa v156, v72 dst_sel:DWORD dst_unused:UNUSED_PAD src0_sel:WORD_1
	v_cvt_f32_f16_sdwa v157, v80 dst_sel:DWORD dst_unused:UNUSED_PAD src0_sel:WORD_1
	v_add_f32_e32 v156, v156, v157
	v_fmac_f32_e32 v59, v37, v156
	v_cvt_f32_f16_e32 v154, v73
	v_cvt_f32_f16_e32 v155, v81
	v_add_f32_e32 v154, v154, v155
	v_fmac_f32_e32 v60, v38, v154
	v_cvt_f32_f16_sdwa v156, v73 dst_sel:DWORD dst_unused:UNUSED_PAD src0_sel:WORD_1
	v_cvt_f32_f16_sdwa v157, v81 dst_sel:DWORD dst_unused:UNUSED_PAD src0_sel:WORD_1
	v_add_f32_e32 v156, v156, v157
	v_fmac_f32_e32 v61, v39, v156
	v_cvt_f32_f16_e32 v154, v74
	v_cvt_f32_f16_e32 v155, v82
	v_add_f32_e32 v154, v154, v155
	v_fmac_f32_e32 v62, v40, v154
	v_cvt_f32_f16_sdwa v156, v74 dst_sel:DWORD dst_unused:UNUSED_PAD src0_sel:WORD_1
	v_cvt_f32_f16_sdwa v157, v82 dst_sel:DWORD dst_unused:UNUSED_PAD src0_sel:WORD_1
	v_add_f32_e32 v156, v156, v157
	v_fmac_f32_e32 v63, v41, v156
	v_cvt_f32_f16_e32 v154, v75
	v_cvt_f32_f16_e32 v155, v83
	v_add_f32_e32 v154, v154, v155
	v_fmac_f32_e32 v64, v42, v154
	v_cvt_f32_f16_sdwa v156, v75 dst_sel:DWORD dst_unused:UNUSED_PAD src0_sel:WORD_1
	v_cvt_f32_f16_sdwa v157, v83 dst_sel:DWORD dst_unused:UNUSED_PAD src0_sel:WORD_1
	v_add_f32_e32 v156, v156, v157
	v_fmac_f32_e32 v65, v43, v156
	v_cvt_f32_f16_e32 v154, v76
	v_cvt_f32_f16_e32 v155, v84
	v_add_f32_e32 v154, v154, v155
	v_fmac_f32_e32 v66, v44, v154
	v_cvt_f32_f16_sdwa v156, v76 dst_sel:DWORD dst_unused:UNUSED_PAD src0_sel:WORD_1
	v_cvt_f32_f16_sdwa v157, v84 dst_sel:DWORD dst_unused:UNUSED_PAD src0_sel:WORD_1
	v_add_f32_e32 v156, v156, v157
	v_fmac_f32_e32 v67, v45, v156
	v_cvt_f32_f16_e32 v154, v77
	v_cvt_f32_f16_e32 v155, v85
	v_add_f32_e32 v154, v154, v155
	v_fmac_f32_e32 v68, v46, v154
	v_cvt_f32_f16_sdwa v156, v77 dst_sel:DWORD dst_unused:UNUSED_PAD src0_sel:WORD_1
	v_cvt_f32_f16_sdwa v157, v85 dst_sel:DWORD dst_unused:UNUSED_PAD src0_sel:WORD_1
	v_add_f32_e32 v156, v156, v157
	v_fmac_f32_e32 v69, v47, v156
	global_store_dwordx4 v150, v[54:57], s[34:35] offset:0
	global_store_dwordx4 v150, v[58:61], s[34:35] offset:1024
	global_store_dwordx4 v150, v[62:65], s[34:35] offset:2048
; DI void row1_phase(const Params& P, int combine_l, int norm_l, int r_begin) {
;     ...
;         *(float4*)(xm + c) = t; xv[i] = t;
;       }
;     }
;     if (norm_l >= 0) {
;       float ss = 0.f;
; #pragma unroll
;       for (int i = 0; i < 4; i++) ss += xv[i].x * xv[i].x + xv[i].y * xv[i].y + xv[i].z * xv[i].z + xv[i].w * xv[i].w;
;       ss = wave_sum(ss);
;       const float rstd = rsqrtf(ss * (1.f / 1024.f) + EPS);
;       const float* g = P.norm1_g + norm_l * 1024;
;       const float* sh = P.mod + (size_t)(norm_l * 9 + n) * 6144; const float* sc = sh + 1024;
; #pragma unroll
;       for (int i = 0; i < 4; i++) {
;         int c = i * 256 + lane * 4;
;         float4 gg = *(const float4*)(g + c), s1 = *(const float4*)(sc + c), s0 = *(const float4*)(sh + c);
;         h4 o;
;         o[0] = (half_t)(xv[i].x * rstd * gg.x * (1.f + s1.x) + s0.x); o[1] = (half_t)(xv[i].y * rstd * gg.y * (1.f + s1.y) + s0.y);
;         o[2] = (half_t)(xv[i].z * rstd * gg.z * (1.f + s1.z) + s0.z); o[3] = (half_t)(xv[i].w * rstd * gg.w * (1.f + s1.w) + s0.w);
;         *(h4*)(P.hx + (size_t)r * D + c) = o;
;       }
	global_store_dwordx4 v150, v[66:69], s[34:35] offset:3072
	v_mul_f32_e32 v152, v54, v54
	v_mul_f32_e32 v153, v55, v55
	v_fmac_f32_e32 v152, v56, v56
	v_fmac_f32_e32 v153, v57, v57
	v_fmac_f32_e32 v152, v58, v58
	v_fmac_f32_e32 v153, v59, v59
	v_fmac_f32_e32 v152, v60, v60
	v_fmac_f32_e32 v153, v61, v61
	v_fmac_f32_e32 v152, v62, v62
	v_fmac_f32_e32 v153, v63, v63
	v_fmac_f32_e32 v152, v64, v64
	v_fmac_f32_e32 v153, v65, v65
	v_fmac_f32_e32 v152, v66, v66
	v_fmac_f32_e32 v153, v67, v67
	v_fmac_f32_e32 v152, v68, v68
	v_fmac_f32_e32 v153, v69, v69
	v_add_f32_e32 v152, v152, v153
	s_nop 1
	v_add_f32_dpp v152, v152, v152 row_ror:8 row_mask:0xf bank_mask:0xf
	s_nop 1
	v_add_f32_dpp v152, v152, v152 row_ror:4 row_mask:0xf bank_mask:0xf
	s_nop 1
	v_add_f32_dpp v152, v152, v152 row_ror:2 row_mask:0xf bank_mask:0xf
	s_nop 1
	v_add_f32_dpp v152, v152, v152 row_ror:1 row_mask:0xf bank_mask:0xf
	s_nop 1
	v_readlane_b32 s22, v152, 0
	v_readlane_b32 s23, v152, 16
	v_readlane_b32 s32, v152, 32
	v_readlane_b32 s99, v152, 48
	v_mov_b32_e32 v152, s22
	v_add_f32_e32 v152, s23, v152
	v_add_f32_e32 v152, s32, v152
	v_add_f32_e32 v152, s99, v152
	v_mov_b32_e32 v153, 0x358637bd
	v_fmamk_f32 v152, v152, 0x3a800000, v153
	v_rsq_f32_e32 v152, v152
	s_nop 1
	v_mul_f32_e32 v54, v54, v152
	v_mul_f32_e32 v55, v55, v152
	v_mul_f32_e32 v56, v56, v152
	v_mul_f32_e32 v57, v57, v152
	v_mul_f32_e32 v58, v58, v152
	v_mul_f32_e32 v59, v59, v152
	v_mul_f32_e32 v60, v60, v152
	v_mul_f32_e32 v61, v61, v152
	v_mul_f32_e32 v62, v62, v152
	v_mul_f32_e32 v63, v63, v152
	v_mul_f32_e32 v64, v64, v152
	v_mul_f32_e32 v65, v65, v152
	v_mul_f32_e32 v66, v66, v152
	v_mul_f32_e32 v67, v67, v152
	v_mul_f32_e32 v68, v68, v152
	v_mul_f32_e32 v69, v69, v152
	v_fma_f32 v54, v54, v0, v16
	v_fma_f32 v55, v55, v1, v17
	v_fma_f32 v56, v56, v2, v18
	v_fma_f32 v57, v57, v3, v19
	v_fma_f32 v58, v58, v4, v20
	v_fma_f32 v59, v59, v5, v21
	v_fma_f32 v60, v60, v6, v22
	v_fma_f32 v61, v61, v7, v23
	v_fma_f32 v62, v62, v8, v24
	v_fma_f32 v63, v63, v9, v25
	v_fma_f32 v64, v64, v10, v26
	v_fma_f32 v65, v65, v11, v27
	v_fma_f32 v66, v66, v12, v28
	v_fma_f32 v67, v67, v13, v29
	v_fma_f32 v68, v68, v14, v30
	v_fma_f32 v69, v69, v15, v31
	v_cvt_pk_f16_f32 v70, v54, v55
	v_cvt_pk_f16_f32 v71, v56, v57
	v_cvt_pk_f16_f32 v72, v58, v59
	v_cvt_pk_f16_f32 v73, v60, v61
	v_cvt_pk_f16_f32 v74, v62, v63
	v_cvt_pk_f16_f32 v75, v64, v65
	v_cvt_pk_f16_f32 v76, v66, v67
	v_cvt_pk_f16_f32 v77, v68, v69
	global_store_dwordx2 v151, v[70:71], s[36:37] offset:0 nt
	global_store_dwordx2 v151, v[72:73], s[36:37] offset:512 nt
	global_store_dwordx2 v151, v[74:75], s[36:37] offset:1024 nt
	global_store_dwordx2 v151, v[76:77], s[36:37] offset:1536 nt
	s_add_u32 s5, s5, 1
	s_sub_u32 s98, s98, 1
	s_cmp_lg_u32 s98, 0
	s_cbranch_scc1 .Lr1b_loop
	s_sub_u32 s9, s5, 0x800
	s_lshr_b32 s9, s9, 13
	s_cmp_lt_u32 s5, 0x800
	s_cselect_b32 s9, 8, s9
	s_cmp_eq_u32 s9, s8
	s_cbranch_scc1 .Lr1b_nr5
	s_mov_b32 s8, s9
	s_waitcnt vmcnt(0)
	s_add_u32 s10, s9, 9
	s_mul_i32 s10, s10, 0x6000
	s_add_u32 s38, s56, s10
	s_addc_u32 s39, s57, 0
	global_load_dwordx4 v[54:57], v150, s[58:59] offset:0
	global_load_dwordx4 v[58:61], v150, s[58:59] offset:1024
	global_load_dwordx4 v[62:65], v150, s[58:59] offset:2048
	global_load_dwordx4 v[66:69], v150, s[58:59] offset:3072
	s_add_u32 s44, s38, 0x1000
	s_addc_u32 s45, s39, 0
	global_load_dwordx4 v[70:73], v150, s[44:45] offset:0
	global_load_dwordx4 v[74:77], v150, s[44:45] offset:1024
	global_load_dwordx4 v[78:81], v150, s[44:45] offset:2048
	global_load_dwordx4 v[82:85], v150, s[44:45] offset:3072
	global_load_dwordx4 v[16:19], v150, s[38:39] offset:0
	global_load_dwordx4 v[20:23], v150, s[38:39] offset:1024
	global_load_dwordx4 v[24:27], v150, s[38:39] offset:2048
	global_load_dwordx4 v[28:31], v150, s[38:39] offset:3072
	s_add_u32 s10, s9, 0
	s_mul_i32 s10, s10, 0x6000
	s_add_u32 s10, s10, 0x5000
	s_add_u32 s38, s56, s10
	s_addc_u32 s39, s57, 0
	global_load_dwordx4 v[32:35], v150, s[38:39] offset:0
	global_load_dwordx4 v[36:39], v150, s[38:39] offset:1024
	global_load_dwordx4 v[40:43], v150, s[38:39] offset:2048
	global_load_dwordx4 v[44:47], v150, s[38:39] offset:3072
	s_waitcnt vmcnt(0)
	v_add_f32_e32 v70, 1.0, v70
	v_add_f32_e32 v71, 1.0, v71
	v_add_f32_e32 v72, 1.0, v72
	v_add_f32_e32 v73, 1.0, v73
	v_add_f32_e32 v74, 1.0, v74
	v_add_f32_e32 v75, 1.0, v75
	v_add_f32_e32 v76, 1.0, v76
	v_add_f32_e32 v77, 1.0, v77
	v_add_f32_e32 v78, 1.0, v78
	v_add_f32_e32 v79, 1.0, v79
	v_add_f32_e32 v80, 1.0, v80
	v_add_f32_e32 v81, 1.0, v81
	v_add_f32_e32 v82, 1.0, v82
	v_add_f32_e32 v83, 1.0, v83
	v_add_f32_e32 v84, 1.0, v84
	v_add_f32_e32 v85, 1.0, v85
	v_mul_f32_e32 v0, v54, v70
	v_mul_f32_e32 v1, v55, v71
	v_mul_f32_e32 v2, v56, v72
	v_mul_f32_e32 v3, v57, v73
	v_mul_f32_e32 v4, v58, v74
	v_mul_f32_e32 v5, v59, v75
	v_mul_f32_e32 v6, v60, v76
	v_mul_f32_e32 v7, v61, v77
	v_mul_f32_e32 v8, v62, v78
	v_mul_f32_e32 v9, v63, v79
	v_mul_f32_e32 v10, v64, v80
	v_mul_f32_e32 v11, v65, v81
	v_mul_f32_e32 v12, v66, v82
	v_mul_f32_e32 v13, v67, v83
	v_mul_f32_e32 v14, v68, v84
	v_mul_f32_e32 v15, v69, v85

; DI void row1_phase(const Params& P, int combine_l, int norm_l, int r_begin) {
;     ...
;   auto process = [&](int r, float4 (&xv)[4], h4 (&ya)[4], h4 (&yb)[4]) {
;     const int n = row_mod(r);
;     if (combine_l >= 0) {
;       float* xm = r < TC ? P.xcbuf + (size_t)r * D : P.out + (size_t)(r - TC) * D;
;       const float* g2 = P.mod + (size_t)(combine_l * 9 + n) * 6144 + 5 * 1024;
; #pragma unroll
;       for (int i = 0; i < 4; i++) {
;         int c = i * 256 + lane * 4;
;         float4 g = *(const float4*)(g2 + c); float4 t = xv[i];
;         t.x += g.x * ((float)ya[i][0] + (float)yb[i][0]); t.y += g.y * ((float)ya[i][1] + (float)yb[i][1]);
;         t.z += g.z * ((float)ya[i][2] + (float)yb[i][2]); t.w += g.w * ((float)ya[i][3] + (float)yb[i][3]);
;         *(float4*)(xm + c) = t; xv[i] = t;
;       }
;     }
;     if (norm_l >= 0) {
;       float ss = 0.f;
; #pragma unroll
;       for (int i = 0; i < 4; i++) ss += xv[i].x * xv[i].x + xv[i].y * xv[i].y + xv[i].z * xv[i].z + xv[i].w * xv[i].w;
;       ss = wave_sum(ss);
;       const float rstd = rsqrtf(ss * (1.f / 1024.f) + EPS);
;       const float* g = P.norm1_g + norm_l * 1024;
;       const float* sh = P.mod + (size_t)(norm_l * 9 + n) * 6144; const float* sc = sh + 1024;
; #pragma unroll
;       for (int i = 0; i < 4; i++) {
;         int c = i * 256 + lane * 4;
;         float4 gg = *(const float4*)(g + c), s1 = *(const float4*)(sc + c), s0 = *(const float4*)(sh + c);
;         h4 o;
;         o[0] = (half_t)(xv[i].x * rstd * gg.x * (1.f + s1.x) + s0.x); o[1] = (half_t)(xv[i].y * rstd * gg.y * (1.f + s1.y) + s0.y);
;         o[2] = (half_t)(xv[i].z * rstd * gg.z * (1.f + s1.z) + s0.z); o[3] = (half_t)(xv[i].w * rstd * gg.w * (1.f + s1.w) + s0.w);
;         *(h4*)(P.hx + (size_t)r * D + c) = o;
;       }
.Lr1b_nr7:
	s_waitcnt vmcnt(44)
	v_accvgpr_read_b32 v54, a64
	v_accvgpr_read_b32 v55, a65
	v_accvgpr_read_b32 v56, a66
	v_accvgpr_read_b32 v57, a67
	v_accvgpr_read_b32 v58, a68
	v_accvgpr_read_b32 v59, a69
	v_accvgpr_read_b32 v60, a70
	v_accvgpr_read_b32 v61, a71
	v_accvgpr_read_b32 v62, a72
	v_accvgpr_read_b32 v63, a73
	v_accvgpr_read_b32 v64, a74
	v_accvgpr_read_b32 v65, a75
	v_accvgpr_read_b32 v66, a76
	v_accvgpr_read_b32 v67, a77
	v_accvgpr_read_b32 v68, a78
	v_accvgpr_read_b32 v69, a79
	v_accvgpr_read_b32 v70, a80
	v_accvgpr_read_b32 v71, a81
	v_accvgpr_read_b32 v72, a82
	v_accvgpr_read_b32 v73, a83
	v_accvgpr_read_b32 v74, a84
	v_accvgpr_read_b32 v75, a85
	v_accvgpr_read_b32 v76, a86
	v_accvgpr_read_b32 v77, a87
	v_accvgpr_read_b32 v78, a88
	v_accvgpr_read_b32 v79, a89
	v_accvgpr_read_b32 v80, a90
	v_accvgpr_read_b32 v81, a91
	v_accvgpr_read_b32 v82, a92
	v_accvgpr_read_b32 v83, a93
	v_accvgpr_read_b32 v84, a94
	v_accvgpr_read_b32 v85, a95
	s_lshl_b32 s10, s5, 12
	s_cmp_lt_u32 s5, 0x800
	s_cselect_b64 s[34:35], s[48:49], s[50:51]
	s_add_u32 s34, s34, s10
	s_addc_u32 s35, s35, 0
	s_lshr_b32 s10, s10, 1
	s_add_u32 s36, s54, s10
	s_addc_u32 s37, s55, 0
	v_cvt_f32_f16_e32 v154, v70
	v_cvt_f32_f16_e32 v155, v78
	v_add_f32_e32 v154, v154, v155
	v_fmac_f32_e32 v54, v32, v154
	v_cvt_f32_f16_sdwa v156, v70 dst_sel:DWORD dst_unused:UNUSED_PAD src0_sel:WORD_1
	v_cvt_f32_f16_sdwa v157, v78 dst_sel:DWORD dst_unused:UNUSED_PAD src0_sel:WORD_1
	v_add_f32_e32 v156, v156, v157
	v_fmac_f32_e32 v55, v33, v156
	v_cvt_f32_f16_e32 v154, v71
	v_cvt_f32_f16_e32 v155, v79
	v_add_f32_e32 v154, v154, v155
	v_fmac_f32_e32 v56, v34, v154
	v_cvt_f32_f16_sdwa v156, v71 dst_sel:DWORD dst_unused:UNUSED_PAD src0_sel:WORD_1
	v_cvt_f32_f16_sdwa v157, v79 dst_sel:DWORD dst_unused:UNUSED_PAD src0_sel:WORD_1
	v_add_f32_e32 v156, v156, v157
	v_fmac_f32_e32 v57, v35, v156
	v_cvt_f32_f16_e32 v154, v72
	v_cvt_f32_f16_e32 v155, v80
	v_add_f32_e32 v154, v154, v155
	v_fmac_f32_e32 v58, v36, v154
	v_cvt_f32_f16_sdwa v156, v72 dst_sel:DWORD dst_unused:UNUSED_PAD src0_sel:WORD_1
	v_cvt_f32_f16_sdwa v157, v80 dst_sel:DWORD dst_unused:UNUSED_PAD src0_sel:WORD_1
	v_add_f32_e32 v156, v156, v157
	v_fmac_f32_e32 v59, v37, v156
	v_cvt_f32_f16_e32 v154, v73
	v_cvt_f32_f16_e32 v155, v81
	v_add_f32_e32 v154, v154, v155
	v_fmac_f32_e32 v60, v38, v154
	v_cvt_f32_f16_sdwa v156, v73 dst_sel:DWORD dst_unused:UNUSED_PAD src0_sel:WORD_1
	v_cvt_f32_f16_sdwa v157, v81 dst_sel:DWORD dst_unused:UNUSED_PAD src0_sel:WORD_1
	v_add_f32_e32 v156, v156, v157
	v_fmac_f32_e32 v61, v39, v156
	v_cvt_f32_f16_e32 v154, v74
	v_cvt_f32_f16_e32 v155, v82
	v_add_f32_e32 v154, v154, v155
	v_fmac_f32_e32 v62, v40, v154
	v_cvt_f32_f16_sdwa v156, v74 dst_sel:DWORD dst_unused:UNUSED_PAD src0_sel:WORD_1
	v_cvt_f32_f16_sdwa v157, v82 dst_sel:DWORD dst_unused:UNUSED_PAD src0_sel:WORD_1
	v_add_f32_e32 v156, v156, v157
	v_fmac_f32_e32 v63, v41, v156
	v_cvt_f32_f16_e32 v154, v75
	v_cvt_f32_f16_e32 v155, v83
	v_add_f32_e32 v154, v154, v155
	v_fmac_f32_e32 v64, v42, v154
	v_cvt_f32_f16_sdwa v156, v75 dst_sel:DWORD dst_unused:UNUSED_PAD src0_sel:WORD_1
	v_cvt_f32_f16_sdwa v157, v83 dst_sel:DWORD dst_unused:UNUSED_PAD src0_sel:WORD_1
	v_add_f32_e32 v156, v156, v157
	v_fmac_f32_e32 v65, v43, v156
	v_cvt_f32_f16_e32 v154, v76
	v_cvt_f32_f16_e32 v155, v84
	v_add_f32_e32 v154, v154, v155
	v_fmac_f32_e32 v66, v44, v154
	v_cvt_f32_f16_sdwa v156, v76 dst_sel:DWORD dst_unused:UNUSED_PAD src0_sel:WORD_1
	v_cvt_f32_f16_sdwa v157, v84 dst_sel:DWORD dst_unused:UNUSED_PAD src0_sel:WORD_1
	v_add_f32_e32 v156, v156, v157
	v_fmac_f32_e32 v67, v45, v156
	v_cvt_f32_f16_e32 v154, v77
	v_cvt_f32_f16_e32 v155, v85
	v_add_f32_e32 v154, v154, v155
	v_fmac_f32_e32 v68, v46, v154
	v_cvt_f32_f16_sdwa v156, v77 dst_sel:DWORD dst_unused:UNUSED_PAD src0_sel:WORD_1
	v_cvt_f32_f16_sdwa v157, v85 dst_sel:DWORD dst_unused:UNUSED_PAD src0_sel:WORD_1
	v_add_f32_e32 v156, v156, v157
	v_fmac_f32_e32 v69, v47, v156
	global_store_dwordx4 v150, v[54:57], s[34:35] offset:0
	global_store_dwordx4 v150, v[58:61], s[34:35] offset:1024
	global_store_dwordx4 v150, v[62:65], s[34:35] offset:2048
	global_store_dwordx4 v150, v[66:69], s[34:35] offset:3072
	v_mul_f32_e32 v152, v54, v54
	v_mul_f32_e32 v153, v55, v55
	v_fmac_f32_e32 v152, v56, v56
	v_fmac_f32_e32 v153, v57, v57
	v_fmac_f32_e32 v152, v58, v58
	v_fmac_f32_e32 v153, v59, v59
	v_fmac_f32_e32 v152, v60, v60
	v_fmac_f32_e32 v153, v61, v61
	v_fmac_f32_e32 v152, v62, v62
	v_fmac_f32_e32 v153, v63, v63
	v_fmac_f32_e32 v152, v64, v64
	v_fmac_f32_e32 v153, v65, v65
	v_fmac_f32_e32 v152, v66, v66
	v_fmac_f32_e32 v153, v67, v67
	v_fmac_f32_e32 v152, v68, v68
	v_fmac_f32_e32 v153, v69, v69
	v_add_f32_e32 v152, v152, v153
	s_nop 1
	v_add_f32_dpp v152, v152, v152 row_ror:8 row_mask:0xf bank_mask:0xf
	s_nop 1
	v_add_f32_dpp v152, v152, v152 row_ror:4 row_mask:0xf bank_mask:0xf
	s_nop 1
	v_add_f32_dpp v152, v152, v152 row_ror:2 row_mask:0xf bank_mask:0xf
	s_nop 1
	v_add_f32_dpp v152, v152, v152 row_ror:1 row_mask:0xf bank_mask:0xf
	s_nop 1
	v_readlane_b32 s22, v152, 0
	v_readlane_b32 s23, v152, 16
	v_readlane_b32 s32, v152, 32
	v_readlane_b32 s99, v152, 48
	v_mov_b32_e32 v152, s22
	v_add_f32_e32 v152, s23, v152
	v_add_f32_e32 v152, s32, v152
	v_add_f32_e32 v152, s99, v152
	v_mov_b32_e32 v153, 0x358637bd
	v_fmamk_f32 v152, v152, 0x3a800000, v153
	v_rsq_f32_e32 v152, v152
	s_nop 1
	v_mul_f32_e32 v54, v54, v152
	v_mul_f32_e32 v55, v55, v152
	v_mul_f32_e32 v56, v56, v152
	v_mul_f32_e32 v57, v57, v152
	v_mul_f32_e32 v58, v58, v152
	v_mul_f32_e32 v59, v59, v152
	v_mul_f32_e32 v60, v60, v152
	v_mul_f32_e32 v61, v61, v152
	v_mul_f32_e32 v62, v62, v152
	v_mul_f32_e32 v63, v63, v152
	v_mul_f32_e32 v64, v64, v152
	v_mul_f32_e32 v65, v65, v152
	v_mul_f32_e32 v66, v66, v152
	v_mul_f32_e32 v67, v67, v152
	v_mul_f32_e32 v68, v68, v152
	v_mul_f32_e32 v69, v69, v152
	v_fma_f32 v54, v54, v0, v16
	v_fma_f32 v55, v55, v1, v17
	v_fma_f32 v56, v56, v2, v18
	v_fma_f32 v57, v57, v3, v19
	v_fma_f32 v58, v58, v4, v20
	v_fma_f32 v59, v59, v5, v21
	v_fma_f32 v60, v60, v6, v22
	v_fma_f32 v61, v61, v7, v23
	v_fma_f32 v62, v62, v8, v24
	v_fma_f32 v63, v63, v9, v25
	v_fma_f32 v64, v64, v10, v26
	v_fma_f32 v65, v65, v11, v27
	v_fma_f32 v66, v66, v12, v28
	v_fma_f32 v67, v67, v13, v29
	v_fma_f32 v68, v68, v14, v30
	v_fma_f32 v69, v69, v15, v31
	v_cvt_pk_f16_f32 v70, v54, v55
	v_cvt_pk_f16_f32 v71, v56, v57
	v_cvt_pk_f16_f32 v72, v58, v59
	v_cvt_pk_f16_f32 v73, v60, v61
	v_cvt_pk_f16_f32 v74, v62, v63
	v_cvt_pk_f16_f32 v75, v64, v65
	v_cvt_pk_f16_f32 v76, v66, v67
	v_cvt_pk_f16_f32 v77, v68, v69
	global_store_dwordx2 v151, v[70:71], s[36:37] offset:0 nt
	global_store_dwordx2 v151, v[72:73], s[36:37] offset:512 nt
	global_store_dwordx2 v151, v[74:75], s[36:37] offset:1024 nt
	global_store_dwordx2 v151, v[76:77], s[36:37] offset:1536 nt
	s_add_u32 s5, s5, 1
	s_sub_u32 s9, s5, 0x800
	s_lshr_b32 s9, s9, 13
	s_cmp_lt_u32 s5, 0x800
	s_cselect_b32 s9, 8, s9
	s_cmp_eq_u32 s9, s8
	s_cbranch_scc1 .Lr1b_nr8
; DI void row1_phase(const Params& P, int combine_l, int norm_l, int r_begin) {
;     ...
;   auto process = [&](int r, float4 (&xv)[4], h4 (&ya)[4], h4 (&yb)[4]) {
;     const int n = row_mod(r);
;     if (combine_l >= 0) {
;       float* xm = r < TC ? P.xcbuf + (size_t)r * D : P.out + (size_t)(r - TC) * D;
;       const float* g2 = P.mod + (size_t)(combine_l * 9 + n) * 6144 + 5 * 1024;
; #pragma unroll
;       for (int i = 0; i < 4; i++) {
;         int c = i * 256 + lane * 4;
;         float4 g = *(const float4*)(g2 + c); float4 t = xv[i];
;         t.x += g.x * ((float)ya[i][0] + (float)yb[i][0]); t.y += g.y * ((float)ya[i][1] + (float)yb[i][1]);
;         t.z += g.z * ((float)ya[i][2] + (float)yb[i][2]); t.w += g.w * ((float)ya[i][3] + (float)yb[i][3]);
;         *(float4*)(xm + c) = t; xv[i] = t;
;       }
;     }
;     if (norm_l >= 0) {
;       float ss = 0.f;
; #pragma unroll
;       for (int i = 0; i < 4; i++) ss += xv[i].x * xv[i].x + xv[i].y * xv[i].y + xv[i].z * xv[i].z + xv[i].w * xv[i].w;
	s_mov_b32 s8, s9
	s_waitcnt vmcnt(0)
	s_add_u32 s10, s9, 9
	s_mul_i32 s10, s10, 0x6000
	s_add_u32 s38, s56, s10
	s_addc_u32 s39, s57, 0
	global_load_dwordx4 v[54:57], v150, s[58:59] offset:0
	global_load_dwordx4 v[58:61], v150, s[58:59] offset:1024
	global_load_dwordx4 v[62:65], v150, s[58:59] offset:2048
	global_load_dwordx4 v[66:69], v150, s[58:59] offset:3072
	s_add_u32 s44, s38, 0x1000
	s_addc_u32 s45, s39, 0
	global_load_dwordx4 v[70:73], v150, s[44:45] offset:0
	global_load_dwordx4 v[74:77], v150, s[44:45] offset:1024
	global_load_dwordx4 v[78:81], v150, s[44:45] offset:2048
	global_load_dwordx4 v[82:85], v150, s[44:45] offset:3072
	global_load_dwordx4 v[16:19], v150, s[38:39] offset:0
	global_load_dwordx4 v[20:23], v150, s[38:39] offset:1024
	global_load_dwordx4 v[24:27], v150, s[38:39] offset:2048
	global_load_dwordx4 v[28:31], v150, s[38:39] offset:3072
	s_add_u32 s10, s9, 0
	s_mul_i32 s10, s10, 0x6000
	s_add_u32 s10, s10, 0x5000
	s_add_u32 s38, s56, s10
	s_addc_u32 s39, s57, 0
	global_load_dwordx4 v[32:35], v150, s[38:39] offset:0
	global_load_dwordx4 v[36:39], v150, s[38:39] offset:1024
	global_load_dwordx4 v[40:43], v150, s[38:39] offset:2048
	global_load_dwordx4 v[44:47], v150, s[38:39] offset:3072
	s_waitcnt vmcnt(0)
	v_add_f32_e32 v70, 1.0, v70
	v_add_f32_e32 v71, 1.0, v71
	v_add_f32_e32 v72, 1.0, v72
	v_add_f32_e32 v73, 1.0, v73
	v_add_f32_e32 v74, 1.0, v74
	v_add_f32_e32 v75, 1.0, v75
	v_add_f32_e32 v76, 1.0, v76
	v_add_f32_e32 v77, 1.0, v77
	v_add_f32_e32 v78, 1.0, v78
	v_add_f32_e32 v79, 1.0, v79
	v_add_f32_e32 v80, 1.0, v80
	v_add_f32_e32 v81, 1.0, v81
	v_add_f32_e32 v82, 1.0, v82
	v_add_f32_e32 v83, 1.0, v83
	v_add_f32_e32 v84, 1.0, v84
	v_add_f32_e32 v85, 1.0, v85
	v_mul_f32_e32 v0, v54, v70
	v_mul_f32_e32 v1, v55, v71
	v_mul_f32_e32 v2, v56, v72
	v_mul_f32_e32 v3, v57, v73
	v_mul_f32_e32 v4, v58, v74
	v_mul_f32_e32 v5, v59, v75
	v_mul_f32_e32 v6, v60, v76
	v_mul_f32_e32 v7, v61, v77
	v_mul_f32_e32 v8, v62, v78
	v_mul_f32_e32 v9, v63, v79
	v_mul_f32_e32 v10, v64, v80
	v_mul_f32_e32 v11, v65, v81
	v_mul_f32_e32 v12, v66, v82
	v_mul_f32_e32 v13, v67, v83
	v_mul_f32_e32 v14, v68, v84
	v_mul_f32_e32 v15, v69, v85
.Lr1b_nr8:
	s_waitcnt vmcnt(32)
	v_accvgpr_read_b32 v54, a96
	v_accvgpr_read_b32 v55, a97
	v_accvgpr_read_b32 v56, a98
	v_accvgpr_read_b32 v57, a99
	v_accvgpr_read_b32 v58, a100
	v_accvgpr_read_b32 v59, a101
	v_accvgpr_read_b32 v60, a102
	v_accvgpr_read_b32 v61, a103
	v_accvgpr_read_b32 v62, a104
	v_accvgpr_read_b32 v63, a105
	v_accvgpr_read_b32 v64, a106
	v_accvgpr_read_b32 v65, a107
	v_accvgpr_read_b32 v66, a108
	v_accvgpr_read_b32 v67, a109
	v_accvgpr_read_b32 v68, a110
	v_accvgpr_read_b32 v69, a111
	v_accvgpr_read_b32 v70, a112
	v_accvgpr_read_b32 v71, a113
	v_accvgpr_read_b32 v72, a114
	v_accvgpr_read_b32 v73, a115
	v_accvgpr_read_b32 v74, a116
	v_accvgpr_read_b32 v75, a117
	v_accvgpr_read_b32 v76, a118
	v_accvgpr_read_b32 v77, a119
	v_accvgpr_read_b32 v78, a120
	v_accvgpr_read_b32 v79, a121
	v_accvgpr_read_b32 v80, a122
	v_accvgpr_read_b32 v81, a123
	v_accvgpr_read_b32 v82, a124
	v_accvgpr_read_b32 v83, a125
	v_accvgpr_read_b32 v84, a126
	v_accvgpr_read_b32 v85, a127
	s_lshl_b32 s10, s5, 12
	s_cmp_lt_u32 s5, 0x800
	s_cselect_b64 s[34:35], s[48:49], s[50:51]
	s_add_u32 s34, s34, s10
	s_addc_u32 s35, s35, 0
	s_lshr_b32 s10, s10, 1
	s_add_u32 s36, s54, s10
	s_addc_u32 s37, s55, 0
	v_cvt_f32_f16_e32 v154, v70
	v_cvt_f32_f16_e32 v155, v78
	v_add_f32_e32 v154, v154, v155
	v_fmac_f32_e32 v54, v32, v154
	v_cvt_f32_f16_sdwa v156, v70 dst_sel:DWORD dst_unused:UNUSED_PAD src0_sel:WORD_1
	v_cvt_f32_f16_sdwa v157, v78 dst_sel:DWORD dst_unused:UNUSED_PAD src0_sel:WORD_1
	v_add_f32_e32 v156, v156, v157
	v_fmac_f32_e32 v55, v33, v156
	v_cvt_f32_f16_e32 v154, v71
	v_cvt_f32_f16_e32 v155, v79
	v_add_f32_e32 v154, v154, v155
	v_fmac_f32_e32 v56, v34, v154
	v_cvt_f32_f16_sdwa v156, v71 dst_sel:DWORD dst_unused:UNUSED_PAD src0_sel:WORD_1
	v_cvt_f32_f16_sdwa v157, v79 dst_sel:DWORD dst_unused:UNUSED_PAD src0_sel:WORD_1
	v_add_f32_e32 v156, v156, v157
	v_fmac_f32_e32 v57, v35, v156
	v_cvt_f32_f16_e32 v154, v72
	v_cvt_f32_f16_e32 v155, v80
	v_add_f32_e32 v154, v154, v155
	v_fmac_f32_e32 v58, v36, v154
	v_cvt_f32_f16_sdwa v156, v72 dst_sel:DWORD dst_unused:UNUSED_PAD src0_sel:WORD_1
	v_cvt_f32_f16_sdwa v157, v80 dst_sel:DWORD dst_unused:UNUSED_PAD src0_sel:WORD_1
	v_add_f32_e32 v156, v156, v157
	v_fmac_f32_e32 v59, v37, v156
	v_cvt_f32_f16_e32 v154, v73
	v_cvt_f32_f16_e32 v155, v81
	v_add_f32_e32 v154, v154, v155
	v_fmac_f32_e32 v60, v38, v154
	v_cvt_f32_f16_sdwa v156, v73 dst_sel:DWORD dst_unused:UNUSED_PAD src0_sel:WORD_1
	v_cvt_f32_f16_sdwa v157, v81 dst_sel:DWORD dst_unused:UNUSED_PAD src0_sel:WORD_1
	v_add_f32_e32 v156, v156, v157
	v_fmac_f32_e32 v61, v39, v156
	v_cvt_f32_f16_e32 v154, v74
	v_cvt_f32_f16_e32 v155, v82
	v_add_f32_e32 v154, v154, v155
	v_fmac_f32_e32 v62, v40, v154
	v_cvt_f32_f16_sdwa v156, v74 dst_sel:DWORD dst_unused:UNUSED_PAD src0_sel:WORD_1
	v_cvt_f32_f16_sdwa v157, v82 dst_sel:DWORD dst_unused:UNUSED_PAD src0_sel:WORD_1
	v_add_f32_e32 v156, v156, v157
	v_fmac_f32_e32 v63, v41, v156
	v_cvt_f32_f16_e32 v154, v75
	v_cvt_f32_f16_e32 v155, v83
	v_add_f32_e32 v154, v154, v155
	v_fmac_f32_e32 v64, v42, v154
	v_cvt_f32_f16_sdwa v156, v75 dst_sel:DWORD dst_unused:UNUSED_PAD src0_sel:WORD_1
	v_cvt_f32_f16_sdwa v157, v83 dst_sel:DWORD dst_unused:UNUSED_PAD src0_sel:WORD_1
	v_add_f32_e32 v156, v156, v157
	v_fmac_f32_e32 v65, v43, v156
	v_cvt_f32_f16_e32 v154, v76
	v_cvt_f32_f16_e32 v155, v84
	v_add_f32_e32 v154, v154, v155
	v_fmac_f32_e32 v66, v44, v154
	v_cvt_f32_f16_sdwa v156, v76 dst_sel:DWORD dst_unused:UNUSED_PAD src0_sel:WORD_1
; DI void row1_phase(const Params& P, int combine_l, int norm_l, int r_begin) {
;     ...
;         t.x += g.x * ((float)ya[i][0] + (float)yb[i][0]); t.y += g.y * ((float)ya[i][1] + (float)yb[i][1]);
;         t.z += g.z * ((float)ya[i][2] + (float)yb[i][2]); t.w += g.w * ((float)ya[i][3] + (float)yb[i][3]);
;         *(float4*)(xm + c) = t; xv[i] = t;
;       }
;     }
;     if (norm_l >= 0) {
;       float ss = 0.f;
; #pragma unroll
;       for (int i = 0; i < 4; i++) ss += xv[i].x * xv[i].x + xv[i].y * xv[i].y + xv[i].z * xv[i].z + xv[i].w * xv[i].w;
;       ss = wave_sum(ss);
;       const float rstd = rsqrtf(ss * (1.f / 1024.f) + EPS);
;       const float* g = P.norm1_g + norm_l * 1024;
;       const float* sh = P.mod + (size_t)(norm_l * 9 + n) * 6144; const float* sc = sh + 1024;
; #pragma unroll
;       for (int i = 0; i < 4; i++) {
;         int c = i * 256 + lane * 4;
;         float4 gg = *(const float4*)(g + c), s1 = *(const float4*)(sc + c), s0 = *(const float4*)(sh + c);
;         h4 o;
;         o[0] = (half_t)(xv[i].x * rstd * gg.x * (1.f + s1.x) + s0.x); o[1] = (half_t)(xv[i].y * rstd * gg.y * (1.f + s1.y) + s0.y);
;         o[2] = (half_t)(xv[i].z * rstd * gg.z * (1.f + s1.z) + s0.z); o[3] = (half_t)(xv[i].w * rstd * gg.w * (1.f + s1.w) + s0.w);
;         *(h4*)(P.hx + (size_t)r * D + c) = o;
;       }
	v_cvt_f32_f16_sdwa v157, v84 dst_sel:DWORD dst_unused:UNUSED_PAD src0_sel:WORD_1
	v_add_f32_e32 v156, v156, v157
	v_fmac_f32_e32 v67, v45, v156
	v_cvt_f32_f16_e32 v154, v77
	v_cvt_f32_f16_e32 v155, v85
	v_add_f32_e32 v154, v154, v155
	v_fmac_f32_e32 v68, v46, v154
	v_cvt_f32_f16_sdwa v156, v77 dst_sel:DWORD dst_unused:UNUSED_PAD src0_sel:WORD_1
	v_cvt_f32_f16_sdwa v157, v85 dst_sel:DWORD dst_unused:UNUSED_PAD src0_sel:WORD_1
	v_add_f32_e32 v156, v156, v157
	v_fmac_f32_e32 v69, v47, v156
	global_store_dwordx4 v150, v[54:57], s[34:35] offset:0
	global_store_dwordx4 v150, v[58:61], s[34:35] offset:1024
	global_store_dwordx4 v150, v[62:65], s[34:35] offset:2048
	global_store_dwordx4 v150, v[66:69], s[34:35] offset:3072
	v_mul_f32_e32 v152, v54, v54
	v_mul_f32_e32 v153, v55, v55
	v_fmac_f32_e32 v152, v56, v56
	v_fmac_f32_e32 v153, v57, v57
	v_fmac_f32_e32 v152, v58, v58
	v_fmac_f32_e32 v153, v59, v59
	v_fmac_f32_e32 v152, v60, v60
	v_fmac_f32_e32 v153, v61, v61
	v_fmac_f32_e32 v152, v62, v62
	v_fmac_f32_e32 v153, v63, v63
	v_fmac_f32_e32 v152, v64, v64
	v_fmac_f32_e32 v153, v65, v65
	v_fmac_f32_e32 v152, v66, v66
	v_fmac_f32_e32 v153, v67, v67
	v_fmac_f32_e32 v152, v68, v68
	v_fmac_f32_e32 v153, v69, v69
	v_add_f32_e32 v152, v152, v153
	s_nop 1
	v_add_f32_dpp v152, v152, v152 row_ror:8 row_mask:0xf bank_mask:0xf
	s_nop 1
	v_add_f32_dpp v152, v152, v152 row_ror:4 row_mask:0xf bank_mask:0xf
	s_nop 1
	v_add_f32_dpp v152, v152, v152 row_ror:2 row_mask:0xf bank_mask:0xf
	s_nop 1
	v_add_f32_dpp v152, v152, v152 row_ror:1 row_mask:0xf bank_mask:0xf
	s_nop 1
	v_readlane_b32 s22, v152, 0
	v_readlane_b32 s23, v152, 16
	v_readlane_b32 s32, v152, 32
	v_readlane_b32 s99, v152, 48
	v_mov_b32_e32 v152, s22
	v_add_f32_e32 v152, s23, v152
	v_add_f32_e32 v152, s32, v152
	v_add_f32_e32 v152, s99, v152
	v_mov_b32_e32 v153, 0x358637bd
	v_fmamk_f32 v152, v152, 0x3a800000, v153
	v_rsq_f32_e32 v152, v152
	s_nop 1
	v_mul_f32_e32 v54, v54, v152
	v_mul_f32_e32 v55, v55, v152
	v_mul_f32_e32 v56, v56, v152
	v_mul_f32_e32 v57, v57, v152
	v_mul_f32_e32 v58, v58, v152
	v_mul_f32_e32 v59, v59, v152
	v_mul_f32_e32 v60, v60, v152
	v_mul_f32_e32 v61, v61, v152
	v_mul_f32_e32 v62, v62, v152
	v_mul_f32_e32 v63, v63, v152
	v_mul_f32_e32 v64, v64, v152
	v_mul_f32_e32 v65, v65, v152
	v_mul_f32_e32 v66, v66, v152
	v_mul_f32_e32 v67, v67, v152
	v_mul_f32_e32 v68, v68, v152
	v_mul_f32_e32 v69, v69, v152
	v_fma_f32 v54, v54, v0, v16
	v_fma_f32 v55, v55, v1, v17
	v_fma_f32 v56, v56, v2, v18
	v_fma_f32 v57, v57, v3, v19
	v_fma_f32 v58, v58, v4, v20
	v_fma_f32 v59, v59, v5, v21
	v_fma_f32 v60, v60, v6, v22
	v_fma_f32 v61, v61, v7, v23
	v_fma_f32 v62, v62, v8, v24
	v_fma_f32 v63, v63, v9, v25
	v_fma_f32 v64, v64, v10, v26
	v_fma_f32 v65, v65, v11, v27
	v_fma_f32 v66, v66, v12, v28
	v_fma_f32 v67, v67, v13, v29
	v_fma_f32 v68, v68, v14, v30
	v_fma_f32 v69, v69, v15, v31
	v_cvt_pk_f16_f32 v70, v54, v55
	v_cvt_pk_f16_f32 v71, v56, v57
	v_cvt_pk_f16_f32 v72, v58, v59
	v_cvt_pk_f16_f32 v73, v60, v61
	v_cvt_pk_f16_f32 v74, v62, v63
	v_cvt_pk_f16_f32 v75, v64, v65
	v_cvt_pk_f16_f32 v76, v66, v67
	v_cvt_pk_f16_f32 v77, v68, v69
	global_store_dwordx2 v151, v[70:71], s[36:37] offset:0 nt
	global_store_dwordx2 v151, v[72:73], s[36:37] offset:512 nt
	global_store_dwordx2 v151, v[74:75], s[36:37] offset:1024 nt
	global_store_dwordx2 v151, v[76:77], s[36:37] offset:1536 nt
	s_add_u32 s5, s5, 1
	s_sub_u32 s9, s5, 0x800
	s_lshr_b32 s9, s9, 13
	s_cmp_lt_u32 s5, 0x800
	s_cselect_b32 s9, 8, s9
	s_cmp_eq_u32 s9, s8
	s_cbranch_scc1 .Lr1b_nr9
	s_mov_b32 s8, s9
	s_waitcnt vmcnt(0)
	s_add_u32 s10, s9, 9
	s_mul_i32 s10, s10, 0x6000
	s_add_u32 s38, s56, s10
	s_addc_u32 s39, s57, 0
	global_load_dwordx4 v[54:57], v150, s[58:59] offset:0
	global_load_dwordx4 v[58:61], v150, s[58:59] offset:1024
	global_load_dwordx4 v[62:65], v150, s[58:59] offset:2048
	global_load_dwordx4 v[66:69], v150, s[58:59] offset:3072
	s_add_u32 s44, s38, 0x1000
	s_addc_u32 s45, s39, 0
	global_load_dwordx4 v[70:73], v150, s[44:45] offset:0
	global_load_dwordx4 v[74:77], v150, s[44:45] offset:1024
	global_load_dwordx4 v[78:81], v150, s[44:45] offset:2048
	global_load_dwordx4 v[82:85], v150, s[44:45] offset:3072
	global_load_dwordx4 v[16:19], v150, s[38:39] offset:0
	global_load_dwordx4 v[20:23], v150, s[38:39] offset:1024
	global_load_dwordx4 v[24:27], v150, s[38:39] offset:2048
	global_load_dwordx4 v[28:31], v150, s[38:39] offset:3072
	s_add_u32 s10, s9, 0
	s_mul_i32 s10, s10, 0x6000
	s_add_u32 s10, s10, 0x5000
	s_add_u32 s38, s56, s10
	s_addc_u32 s39, s57, 0
	global_load_dwordx4 v[32:35], v150, s[38:39] offset:0
	global_load_dwordx4 v[36:39], v150, s[38:39] offset:1024
	global_load_dwordx4 v[40:43], v150, s[38:39] offset:2048
	global_load_dwordx4 v[44:47], v150, s[38:39] offset:3072
	s_waitcnt vmcnt(0)
	v_add_f32_e32 v70, 1.0, v70
	v_add_f32_e32 v71, 1.0, v71
	v_add_f32_e32 v72, 1.0, v72
	v_add_f32_e32 v73, 1.0, v73
	v_add_f32_e32 v74, 1.0, v74
	v_add_f32_e32 v75, 1.0, v75
	v_add_f32_e32 v76, 1.0, v76
	v_add_f32_e32 v77, 1.0, v77
	v_add_f32_e32 v78, 1.0, v78
	v_add_f32_e32 v79, 1.0, v79
	v_add_f32_e32 v80, 1.0, v80
	v_add_f32_e32 v81, 1.0, v81
	v_add_f32_e32 v82, 1.0, v82
	v_add_f32_e32 v83, 1.0, v83
	v_add_f32_e32 v84, 1.0, v84
	v_add_f32_e32 v85, 1.0, v85
	v_mul_f32_e32 v0, v54, v70
	v_mul_f32_e32 v1, v55, v71
	v_mul_f32_e32 v2, v56, v72
	v_mul_f32_e32 v3, v57, v73
	v_mul_f32_e32 v4, v58, v74
	v_mul_f32_e32 v5, v59, v75
	v_mul_f32_e32 v6, v60, v76
	v_mul_f32_e32 v7, v61, v77
	v_mul_f32_e32 v8, v62, v78
	v_mul_f32_e32 v9, v63, v79
	v_mul_f32_e32 v10, v64, v80
	v_mul_f32_e32 v11, v65, v81
	v_mul_f32_e32 v12, v66, v82
	v_mul_f32_e32 v13, v67, v83
	v_mul_f32_e32 v14, v68, v84
	v_mul_f32_e32 v15, v69, v85
; DI void row1_phase(const Params& P, int combine_l, int norm_l, int r_begin) {
;     ...
;   auto process = [&](int r, float4 (&xv)[4], h4 (&ya)[4], h4 (&yb)[4]) {
;     const int n = row_mod(r);
;     if (combine_l >= 0) {
;       float* xm = r < TC ? P.xcbuf + (size_t)r * D : P.out + (size_t)(r - TC) * D;
;       const float* g2 = P.mod + (size_t)(combine_l * 9 + n) * 6144 + 5 * 1024;
; #pragma unroll
;       for (int i = 0; i < 4; i++) {
;         int c = i * 256 + lane * 4;
;         float4 g = *(const float4*)(g2 + c); float4 t = xv[i];
;         t.x += g.x * ((float)ya[i][0] + (float)yb[i][0]); t.y += g.y * ((float)ya[i][1] + (float)yb[i][1]);
;         t.z += g.z * ((float)ya[i][2] + (float)yb[i][2]); t.w += g.w * ((float)ya[i][3] + (float)yb[i][3]);
;         *(float4*)(xm + c) = t; xv[i] = t;
;       }
;     }
;     if (norm_l >= 0) {
;       float ss = 0.f;
; #pragma unroll
;       for (int i = 0; i < 4; i++) ss += xv[i].x * xv[i].x + xv[i].y * xv[i].y + xv[i].z * xv[i].z + xv[i].w * xv[i].w;
;       ss = wave_sum(ss);
;       const float rstd = rsqrtf(ss * (1.f / 1024.f) + EPS);
;       const float* g = P.norm1_g + norm_l * 1024;
;       const float* sh = P.mod + (size_t)(norm_l * 9 + n) * 6144; const float* sc = sh + 1024;
; #pragma unroll
;       for (int i = 0; i < 4; i++) {
;         int c = i * 256 + lane * 4;
;         float4 gg = *(const float4*)(g + c), s1 = *(const float4*)(sc + c), s0 = *(const float4*)(sh + c);
;         h4 o;
;         o[0] = (half_t)(xv[i].x * rstd * gg.x * (1.f + s1.x) + s0.x); o[1] = (half_t)(xv[i].y * rstd * gg.y * (1.f + s1.y) + s0.y);
;         o[2] = (half_t)(xv[i].z * rstd * gg.z * (1.f + s1.z) + s0.z); o[3] = (half_t)(xv[i].w * rstd * gg.w * (1.f + s1.w) + s0.w);
;         *(h4*)(P.hx + (size_t)r * D + c) = o;
;       }
.Lr1b_nr9:
	s_waitcnt vmcnt(20)
	v_accvgpr_read_b32 v54, a0
	v_accvgpr_read_b32 v55, a1
	v_accvgpr_read_b32 v56, a2
	v_accvgpr_read_b32 v57, a3
	v_accvgpr_read_b32 v58, a4
	v_accvgpr_read_b32 v59, a5
	v_accvgpr_read_b32 v60, a6
	v_accvgpr_read_b32 v61, a7
	v_accvgpr_read_b32 v62, a8
	v_accvgpr_read_b32 v63, a9
	v_accvgpr_read_b32 v64, a10
	v_accvgpr_read_b32 v65, a11
	v_accvgpr_read_b32 v66, a12
	v_accvgpr_read_b32 v67, a13
	v_accvgpr_read_b32 v68, a14
	v_accvgpr_read_b32 v69, a15
	v_accvgpr_read_b32 v70, a16
	v_accvgpr_read_b32 v71, a17
	v_accvgpr_read_b32 v72, a18
	v_accvgpr_read_b32 v73, a19
	v_accvgpr_read_b32 v74, a20
	v_accvgpr_read_b32 v75, a21
	v_accvgpr_read_b32 v76, a22
	v_accvgpr_read_b32 v77, a23
	v_accvgpr_read_b32 v78, a24
	v_accvgpr_read_b32 v79, a25
	v_accvgpr_read_b32 v80, a26
	v_accvgpr_read_b32 v81, a27
	v_accvgpr_read_b32 v82, a28
	v_accvgpr_read_b32 v83, a29
	v_accvgpr_read_b32 v84, a30
	v_accvgpr_read_b32 v85, a31
	s_lshl_b32 s10, s5, 12
	s_cmp_lt_u32 s5, 0x800
	s_cselect_b64 s[34:35], s[48:49], s[50:51]
	s_add_u32 s34, s34, s10
	s_addc_u32 s35, s35, 0
	s_lshr_b32 s10, s10, 1
	s_add_u32 s36, s54, s10
	s_addc_u32 s37, s55, 0
	v_cvt_f32_f16_e32 v154, v70
	v_cvt_f32_f16_e32 v155, v78
	v_add_f32_e32 v154, v154, v155
	v_fmac_f32_e32 v54, v32, v154
	v_cvt_f32_f16_sdwa v156, v70 dst_sel:DWORD dst_unused:UNUSED_PAD src0_sel:WORD_1
	v_cvt_f32_f16_sdwa v157, v78 dst_sel:DWORD dst_unused:UNUSED_PAD src0_sel:WORD_1
	v_add_f32_e32 v156, v156, v157
	v_fmac_f32_e32 v55, v33, v156
	v_cvt_f32_f16_e32 v154, v71
	v_cvt_f32_f16_e32 v155, v79
	v_add_f32_e32 v154, v154, v155
	v_fmac_f32_e32 v56, v34, v154
	v_cvt_f32_f16_sdwa v156, v71 dst_sel:DWORD dst_unused:UNUSED_PAD src0_sel:WORD_1
	v_cvt_f32_f16_sdwa v157, v79 dst_sel:DWORD dst_unused:UNUSED_PAD src0_sel:WORD_1
	v_add_f32_e32 v156, v156, v157
	v_fmac_f32_e32 v57, v35, v156
	v_cvt_f32_f16_e32 v154, v72
	v_cvt_f32_f16_e32 v155, v80
	v_add_f32_e32 v154, v154, v155
	v_fmac_f32_e32 v58, v36, v154
	v_cvt_f32_f16_sdwa v156, v72 dst_sel:DWORD dst_unused:UNUSED_PAD src0_sel:WORD_1
	v_cvt_f32_f16_sdwa v157, v80 dst_sel:DWORD dst_unused:UNUSED_PAD src0_sel:WORD_1
	v_add_f32_e32 v156, v156, v157
	v_fmac_f32_e32 v59, v37, v156
	v_cvt_f32_f16_e32 v154, v73
	v_cvt_f32_f16_e32 v155, v81
	v_add_f32_e32 v154, v154, v155
	v_fmac_f32_e32 v60, v38, v154
	v_cvt_f32_f16_sdwa v156, v73 dst_sel:DWORD dst_unused:UNUSED_PAD src0_sel:WORD_1
	v_cvt_f32_f16_sdwa v157, v81 dst_sel:DWORD dst_unused:UNUSED_PAD src0_sel:WORD_1
	v_add_f32_e32 v156, v156, v157
	v_fmac_f32_e32 v61, v39, v156
	v_cvt_f32_f16_e32 v154, v74
	v_cvt_f32_f16_e32 v155, v82
	v_add_f32_e32 v154, v154, v155
	v_fmac_f32_e32 v62, v40, v154
	v_cvt_f32_f16_sdwa v156, v74 dst_sel:DWORD dst_unused:UNUSED_PAD src0_sel:WORD_1
	v_cvt_f32_f16_sdwa v157, v82 dst_sel:DWORD dst_unused:UNUSED_PAD src0_sel:WORD_1
	v_add_f32_e32 v156, v156, v157
	v_fmac_f32_e32 v63, v41, v156
	v_cvt_f32_f16_e32 v154, v75
	v_cvt_f32_f16_e32 v155, v83
	v_add_f32_e32 v154, v154, v155
	v_fmac_f32_e32 v64, v42, v154
	v_cvt_f32_f16_sdwa v156, v75 dst_sel:DWORD dst_unused:UNUSED_PAD src0_sel:WORD_1
	v_cvt_f32_f16_sdwa v157, v83 dst_sel:DWORD dst_unused:UNUSED_PAD src0_sel:WORD_1
	v_add_f32_e32 v156, v156, v157
	v_fmac_f32_e32 v65, v43, v156
	v_cvt_f32_f16_e32 v154, v76
	v_cvt_f32_f16_e32 v155, v84
	v_add_f32_e32 v154, v154, v155
	v_fmac_f32_e32 v66, v44, v154
	v_cvt_f32_f16_sdwa v156, v76 dst_sel:DWORD dst_unused:UNUSED_PAD src0_sel:WORD_1
	v_cvt_f32_f16_sdwa v157, v84 dst_sel:DWORD dst_unused:UNUSED_PAD src0_sel:WORD_1
	v_add_f32_e32 v156, v156, v157
	v_fmac_f32_e32 v67, v45, v156
	v_cvt_f32_f16_e32 v154, v77
	v_cvt_f32_f16_e32 v155, v85
	v_add_f32_e32 v154, v154, v155
	v_fmac_f32_e32 v68, v46, v154
	v_cvt_f32_f16_sdwa v156, v77 dst_sel:DWORD dst_unused:UNUSED_PAD src0_sel:WORD_1
	v_cvt_f32_f16_sdwa v157, v85 dst_sel:DWORD dst_unused:UNUSED_PAD src0_sel:WORD_1
	v_add_f32_e32 v156, v156, v157
	v_fmac_f32_e32 v69, v47, v156
	global_store_dwordx4 v150, v[54:57], s[34:35] offset:0
	global_store_dwordx4 v150, v[58:61], s[34:35] offset:1024
	global_store_dwordx4 v150, v[62:65], s[34:35] offset:2048
	global_store_dwordx4 v150, v[66:69], s[34:35] offset:3072
	v_mul_f32_e32 v152, v54, v54
	v_mul_f32_e32 v153, v55, v55
	v_fmac_f32_e32 v152, v56, v56
	v_fmac_f32_e32 v153, v57, v57
	v_fmac_f32_e32 v152, v58, v58
	v_fmac_f32_e32 v153, v59, v59
	v_fmac_f32_e32 v152, v60, v60
	v_fmac_f32_e32 v153, v61, v61
	v_fmac_f32_e32 v152, v62, v62
	v_fmac_f32_e32 v153, v63, v63
	v_fmac_f32_e32 v152, v64, v64
	v_fmac_f32_e32 v153, v65, v65
	v_fmac_f32_e32 v152, v66, v66
	v_fmac_f32_e32 v153, v67, v67
	v_fmac_f32_e32 v152, v68, v68
	v_fmac_f32_e32 v153, v69, v69
	v_add_f32_e32 v152, v152, v153
	s_nop 1
	v_add_f32_dpp v152, v152, v152 row_ror:8 row_mask:0xf bank_mask:0xf
	s_nop 1
	v_add_f32_dpp v152, v152, v152 row_ror:4 row_mask:0xf bank_mask:0xf
	s_nop 1
	v_add_f32_dpp v152, v152, v152 row_ror:2 row_mask:0xf bank_mask:0xf
	s_nop 1
	v_add_f32_dpp v152, v152, v152 row_ror:1 row_mask:0xf bank_mask:0xf
	s_nop 1
	v_readlane_b32 s22, v152, 0
	v_readlane_b32 s23, v152, 16
	v_readlane_b32 s32, v152, 32
	v_readlane_b32 s99, v152, 48
	v_mov_b32_e32 v152, s22
	v_add_f32_e32 v152, s23, v152
	v_add_f32_e32 v152, s32, v152
	v_add_f32_e32 v152, s99, v152
	v_mov_b32_e32 v153, 0x358637bd
	v_fmamk_f32 v152, v152, 0x3a800000, v153
	v_rsq_f32_e32 v152, v152
	s_nop 1
	v_mul_f32_e32 v54, v54, v152
	v_mul_f32_e32 v55, v55, v152
	v_mul_f32_e32 v56, v56, v152
	v_mul_f32_e32 v57, v57, v152
	v_mul_f32_e32 v58, v58, v152
	v_mul_f32_e32 v59, v59, v152
	v_mul_f32_e32 v60, v60, v152
	v_mul_f32_e32 v61, v61, v152
	v_mul_f32_e32 v62, v62, v152
	v_mul_f32_e32 v63, v63, v152
	v_mul_f32_e32 v64, v64, v152
	v_mul_f32_e32 v65, v65, v152
	v_mul_f32_e32 v66, v66, v152
	v_mul_f32_e32 v67, v67, v152
	v_mul_f32_e32 v68, v68, v152
	v_mul_f32_e32 v69, v69, v152
	v_fma_f32 v54, v54, v0, v16
	v_fma_f32 v55, v55, v1, v17
	v_fma_f32 v56, v56, v2, v18
	v_fma_f32 v57, v57, v3, v19
	v_fma_f32 v58, v58, v4, v20
	v_fma_f32 v59, v59, v5, v21
	v_fma_f32 v60, v60, v6, v22
	v_fma_f32 v61, v61, v7, v23
	v_fma_f32 v62, v62, v8, v24
	v_fma_f32 v63, v63, v9, v25
	v_fma_f32 v64, v64, v10, v26
	v_fma_f32 v65, v65, v11, v27
	v_fma_f32 v66, v66, v12, v28
	v_fma_f32 v67, v67, v13, v29
	v_fma_f32 v68, v68, v14, v30
	v_fma_f32 v69, v69, v15, v31
	v_cvt_pk_f16_f32 v70, v54, v55
	v_cvt_pk_f16_f32 v71, v56, v57
	v_cvt_pk_f16_f32 v72, v58, v59
	v_cvt_pk_f16_f32 v73, v60, v61
	v_cvt_pk_f16_f32 v74, v62, v63
	v_cvt_pk_f16_f32 v75, v64, v65
	v_cvt_pk_f16_f32 v76, v66, v67
	v_cvt_pk_f16_f32 v77, v68, v69
	global_store_dwordx2 v151, v[70:71], s[36:37] offset:0 nt
	global_store_dwordx2 v151, v[72:73], s[36:37] offset:512 nt
	global_store_dwordx2 v151, v[74:75], s[36:37] offset:1024 nt
	global_store_dwordx2 v151, v[76:77], s[36:37] offset:1536 nt
	s_add_u32 s5, s5, 1
	s_sub_u32 s9, s5, 0x800
	s_lshr_b32 s9, s9, 13
	s_cmp_lt_u32 s5, 0x800
	s_cselect_b32 s9, 8, s9
	s_cmp_eq_u32 s9, s8
	s_cbranch_scc1 .Lr1b_nr10
; DI void row1_phase(const Params& P, int combine_l, int norm_l, int r_begin) {
;     ...
;       const float* sh = P.mod + (size_t)(norm_l * 9 + n) * 6144; const float* sc = sh + 1024;
; #pragma unroll
;       for (int i = 0; i < 4; i++) {
;         int c = i * 256 + lane * 4;
;         float4 gg = *(const float4*)(g + c), s1 = *(const float4*)(sc + c), s0 = *(const float4*)(sh + c);
	s_mov_b32 s8, s9
	s_waitcnt vmcnt(0)
	s_add_u32 s10, s9, 9
	s_mul_i32 s10, s10, 0x6000
	s_add_u32 s38, s56, s10
	s_addc_u32 s39, s57, 0
	global_load_dwordx4 v[54:57], v150, s[58:59] offset:0
	global_load_dwordx4 v[58:61], v150, s[58:59] offset:1024
	global_load_dwordx4 v[62:65], v150, s[58:59] offset:2048
	global_load_dwordx4 v[66:69], v150, s[58:59] offset:3072
	s_add_u32 s44, s38, 0x1000
	s_addc_u32 s45, s39, 0
	global_load_dwordx4 v[70:73], v150, s[44:45] offset:0
	global_load_dwordx4 v[74:77], v150, s[44:45] offset:1024
	global_load_dwordx4 v[78:81], v150, s[44:45] offset:2048
	global_load_dwordx4 v[82:85], v150, s[44:45] offset:3072
	global_load_dwordx4 v[16:19], v150, s[38:39] offset:0
	global_load_dwordx4 v[20:23], v150, s[38:39] offset:1024
	global_load_dwordx4 v[24:27], v150, s[38:39] offset:2048
	global_load_dwordx4 v[28:31], v150, s[38:39] offset:3072
	s_add_u32 s10, s9, 0
	s_mul_i32 s10, s10, 0x6000
	s_add_u32 s10, s10, 0x5000
	s_add_u32 s38, s56, s10
	s_addc_u32 s39, s57, 0
	global_load_dwordx4 v[32:35], v150, s[38:39] offset:0
	global_load_dwordx4 v[36:39], v150, s[38:39] offset:1024
	global_load_dwordx4 v[40:43], v150, s[38:39] offset:2048
	global_load_dwordx4 v[44:47], v150, s[38:39] offset:3072
	s_waitcnt vmcnt(0)
	v_add_f32_e32 v70, 1.0, v70
	v_add_f32_e32 v71, 1.0, v71
	v_add_f32_e32 v72, 1.0, v72
	v_add_f32_e32 v73, 1.0, v73
	v_add_f32_e32 v74, 1.0, v74
	v_add_f32_e32 v75, 1.0, v75
	v_add_f32_e32 v76, 1.0, v76
	v_add_f32_e32 v77, 1.0, v77
	v_add_f32_e32 v78, 1.0, v78
	v_add_f32_e32 v79, 1.0, v79
	v_add_f32_e32 v80, 1.0, v80
	v_add_f32_e32 v81, 1.0, v81
	v_add_f32_e32 v82, 1.0, v82
	v_add_f32_e32 v83, 1.0, v83
	v_add_f32_e32 v84, 1.0, v84
	v_add_f32_e32 v85, 1.0, v85
	v_mul_f32_e32 v0, v54, v70
	v_mul_f32_e32 v1, v55, v71
	v_mul_f32_e32 v2, v56, v72
	v_mul_f32_e32 v3, v57, v73
	v_mul_f32_e32 v4, v58, v74
	v_mul_f32_e32 v5, v59, v75
	v_mul_f32_e32 v6, v60, v76
	v_mul_f32_e32 v7, v61, v77
	v_mul_f32_e32 v8, v62, v78
	v_mul_f32_e32 v9, v63, v79
	v_mul_f32_e32 v10, v64, v80
	v_mul_f32_e32 v11, v65, v81
	v_mul_f32_e32 v12, v66, v82
	v_mul_f32_e32 v13, v67, v83
	v_mul_f32_e32 v14, v68, v84
	v_mul_f32_e32 v15, v69, v85
; DI void row1_phase(const Params& P, int combine_l, int norm_l, int r_begin) {
;     ...
;   auto process = [&](int r, float4 (&xv)[4], h4 (&ya)[4], h4 (&yb)[4]) {
;     const int n = row_mod(r);
;     if (combine_l >= 0) {
;       float* xm = r < TC ? P.xcbuf + (size_t)r * D : P.out + (size_t)(r - TC) * D;
;       const float* g2 = P.mod + (size_t)(combine_l * 9 + n) * 6144 + 5 * 1024;
; #pragma unroll
;       for (int i = 0; i < 4; i++) {
;         int c = i * 256 + lane * 4;
;         float4 g = *(const float4*)(g2 + c); float4 t = xv[i];
;         t.x += g.x * ((float)ya[i][0] + (float)yb[i][0]); t.y += g.y * ((float)ya[i][1] + (float)yb[i][1]);
;         t.z += g.z * ((float)ya[i][2] + (float)yb[i][2]); t.w += g.w * ((float)ya[i][3] + (float)yb[i][3]);
;         *(float4*)(xm + c) = t; xv[i] = t;
;       }
;     }
;     if (norm_l >= 0) {
;       float ss = 0.f;
; #pragma unroll
;       for (int i = 0; i < 4; i++) ss += xv[i].x * xv[i].x + xv[i].y * xv[i].y + xv[i].z * xv[i].z + xv[i].w * xv[i].w;
;       ss = wave_sum(ss);
;       const float rstd = rsqrtf(ss * (1.f / 1024.f) + EPS);
;       const float* g = P.norm1_g + norm_l * 1024;
;       const float* sh = P.mod + (size_t)(norm_l * 9 + n) * 6144; const float* sc = sh + 1024;
; #pragma unroll
;       for (int i = 0; i < 4; i++) {
;         int c = i * 256 + lane * 4;
;         float4 gg = *(const float4*)(g + c), s1 = *(const float4*)(sc + c), s0 = *(const float4*)(sh + c);
;         h4 o;
;         o[0] = (half_t)(xv[i].x * rstd * gg.x * (1.f + s1.x) + s0.x); o[1] = (half_t)(xv[i].y * rstd * gg.y * (1.f + s1.y) + s0.y);
;         o[2] = (half_t)(xv[i].z * rstd * gg.z * (1.f + s1.z) + s0.z); o[3] = (half_t)(xv[i].w * rstd * gg.w * (1.f + s1.w) + s0.w);
;         *(h4*)(P.hx + (size_t)r * D + c) = o;
;       }
.Lr1b_nr10:
	s_waitcnt vmcnt(8)
	v_accvgpr_read_b32 v54, a32
	v_accvgpr_read_b32 v55, a33
	v_accvgpr_read_b32 v56, a34
	v_accvgpr_read_b32 v57, a35
	v_accvgpr_read_b32 v58, a36
	v_accvgpr_read_b32 v59, a37
	v_accvgpr_read_b32 v60, a38
	v_accvgpr_read_b32 v61, a39
	v_accvgpr_read_b32 v62, a40
	v_accvgpr_read_b32 v63, a41
	v_accvgpr_read_b32 v64, a42
	v_accvgpr_read_b32 v65, a43
	v_accvgpr_read_b32 v66, a44
	v_accvgpr_read_b32 v67, a45
	v_accvgpr_read_b32 v68, a46
	v_accvgpr_read_b32 v69, a47
	v_accvgpr_read_b32 v70, a48
	v_accvgpr_read_b32 v71, a49
	v_accvgpr_read_b32 v72, a50
	v_accvgpr_read_b32 v73, a51
	v_accvgpr_read_b32 v74, a52
	v_accvgpr_read_b32 v75, a53
	v_accvgpr_read_b32 v76, a54
	v_accvgpr_read_b32 v77, a55
	v_accvgpr_read_b32 v78, a56
	v_accvgpr_read_b32 v79, a57
	v_accvgpr_read_b32 v80, a58
	v_accvgpr_read_b32 v81, a59
	v_accvgpr_read_b32 v82, a60
	v_accvgpr_read_b32 v83, a61
	v_accvgpr_read_b32 v84, a62
	v_accvgpr_read_b32 v85, a63
	s_lshl_b32 s10, s5, 12
	s_cmp_lt_u32 s5, 0x800
	s_cselect_b64 s[34:35], s[48:49], s[50:51]
	s_add_u32 s34, s34, s10
	s_addc_u32 s35, s35, 0
	s_lshr_b32 s10, s10, 1
	s_add_u32 s36, s54, s10
	s_addc_u32 s37, s55, 0
	v_cvt_f32_f16_e32 v154, v70
	v_cvt_f32_f16_e32 v155, v78
	v_add_f32_e32 v154, v154, v155
	v_fmac_f32_e32 v54, v32, v154
	v_cvt_f32_f16_sdwa v156, v70 dst_sel:DWORD dst_unused:UNUSED_PAD src0_sel:WORD_1
	v_cvt_f32_f16_sdwa v157, v78 dst_sel:DWORD dst_unused:UNUSED_PAD src0_sel:WORD_1
	v_add_f32_e32 v156, v156, v157
	v_fmac_f32_e32 v55, v33, v156
	v_cvt_f32_f16_e32 v154, v71
	v_cvt_f32_f16_e32 v155, v79
	v_add_f32_e32 v154, v154, v155
	v_fmac_f32_e32 v56, v34, v154
	v_cvt_f32_f16_sdwa v156, v71 dst_sel:DWORD dst_unused:UNUSED_PAD src0_sel:WORD_1
	v_cvt_f32_f16_sdwa v157, v79 dst_sel:DWORD dst_unused:UNUSED_PAD src0_sel:WORD_1
	v_add_f32_e32 v156, v156, v157
	v_fmac_f32_e32 v57, v35, v156
	v_cvt_f32_f16_e32 v154, v72
	v_cvt_f32_f16_e32 v155, v80
	v_add_f32_e32 v154, v154, v155
	v_fmac_f32_e32 v58, v36, v154
	v_cvt_f32_f16_sdwa v156, v72 dst_sel:DWORD dst_unused:UNUSED_PAD src0_sel:WORD_1
	v_cvt_f32_f16_sdwa v157, v80 dst_sel:DWORD dst_unused:UNUSED_PAD src0_sel:WORD_1
	v_add_f32_e32 v156, v156, v157
	v_fmac_f32_e32 v59, v37, v156
	v_cvt_f32_f16_e32 v154, v73
	v_cvt_f32_f16_e32 v155, v81
	v_add_f32_e32 v154, v154, v155
	v_fmac_f32_e32 v60, v38, v154
	v_cvt_f32_f16_sdwa v156, v73 dst_sel:DWORD dst_unused:UNUSED_PAD src0_sel:WORD_1
	v_cvt_f32_f16_sdwa v157, v81 dst_sel:DWORD dst_unused:UNUSED_PAD src0_sel:WORD_1
	v_add_f32_e32 v156, v156, v157
	v_fmac_f32_e32 v61, v39, v156
	v_cvt_f32_f16_e32 v154, v74
	v_cvt_f32_f16_e32 v155, v82
	v_add_f32_e32 v154, v154, v155
	v_fmac_f32_e32 v62, v40, v154
	v_cvt_f32_f16_sdwa v156, v74 dst_sel:DWORD dst_unused:UNUSED_PAD src0_sel:WORD_1
	v_cvt_f32_f16_sdwa v157, v82 dst_sel:DWORD dst_unused:UNUSED_PAD src0_sel:WORD_1
	v_add_f32_e32 v156, v156, v157
	v_fmac_f32_e32 v63, v41, v156
	v_cvt_f32_f16_e32 v154, v75
	v_cvt_f32_f16_e32 v155, v83
	v_add_f32_e32 v154, v154, v155
	v_fmac_f32_e32 v64, v42, v154
	v_cvt_f32_f16_sdwa v156, v75 dst_sel:DWORD dst_unused:UNUSED_PAD src0_sel:WORD_1
	v_cvt_f32_f16_sdwa v157, v83 dst_sel:DWORD dst_unused:UNUSED_PAD src0_sel:WORD_1
	v_add_f32_e32 v156, v156, v157
	v_fmac_f32_e32 v65, v43, v156
	v_cvt_f32_f16_e32 v154, v76
	v_cvt_f32_f16_e32 v155, v84
	v_add_f32_e32 v154, v154, v155
	v_fmac_f32_e32 v66, v44, v154
	v_cvt_f32_f16_sdwa v156, v76 dst_sel:DWORD dst_unused:UNUSED_PAD src0_sel:WORD_1
	v_cvt_f32_f16_sdwa v157, v84 dst_sel:DWORD dst_unused:UNUSED_PAD src0_sel:WORD_1
	v_add_f32_e32 v156, v156, v157
	v_fmac_f32_e32 v67, v45, v156
	v_cvt_f32_f16_e32 v154, v77
	v_cvt_f32_f16_e32 v155, v85
	v_add_f32_e32 v154, v154, v155
	v_fmac_f32_e32 v68, v46, v154
	v_cvt_f32_f16_sdwa v156, v77 dst_sel:DWORD dst_unused:UNUSED_PAD src0_sel:WORD_1
	v_cvt_f32_f16_sdwa v157, v85 dst_sel:DWORD dst_unused:UNUSED_PAD src0_sel:WORD_1
	v_add_f32_e32 v156, v156, v157
	v_fmac_f32_e32 v69, v47, v156
	global_store_dwordx4 v150, v[54:57], s[34:35] offset:0
	global_store_dwordx4 v150, v[58:61], s[34:35] offset:1024
	global_store_dwordx4 v150, v[62:65], s[34:35] offset:2048
	global_store_dwordx4 v150, v[66:69], s[34:35] offset:3072
	v_mul_f32_e32 v152, v54, v54
	v_mul_f32_e32 v153, v55, v55
	v_fmac_f32_e32 v152, v56, v56
	v_fmac_f32_e32 v153, v57, v57
	v_fmac_f32_e32 v152, v58, v58
	v_fmac_f32_e32 v153, v59, v59
	v_fmac_f32_e32 v152, v60, v60
	v_fmac_f32_e32 v153, v61, v61
	v_fmac_f32_e32 v152, v62, v62
	v_fmac_f32_e32 v153, v63, v63
	v_fmac_f32_e32 v152, v64, v64
	v_fmac_f32_e32 v153, v65, v65
	v_fmac_f32_e32 v152, v66, v66
	v_fmac_f32_e32 v153, v67, v67
	v_fmac_f32_e32 v152, v68, v68
	v_fmac_f32_e32 v153, v69, v69
	v_add_f32_e32 v152, v152, v153
	s_nop 1
	v_add_f32_dpp v152, v152, v152 row_ror:8 row_mask:0xf bank_mask:0xf
	s_nop 1
	v_add_f32_dpp v152, v152, v152 row_ror:4 row_mask:0xf bank_mask:0xf
	s_nop 1
	v_add_f32_dpp v152, v152, v152 row_ror:2 row_mask:0xf bank_mask:0xf
	s_nop 1
	v_add_f32_dpp v152, v152, v152 row_ror:1 row_mask:0xf bank_mask:0xf
	s_nop 1
	v_readlane_b32 s22, v152, 0
	v_readlane_b32 s23, v152, 16
	v_readlane_b32 s32, v152, 32
	v_readlane_b32 s99, v152, 48
	v_mov_b32_e32 v152, s22
	v_add_f32_e32 v152, s23, v152
	v_add_f32_e32 v152, s32, v152
	v_add_f32_e32 v152, s99, v152
	v_mov_b32_e32 v153, 0x358637bd
	v_fmamk_f32 v152, v152, 0x3a800000, v153
	v_rsq_f32_e32 v152, v152
	s_nop 1
	v_mul_f32_e32 v54, v54, v152
	v_mul_f32_e32 v55, v55, v152
	v_mul_f32_e32 v56, v56, v152
	v_mul_f32_e32 v57, v57, v152
	v_mul_f32_e32 v58, v58, v152
	v_mul_f32_e32 v59, v59, v152
	v_mul_f32_e32 v60, v60, v152
	v_mul_f32_e32 v61, v61, v152
	v_mul_f32_e32 v62, v62, v152
	v_mul_f32_e32 v63, v63, v152
	v_mul_f32_e32 v64, v64, v152
	v_mul_f32_e32 v65, v65, v152
	v_mul_f32_e32 v66, v66, v152
	v_mul_f32_e32 v67, v67, v152
	v_mul_f32_e32 v68, v68, v152
	v_mul_f32_e32 v69, v69, v152
	v_fma_f32 v54, v54, v0, v16
	v_fma_f32 v55, v55, v1, v17
	v_fma_f32 v56, v56, v2, v18
	v_fma_f32 v57, v57, v3, v19
	v_fma_f32 v58, v58, v4, v20
	v_fma_f32 v59, v59, v5, v21
	v_fma_f32 v60, v60, v6, v22
	v_fma_f32 v61, v61, v7, v23
	v_fma_f32 v62, v62, v8, v24
	v_fma_f32 v63, v63, v9, v25
	v_fma_f32 v64, v64, v10, v26
	v_fma_f32 v65, v65, v11, v27
	v_fma_f32 v66, v66, v12, v28
	v_fma_f32 v67, v67, v13, v29
	v_fma_f32 v68, v68, v14, v30
	v_fma_f32 v69, v69, v15, v31
	v_cvt_pk_f16_f32 v70, v54, v55
	v_cvt_pk_f16_f32 v71, v56, v57
	v_cvt_pk_f16_f32 v72, v58, v59
	v_cvt_pk_f16_f32 v73, v60, v61
	v_cvt_pk_f16_f32 v74, v62, v63
	v_cvt_pk_f16_f32 v75, v64, v65
	v_cvt_pk_f16_f32 v76, v66, v67
	v_cvt_pk_f16_f32 v77, v68, v69
	global_store_dwordx2 v151, v[70:71], s[36:37] offset:0 nt
	global_store_dwordx2 v151, v[72:73], s[36:37] offset:512 nt
	global_store_dwordx2 v151, v[74:75], s[36:37] offset:1024 nt
	global_store_dwordx2 v151, v[76:77], s[36:37] offset:1536 nt
	s_add_u32 s5, s5, 1
	s_waitcnt vmcnt(0)
	s_branch .Lr1_done

; DI void row1_phase(const Params& P, int combine_l, int norm_l, int r_begin) {
;     ...
;     if (combine_l < 0) {
;       const float* src = r < TC ? P.ctx + (size_t)r * D : P.x + (size_t)(r - TC) * D;
; #pragma unroll
;       for (int i = 0; i < 4; i++) xv[i] = *(const float4*)(src + i * 256 + lane * 4);
;     ...
;     if (norm_l >= 0) {
;       float ss = 0.f;
; #pragma unroll
;       for (int i = 0; i < 4; i++) ss += xv[i].x * xv[i].x + xv[i].y * xv[i].y + xv[i].z * xv[i].z + xv[i].w * xv[i].w;
;       ss = wave_sum(ss);
;       const float rstd = rsqrtf(ss * (1.f / 1024.f) + EPS);
;       const float* g = P.norm1_g + norm_l * 1024;
;       const float* sh = P.mod + (size_t)(norm_l * 9 + n) * 6144; const float* sc = sh + 1024;
; #pragma unroll
;       for (int i = 0; i < 4; i++) {
;         int c = i * 256 + lane * 4;
;         float4 gg = *(const float4*)(g + c), s1 = *(const float4*)(sc + c), s0 = *(const float4*)(sh + c);
;         h4 o;
;         o[0] = (half_t)(xv[i].x * rstd * gg.x * (1.f + s1.x) + s0.x); o[1] = (half_t)(xv[i].y * rstd * gg.y * (1.f + s1.y) + s0.y);
;         o[2] = (half_t)(xv[i].z * rstd * gg.z * (1.f + s1.z) + s0.z); o[3] = (half_t)(xv[i].w * rstd * gg.w * (1.f + s1.w) + s0.w);
;         *(h4*)(P.hx + (size_t)r * D + c) = o;
;       }
.Lr1a_nr1:
	s_waitcnt vmcnt(16)
	v_accvgpr_read_b32 v54, a0
	v_accvgpr_read_b32 v55, a1
	v_accvgpr_read_b32 v56, a2
	v_accvgpr_read_b32 v57, a3
	v_accvgpr_read_b32 v58, a4
	v_accvgpr_read_b32 v59, a5
	v_accvgpr_read_b32 v60, a6
	v_accvgpr_read_b32 v61, a7
	v_accvgpr_read_b32 v62, a8
	v_accvgpr_read_b32 v63, a9
	v_accvgpr_read_b32 v64, a10
	v_accvgpr_read_b32 v65, a11
	v_accvgpr_read_b32 v66, a12
	v_accvgpr_read_b32 v67, a13
	v_accvgpr_read_b32 v68, a14
	v_accvgpr_read_b32 v69, a15
	s_lshl_b32 s10, s5, 12
	s_lshr_b32 s10, s10, 1
	s_add_u32 s36, s54, s10
	s_addc_u32 s37, s55, 0
	s_cmp_lt_u32 s7, 0x800
	s_cselect_b64 s[60:61], s[48:49], s[50:51]
	s_lshl_b32 s10, s7, 12
	s_add_u32 s60, s60, s10
	s_addc_u32 s61, s61, 0
	global_load_dwordx4 a[0:3], v150, s[60:61] offset:0 nt
	global_load_dwordx4 a[4:7], v150, s[60:61] offset:1024 nt
	global_load_dwordx4 a[8:11], v150, s[60:61] offset:2048 nt
	global_load_dwordx4 a[12:15], v150, s[60:61] offset:3072 nt
	s_add_u32 s7, s7, 1
	v_mul_f32_e32 v152, v54, v54
	v_mul_f32_e32 v153, v55, v55
	v_fmac_f32_e32 v152, v56, v56
	v_fmac_f32_e32 v153, v57, v57
	v_fmac_f32_e32 v152, v58, v58
	v_fmac_f32_e32 v153, v59, v59
	v_fmac_f32_e32 v152, v60, v60
	v_fmac_f32_e32 v153, v61, v61
	v_fmac_f32_e32 v152, v62, v62
	v_fmac_f32_e32 v153, v63, v63
	v_fmac_f32_e32 v152, v64, v64
	v_fmac_f32_e32 v153, v65, v65
	v_fmac_f32_e32 v152, v66, v66
	v_fmac_f32_e32 v153, v67, v67
	v_fmac_f32_e32 v152, v68, v68
	v_fmac_f32_e32 v153, v69, v69
	v_add_f32_e32 v152, v152, v153
	s_nop 1
	v_add_f32_dpp v152, v152, v152 row_ror:8 row_mask:0xf bank_mask:0xf
	s_nop 1
	v_add_f32_dpp v152, v152, v152 row_ror:4 row_mask:0xf bank_mask:0xf
	s_nop 1
	v_add_f32_dpp v152, v152, v152 row_ror:2 row_mask:0xf bank_mask:0xf
	s_nop 1
	v_add_f32_dpp v152, v152, v152 row_ror:1 row_mask:0xf bank_mask:0xf
	s_nop 1
	v_readlane_b32 s22, v152, 0
	v_readlane_b32 s23, v152, 16
	v_readlane_b32 s32, v152, 32
	v_readlane_b32 s99, v152, 48
	v_mov_b32_e32 v152, s22
	v_add_f32_e32 v152, s23, v152
	v_add_f32_e32 v152, s32, v152
	v_add_f32_e32 v152, s99, v152
	v_mov_b32_e32 v153, 0x358637bd
	v_fmamk_f32 v152, v152, 0x3a800000, v153
	v_rsq_f32_e32 v152, v152
	s_nop 1
	v_mul_f32_e32 v54, v54, v152
	v_mul_f32_e32 v55, v55, v152
	v_mul_f32_e32 v56, v56, v152
	v_mul_f32_e32 v57, v57, v152
	v_mul_f32_e32 v58, v58, v152
	v_mul_f32_e32 v59, v59, v152
	v_mul_f32_e32 v60, v60, v152
	v_mul_f32_e32 v61, v61, v152
	v_mul_f32_e32 v62, v62, v152
	v_mul_f32_e32 v63, v63, v152
	v_mul_f32_e32 v64, v64, v152
	v_mul_f32_e32 v65, v65, v152
	v_mul_f32_e32 v66, v66, v152
	v_mul_f32_e32 v67, v67, v152
	v_mul_f32_e32 v68, v68, v152
	v_mul_f32_e32 v69, v69, v152
	v_fma_f32 v54, v54, v0, v16
	v_fma_f32 v55, v55, v1, v17
	v_fma_f32 v56, v56, v2, v18
	v_fma_f32 v57, v57, v3, v19
	v_fma_f32 v58, v58, v4, v20
	v_fma_f32 v59, v59, v5, v21
	v_fma_f32 v60, v60, v6, v22
	v_fma_f32 v61, v61, v7, v23
	v_fma_f32 v62, v62, v8, v24
	v_fma_f32 v63, v63, v9, v25
	v_fma_f32 v64, v64, v10, v26
	v_fma_f32 v65, v65, v11, v27
	v_fma_f32 v66, v66, v12, v28
	v_fma_f32 v67, v67, v13, v29
	v_fma_f32 v68, v68, v14, v30
	v_fma_f32 v69, v69, v15, v31
	v_cvt_pk_f16_f32 v70, v54, v55
	v_cvt_pk_f16_f32 v71, v56, v57
	v_cvt_pk_f16_f32 v72, v58, v59
	v_cvt_pk_f16_f32 v73, v60, v61
	v_cvt_pk_f16_f32 v74, v62, v63
	v_cvt_pk_f16_f32 v75, v64, v65
	v_cvt_pk_f16_f32 v76, v66, v67
	v_cvt_pk_f16_f32 v77, v68, v69
	global_store_dwordx2 v151, v[70:71], s[36:37] offset:0 nt
	global_store_dwordx2 v151, v[72:73], s[36:37] offset:512 nt
	global_store_dwordx2 v151, v[74:75], s[36:37] offset:1024 nt
	global_store_dwordx2 v151, v[76:77], s[36:37] offset:1536 nt
	s_add_u32 s5, s5, 1
	s_sub_u32 s9, s5, 0x800
	s_lshr_b32 s9, s9, 13
	s_cmp_lt_u32 s5, 0x800
	s_cselect_b32 s9, 8, s9
	s_cmp_eq_u32 s9, s8
	s_cbranch_scc1 .Lr1a_nr2
	s_mov_b32 s8, s9
	s_waitcnt vmcnt(0)
	s_add_u32 s10, s9, 0
	s_mul_i32 s10, s10, 0x6000
	s_add_u32 s38, s56, s10
	s_addc_u32 s39, s57, 0
	global_load_dwordx4 v[54:57], v150, s[58:59] offset:0
	global_load_dwordx4 v[58:61], v150, s[58:59] offset:1024
	global_load_dwordx4 v[62:65], v150, s[58:59] offset:2048
	global_load_dwordx4 v[66:69], v150, s[58:59] offset:3072
	s_add_u32 s44, s38, 0x1000
	s_addc_u32 s45, s39, 0
	global_load_dwordx4 v[70:73], v150, s[44:45] offset:0
	global_load_dwordx4 v[74:77], v150, s[44:45] offset:1024
	global_load_dwordx4 v[78:81], v150, s[44:45] offset:2048
	global_load_dwordx4 v[82:85], v150, s[44:45] offset:3072
	global_load_dwordx4 v[16:19], v150, s[38:39] offset:0
	global_load_dwordx4 v[20:23], v150, s[38:39] offset:1024
	global_load_dwordx4 v[24:27], v150, s[38:39] offset:2048
	global_load_dwordx4 v[28:31], v150, s[38:39] offset:3072
	s_waitcnt vmcnt(0)
	v_add_f32_e32 v70, 1.0, v70
	v_add_f32_e32 v71, 1.0, v71
	v_add_f32_e32 v72, 1.0, v72
	v_add_f32_e32 v73, 1.0, v73
	v_add_f32_e32 v74, 1.0, v74
	v_add_f32_e32 v75, 1.0, v75
	v_add_f32_e32 v76, 1.0, v76
	v_add_f32_e32 v77, 1.0, v77
	v_add_f32_e32 v78, 1.0, v78
	v_add_f32_e32 v79, 1.0, v79
	v_add_f32_e32 v80, 1.0, v80
	v_add_f32_e32 v81, 1.0, v81
	v_add_f32_e32 v82, 1.0, v82
	v_add_f32_e32 v83, 1.0, v83
	v_add_f32_e32 v84, 1.0, v84
	v_add_f32_e32 v85, 1.0, v85
	v_mul_f32_e32 v0, v54, v70
	v_mul_f32_e32 v1, v55, v71
	v_mul_f32_e32 v2, v56, v72
	v_mul_f32_e32 v3, v57, v73
	v_mul_f32_e32 v4, v58, v74
	v_mul_f32_e32 v5, v59, v75
	v_mul_f32_e32 v6, v60, v76
	v_mul_f32_e32 v7, v61, v77
	v_mul_f32_e32 v8, v62, v78
	v_mul_f32_e32 v9, v63, v79
	v_mul_f32_e32 v10, v64, v80
	v_mul_f32_e32 v11, v65, v81
	v_mul_f32_e32 v12, v66, v82
	v_mul_f32_e32 v13, v67, v83
	v_mul_f32_e32 v14, v68, v84
	v_mul_f32_e32 v15, v69, v85
; DI void row1_phase(const Params& P, int combine_l, int norm_l, int r_begin) {
;     ...
;     if (combine_l < 0) {
;       const float* src = r < TC ? P.ctx + (size_t)r * D : P.x + (size_t)(r - TC) * D;
; #pragma unroll
;       for (int i = 0; i < 4; i++) xv[i] = *(const float4*)(src + i * 256 + lane * 4);
;     ...
;     if (norm_l >= 0) {
;       float ss = 0.f;
; #pragma unroll
;       for (int i = 0; i < 4; i++) ss += xv[i].x * xv[i].x + xv[i].y * xv[i].y + xv[i].z * xv[i].z + xv[i].w * xv[i].w;
;       ss = wave_sum(ss);
;       const float rstd = rsqrtf(ss * (1.f / 1024.f) + EPS);
;       const float* g = P.norm1_g + norm_l * 1024;
;       const float* sh = P.mod + (size_t)(norm_l * 9 + n) * 6144; const float* sc = sh + 1024;
; #pragma unroll
;       for (int i = 0; i < 4; i++) {
;         int c = i * 256 + lane * 4;
;         float4 gg = *(const float4*)(g + c), s1 = *(const float4*)(sc + c), s0 = *(const float4*)(sh + c);
;         h4 o;
;         o[0] = (half_t)(xv[i].x * rstd * gg.x * (1.f + s1.x) + s0.x); o[1] = (half_t)(xv[i].y * rstd * gg.y * (1.f + s1.y) + s0.y);
;         o[2] = (half_t)(xv[i].z * rstd * gg.z * (1.f + s1.z) + s0.z); o[3] = (half_t)(xv[i].w * rstd * gg.w * (1.f + s1.w) + s0.w);
;         *(h4*)(P.hx + (size_t)r * D + c) = o;
;       }
.Lr1a_nr2:
	s_waitcnt vmcnt(16)
	v_accvgpr_read_b32 v54, a32
	v_accvgpr_read_b32 v55, a33
	v_accvgpr_read_b32 v56, a34
	v_accvgpr_read_b32 v57, a35
	v_accvgpr_read_b32 v58, a36
	v_accvgpr_read_b32 v59, a37
	v_accvgpr_read_b32 v60, a38
	v_accvgpr_read_b32 v61, a39
	v_accvgpr_read_b32 v62, a40
	v_accvgpr_read_b32 v63, a41
	v_accvgpr_read_b32 v64, a42
	v_accvgpr_read_b32 v65, a43
	v_accvgpr_read_b32 v66, a44
	v_accvgpr_read_b32 v67, a45
	v_accvgpr_read_b32 v68, a46
	v_accvgpr_read_b32 v69, a47
	s_lshl_b32 s10, s5, 12
	s_lshr_b32 s10, s10, 1
	s_add_u32 s36, s54, s10
	s_addc_u32 s37, s55, 0
	s_cmp_lt_u32 s7, 0x800
	s_cselect_b64 s[60:61], s[48:49], s[50:51]
	s_lshl_b32 s10, s7, 12
	s_add_u32 s60, s60, s10
	s_addc_u32 s61, s61, 0
	global_load_dwordx4 a[32:35], v150, s[60:61] offset:0 nt
	global_load_dwordx4 a[36:39], v150, s[60:61] offset:1024 nt
	global_load_dwordx4 a[40:43], v150, s[60:61] offset:2048 nt
	global_load_dwordx4 a[44:47], v150, s[60:61] offset:3072 nt
	s_add_u32 s7, s7, 1
	v_mul_f32_e32 v152, v54, v54
	v_mul_f32_e32 v153, v55, v55
	v_fmac_f32_e32 v152, v56, v56
	v_fmac_f32_e32 v153, v57, v57
	v_fmac_f32_e32 v152, v58, v58
	v_fmac_f32_e32 v153, v59, v59
	v_fmac_f32_e32 v152, v60, v60
	v_fmac_f32_e32 v153, v61, v61
	v_fmac_f32_e32 v152, v62, v62
	v_fmac_f32_e32 v153, v63, v63
	v_fmac_f32_e32 v152, v64, v64
	v_fmac_f32_e32 v153, v65, v65
	v_fmac_f32_e32 v152, v66, v66
	v_fmac_f32_e32 v153, v67, v67
	v_fmac_f32_e32 v152, v68, v68
	v_fmac_f32_e32 v153, v69, v69
	v_add_f32_e32 v152, v152, v153
	s_nop 1
	v_add_f32_dpp v152, v152, v152 row_ror:8 row_mask:0xf bank_mask:0xf
	s_nop 1
	v_add_f32_dpp v152, v152, v152 row_ror:4 row_mask:0xf bank_mask:0xf
	s_nop 1
	v_add_f32_dpp v152, v152, v152 row_ror:2 row_mask:0xf bank_mask:0xf
	s_nop 1
	v_add_f32_dpp v152, v152, v152 row_ror:1 row_mask:0xf bank_mask:0xf
	s_nop 1
	v_readlane_b32 s22, v152, 0
	v_readlane_b32 s23, v152, 16
	v_readlane_b32 s32, v152, 32
	v_readlane_b32 s99, v152, 48
	v_mov_b32_e32 v152, s22
	v_add_f32_e32 v152, s23, v152
	v_add_f32_e32 v152, s32, v152
	v_add_f32_e32 v152, s99, v152
	v_mov_b32_e32 v153, 0x358637bd
	v_fmamk_f32 v152, v152, 0x3a800000, v153
	v_rsq_f32_e32 v152, v152
	s_nop 1
	v_mul_f32_e32 v54, v54, v152
	v_mul_f32_e32 v55, v55, v152
	v_mul_f32_e32 v56, v56, v152
	v_mul_f32_e32 v57, v57, v152
	v_mul_f32_e32 v58, v58, v152
	v_mul_f32_e32 v59, v59, v152
	v_mul_f32_e32 v60, v60, v152
	v_mul_f32_e32 v61, v61, v152
	v_mul_f32_e32 v62, v62, v152
	v_mul_f32_e32 v63, v63, v152
	v_mul_f32_e32 v64, v64, v152
	v_mul_f32_e32 v65, v65, v152
	v_mul_f32_e32 v66, v66, v152
	v_mul_f32_e32 v67, v67, v152
	v_mul_f32_e32 v68, v68, v152
	v_mul_f32_e32 v69, v69, v152
	v_fma_f32 v54, v54, v0, v16
	v_fma_f32 v55, v55, v1, v17
	v_fma_f32 v56, v56, v2, v18
	v_fma_f32 v57, v57, v3, v19
	v_fma_f32 v58, v58, v4, v20
	v_fma_f32 v59, v59, v5, v21
	v_fma_f32 v60, v60, v6, v22
	v_fma_f32 v61, v61, v7, v23
	v_fma_f32 v62, v62, v8, v24
	v_fma_f32 v63, v63, v9, v25
	v_fma_f32 v64, v64, v10, v26
	v_fma_f32 v65, v65, v11, v27
	v_fma_f32 v66, v66, v12, v28
	v_fma_f32 v67, v67, v13, v29
	v_fma_f32 v68, v68, v14, v30
	v_fma_f32 v69, v69, v15, v31
	v_cvt_pk_f16_f32 v70, v54, v55
	v_cvt_pk_f16_f32 v71, v56, v57
	v_cvt_pk_f16_f32 v72, v58, v59
	v_cvt_pk_f16_f32 v73, v60, v61
	v_cvt_pk_f16_f32 v74, v62, v63
	v_cvt_pk_f16_f32 v75, v64, v65
	v_cvt_pk_f16_f32 v76, v66, v67
	v_cvt_pk_f16_f32 v77, v68, v69
	global_store_dwordx2 v151, v[70:71], s[36:37] offset:0 nt
	global_store_dwordx2 v151, v[72:73], s[36:37] offset:512 nt
	global_store_dwordx2 v151, v[74:75], s[36:37] offset:1024 nt
	global_store_dwordx2 v151, v[76:77], s[36:37] offset:1536 nt
	s_add_u32 s5, s5, 1
	s_sub_u32 s9, s5, 0x800
	s_lshr_b32 s9, s9, 13
	s_cmp_lt_u32 s5, 0x800
	s_cselect_b32 s9, 8, s9
	s_cmp_eq_u32 s9, s8
	s_cbranch_scc1 .Lr1a_nr3
	s_mov_b32 s8, s9
	s_waitcnt vmcnt(0)
	s_add_u32 s10, s9, 0
	s_mul_i32 s10, s10, 0x6000
	s_add_u32 s38, s56, s10
	s_addc_u32 s39, s57, 0
	global_load_dwordx4 v[54:57], v150, s[58:59] offset:0
	global_load_dwordx4 v[58:61], v150, s[58:59] offset:1024
	global_load_dwordx4 v[62:65], v150, s[58:59] offset:2048
	global_load_dwordx4 v[66:69], v150, s[58:59] offset:3072
	s_add_u32 s44, s38, 0x1000
	s_addc_u32 s45, s39, 0
	global_load_dwordx4 v[70:73], v150, s[44:45] offset:0
	global_load_dwordx4 v[74:77], v150, s[44:45] offset:1024
	global_load_dwordx4 v[78:81], v150, s[44:45] offset:2048
	global_load_dwordx4 v[82:85], v150, s[44:45] offset:3072
	global_load_dwordx4 v[16:19], v150, s[38:39] offset:0
	global_load_dwordx4 v[20:23], v150, s[38:39] offset:1024
	global_load_dwordx4 v[24:27], v150, s[38:39] offset:2048
	global_load_dwordx4 v[28:31], v150, s[38:39] offset:3072
	s_waitcnt vmcnt(0)
	v_add_f32_e32 v70, 1.0, v70
	v_add_f32_e32 v71, 1.0, v71
	v_add_f32_e32 v72, 1.0, v72
	v_add_f32_e32 v73, 1.0, v73
	v_add_f32_e32 v74, 1.0, v74
	v_add_f32_e32 v75, 1.0, v75
	v_add_f32_e32 v76, 1.0, v76
	v_add_f32_e32 v77, 1.0, v77
	v_add_f32_e32 v78, 1.0, v78
	v_add_f32_e32 v79, 1.0, v79
	v_add_f32_e32 v80, 1.0, v80
	v_add_f32_e32 v81, 1.0, v81
	v_add_f32_e32 v82, 1.0, v82
	v_add_f32_e32 v83, 1.0, v83
	v_add_f32_e32 v84, 1.0, v84
	v_add_f32_e32 v85, 1.0, v85
	v_mul_f32_e32 v0, v54, v70
	v_mul_f32_e32 v1, v55, v71
	v_mul_f32_e32 v2, v56, v72
	v_mul_f32_e32 v3, v57, v73
	v_mul_f32_e32 v4, v58, v74
	v_mul_f32_e32 v5, v59, v75
	v_mul_f32_e32 v6, v60, v76
	v_mul_f32_e32 v7, v61, v77
	v_mul_f32_e32 v8, v62, v78
	v_mul_f32_e32 v9, v63, v79
	v_mul_f32_e32 v10, v64, v80
	v_mul_f32_e32 v11, v65, v81
	v_mul_f32_e32 v12, v66, v82
	v_mul_f32_e32 v13, v67, v83
	v_mul_f32_e32 v14, v68, v84
	v_mul_f32_e32 v15, v69, v85
; DI void row1_phase(const Params& P, int combine_l, int norm_l, int r_begin) {
;     ...
;     if (combine_l < 0) {
;       const float* src = r < TC ? P.ctx + (size_t)r * D : P.x + (size_t)(r - TC) * D;
; #pragma unroll
;       for (int i = 0; i < 4; i++) xv[i] = *(const float4*)(src + i * 256 + lane * 4);
;     ...
;     if (norm_l >= 0) {
;       float ss = 0.f;
; #pragma unroll
;       for (int i = 0; i < 4; i++) ss += xv[i].x * xv[i].x + xv[i].y * xv[i].y + xv[i].z * xv[i].z + xv[i].w * xv[i].w;
;       ss = wave_sum(ss);
;       const float rstd = rsqrtf(ss * (1.f / 1024.f) + EPS);
;       const float* g = P.norm1_g + norm_l * 1024;
;       const float* sh = P.mod + (size_t)(norm_l * 9 + n) * 6144; const float* sc = sh + 1024;
; #pragma unroll
;       for (int i = 0; i < 4; i++) {
;         int c = i * 256 + lane * 4;
;         float4 gg = *(const float4*)(g + c), s1 = *(const float4*)(sc + c), s0 = *(const float4*)(sh + c);
;         h4 o;
;         o[0] = (half_t)(xv[i].x * rstd * gg.x * (1.f + s1.x) + s0.x); o[1] = (half_t)(xv[i].y * rstd * gg.y * (1.f + s1.y) + s0.y);
;         o[2] = (half_t)(xv[i].z * rstd * gg.z * (1.f + s1.z) + s0.z); o[3] = (half_t)(xv[i].w * rstd * gg.w * (1.f + s1.w) + s0.w);
;         *(h4*)(P.hx + (size_t)r * D + c) = o;
;       }
.Lr1a_nr3:
	s_waitcnt vmcnt(16)
	v_accvgpr_read_b32 v54, a64
	v_accvgpr_read_b32 v55, a65
	v_accvgpr_read_b32 v56, a66
	v_accvgpr_read_b32 v57, a67
	v_accvgpr_read_b32 v58, a68
	v_accvgpr_read_b32 v59, a69
	v_accvgpr_read_b32 v60, a70
	v_accvgpr_read_b32 v61, a71
	v_accvgpr_read_b32 v62, a72
	v_accvgpr_read_b32 v63, a73
	v_accvgpr_read_b32 v64, a74
	v_accvgpr_read_b32 v65, a75
	v_accvgpr_read_b32 v66, a76
	v_accvgpr_read_b32 v67, a77
	v_accvgpr_read_b32 v68, a78
	v_accvgpr_read_b32 v69, a79
	s_lshl_b32 s10, s5, 12
	s_lshr_b32 s10, s10, 1
	s_add_u32 s36, s54, s10
	s_addc_u32 s37, s55, 0
	s_cmp_lt_u32 s7, 0x800
	s_cselect_b64 s[60:61], s[48:49], s[50:51]
	s_lshl_b32 s10, s7, 12
	s_add_u32 s60, s60, s10
	s_addc_u32 s61, s61, 0
	global_load_dwordx4 a[64:67], v150, s[60:61] offset:0 nt
	global_load_dwordx4 a[68:71], v150, s[60:61] offset:1024 nt
	global_load_dwordx4 a[72:75], v150, s[60:61] offset:2048 nt
	global_load_dwordx4 a[76:79], v150, s[60:61] offset:3072 nt
	s_add_u32 s7, s7, 1
	v_mul_f32_e32 v152, v54, v54
	v_mul_f32_e32 v153, v55, v55
	v_fmac_f32_e32 v152, v56, v56
	v_fmac_f32_e32 v153, v57, v57
	v_fmac_f32_e32 v152, v58, v58
	v_fmac_f32_e32 v153, v59, v59
	v_fmac_f32_e32 v152, v60, v60
	v_fmac_f32_e32 v153, v61, v61
	v_fmac_f32_e32 v152, v62, v62
	v_fmac_f32_e32 v153, v63, v63
	v_fmac_f32_e32 v152, v64, v64
	v_fmac_f32_e32 v153, v65, v65
	v_fmac_f32_e32 v152, v66, v66
	v_fmac_f32_e32 v153, v67, v67
	v_fmac_f32_e32 v152, v68, v68
	v_fmac_f32_e32 v153, v69, v69
	v_add_f32_e32 v152, v152, v153
	s_nop 1
	v_add_f32_dpp v152, v152, v152 row_ror:8 row_mask:0xf bank_mask:0xf
	s_nop 1
	v_add_f32_dpp v152, v152, v152 row_ror:4 row_mask:0xf bank_mask:0xf
	s_nop 1
	v_add_f32_dpp v152, v152, v152 row_ror:2 row_mask:0xf bank_mask:0xf
	s_nop 1
	v_add_f32_dpp v152, v152, v152 row_ror:1 row_mask:0xf bank_mask:0xf
	s_nop 1
	v_readlane_b32 s22, v152, 0
	v_readlane_b32 s23, v152, 16
	v_readlane_b32 s32, v152, 32
	v_readlane_b32 s99, v152, 48
	v_mov_b32_e32 v152, s22
	v_add_f32_e32 v152, s23, v152
	v_add_f32_e32 v152, s32, v152
	v_add_f32_e32 v152, s99, v152
	v_mov_b32_e32 v153, 0x358637bd
	v_fmamk_f32 v152, v152, 0x3a800000, v153
	v_rsq_f32_e32 v152, v152
	s_nop 1
	v_mul_f32_e32 v54, v54, v152
	v_mul_f32_e32 v55, v55, v152
	v_mul_f32_e32 v56, v56, v152
	v_mul_f32_e32 v57, v57, v152
	v_mul_f32_e32 v58, v58, v152
	v_mul_f32_e32 v59, v59, v152
	v_mul_f32_e32 v60, v60, v152
	v_mul_f32_e32 v61, v61, v152
	v_mul_f32_e32 v62, v62, v152
	v_mul_f32_e32 v63, v63, v152
	v_mul_f32_e32 v64, v64, v152
	v_mul_f32_e32 v65, v65, v152
	v_mul_f32_e32 v66, v66, v152
	v_mul_f32_e32 v67, v67, v152
	v_mul_f32_e32 v68, v68, v152
	v_mul_f32_e32 v69, v69, v152
	v_fma_f32 v54, v54, v0, v16
	v_fma_f32 v55, v55, v1, v17
	v_fma_f32 v56, v56, v2, v18
	v_fma_f32 v57, v57, v3, v19
	v_fma_f32 v58, v58, v4, v20
	v_fma_f32 v59, v59, v5, v21
	v_fma_f32 v60, v60, v6, v22
	v_fma_f32 v61, v61, v7, v23
	v_fma_f32 v62, v62, v8, v24
	v_fma_f32 v63, v63, v9, v25
	v_fma_f32 v64, v64, v10, v26
	v_fma_f32 v65, v65, v11, v27
	v_fma_f32 v66, v66, v12, v28
	v_fma_f32 v67, v67, v13, v29
	v_fma_f32 v68, v68, v14, v30
	v_fma_f32 v69, v69, v15, v31
	v_cvt_pk_f16_f32 v70, v54, v55
	v_cvt_pk_f16_f32 v71, v56, v57
	v_cvt_pk_f16_f32 v72, v58, v59
	v_cvt_pk_f16_f32 v73, v60, v61
	v_cvt_pk_f16_f32 v74, v62, v63
	v_cvt_pk_f16_f32 v75, v64, v65
	v_cvt_pk_f16_f32 v76, v66, v67
	v_cvt_pk_f16_f32 v77, v68, v69
	global_store_dwordx2 v151, v[70:71], s[36:37] offset:0 nt
	global_store_dwordx2 v151, v[72:73], s[36:37] offset:512 nt
	global_store_dwordx2 v151, v[74:75], s[36:37] offset:1024 nt
	global_store_dwordx2 v151, v[76:77], s[36:37] offset:1536 nt
	s_add_u32 s5, s5, 1
	s_sub_u32 s9, s5, 0x800
	s_lshr_b32 s9, s9, 13
	s_cmp_lt_u32 s5, 0x800
	s_cselect_b32 s9, 8, s9
	s_cmp_eq_u32 s9, s8
	s_cbranch_scc1 .Lr1a_nr4
	s_mov_b32 s8, s9
	s_waitcnt vmcnt(0)
	s_add_u32 s10, s9, 0
	s_mul_i32 s10, s10, 0x6000
	s_add_u32 s38, s56, s10
	s_addc_u32 s39, s57, 0
	global_load_dwordx4 v[54:57], v150, s[58:59] offset:0
	global_load_dwordx4 v[58:61], v150, s[58:59] offset:1024
	global_load_dwordx4 v[62:65], v150, s[58:59] offset:2048
	global_load_dwordx4 v[66:69], v150, s[58:59] offset:3072
	s_add_u32 s44, s38, 0x1000
	s_addc_u32 s45, s39, 0
	global_load_dwordx4 v[70:73], v150, s[44:45] offset:0
	global_load_dwordx4 v[74:77], v150, s[44:45] offset:1024
	global_load_dwordx4 v[78:81], v150, s[44:45] offset:2048
	global_load_dwordx4 v[82:85], v150, s[44:45] offset:3072
	global_load_dwordx4 v[16:19], v150, s[38:39] offset:0
	global_load_dwordx4 v[20:23], v150, s[38:39] offset:1024
	global_load_dwordx4 v[24:27], v150, s[38:39] offset:2048
	global_load_dwordx4 v[28:31], v150, s[38:39] offset:3072
	s_waitcnt vmcnt(0)
	v_add_f32_e32 v70, 1.0, v70
	v_add_f32_e32 v71, 1.0, v71
	v_add_f32_e32 v72, 1.0, v72
	v_add_f32_e32 v73, 1.0, v73
	v_add_f32_e32 v74, 1.0, v74
	v_add_f32_e32 v75, 1.0, v75
	v_add_f32_e32 v76, 1.0, v76
	v_add_f32_e32 v77, 1.0, v77
	v_add_f32_e32 v78, 1.0, v78
	v_add_f32_e32 v79, 1.0, v79
	v_add_f32_e32 v80, 1.0, v80
	v_add_f32_e32 v81, 1.0, v81
	v_add_f32_e32 v82, 1.0, v82
	v_add_f32_e32 v83, 1.0, v83
	v_add_f32_e32 v84, 1.0, v84
	v_add_f32_e32 v85, 1.0, v85
	v_mul_f32_e32 v0, v54, v70
	v_mul_f32_e32 v1, v55, v71
	v_mul_f32_e32 v2, v56, v72
	v_mul_f32_e32 v3, v57, v73
	v_mul_f32_e32 v4, v58, v74
	v_mul_f32_e32 v5, v59, v75
	v_mul_f32_e32 v6, v60, v76
	v_mul_f32_e32 v7, v61, v77
	v_mul_f32_e32 v8, v62, v78
	v_mul_f32_e32 v9, v63, v79
	v_mul_f32_e32 v10, v64, v80
	v_mul_f32_e32 v11, v65, v81
	v_mul_f32_e32 v12, v66, v82
	v_mul_f32_e32 v13, v67, v83
	v_mul_f32_e32 v14, v68, v84
	v_mul_f32_e32 v15, v69, v85
; DI void row1_phase(const Params& P, int combine_l, int norm_l, int r_begin) {
;     ...
;     if (combine_l < 0) {
;       const float* src = r < TC ? P.ctx + (size_t)r * D : P.x + (size_t)(r - TC) * D;
; #pragma unroll
;       for (int i = 0; i < 4; i++) xv[i] = *(const float4*)(src + i * 256 + lane * 4);
;     ...
;     if (norm_l >= 0) {
;       float ss = 0.f;
; #pragma unroll
;       for (int i = 0; i < 4; i++) ss += xv[i].x * xv[i].x + xv[i].y * xv[i].y + xv[i].z * xv[i].z + xv[i].w * xv[i].w;
;       ss = wave_sum(ss);
;       const float rstd = rsqrtf(ss * (1.f / 1024.f) + EPS);
;       const float* g = P.norm1_g + norm_l * 1024;
;       const float* sh = P.mod + (size_t)(norm_l * 9 + n) * 6144; const float* sc = sh + 1024;
; #pragma unroll
;       for (int i = 0; i < 4; i++) {
;         int c = i * 256 + lane * 4;
;         float4 gg = *(const float4*)(g + c), s1 = *(const float4*)(sc + c), s0 = *(const float4*)(sh + c);
;         h4 o;
;         o[0] = (half_t)(xv[i].x * rstd * gg.x * (1.f + s1.x) + s0.x); o[1] = (half_t)(xv[i].y * rstd * gg.y * (1.f + s1.y) + s0.y);
;         o[2] = (half_t)(xv[i].z * rstd * gg.z * (1.f + s1.z) + s0.z); o[3] = (half_t)(xv[i].w * rstd * gg.w * (1.f + s1.w) + s0.w);
;         *(h4*)(P.hx + (size_t)r * D + c) = o;
;       }
.Lr1a_nr4:
	s_waitcnt vmcnt(16)
	v_accvgpr_read_b32 v54, a96
	v_accvgpr_read_b32 v55, a97
	v_accvgpr_read_b32 v56, a98
	v_accvgpr_read_b32 v57, a99
	v_accvgpr_read_b32 v58, a100
	v_accvgpr_read_b32 v59, a101
	v_accvgpr_read_b32 v60, a102
	v_accvgpr_read_b32 v61, a103
	v_accvgpr_read_b32 v62, a104
	v_accvgpr_read_b32 v63, a105
	v_accvgpr_read_b32 v64, a106
	v_accvgpr_read_b32 v65, a107
	v_accvgpr_read_b32 v66, a108
	v_accvgpr_read_b32 v67, a109
	v_accvgpr_read_b32 v68, a110
	v_accvgpr_read_b32 v69, a111
	s_lshl_b32 s10, s5, 12
	s_lshr_b32 s10, s10, 1
	s_add_u32 s36, s54, s10
	s_addc_u32 s37, s55, 0
	s_cmp_lt_u32 s7, 0x800
	s_cselect_b64 s[60:61], s[48:49], s[50:51]
	s_lshl_b32 s10, s7, 12
	s_add_u32 s60, s60, s10
	s_addc_u32 s61, s61, 0
	global_load_dwordx4 a[96:99], v150, s[60:61] offset:0 nt
	global_load_dwordx4 a[100:103], v150, s[60:61] offset:1024 nt
	global_load_dwordx4 a[104:107], v150, s[60:61] offset:2048 nt
	global_load_dwordx4 a[108:111], v150, s[60:61] offset:3072 nt
	s_add_u32 s7, s7, 1
	v_mul_f32_e32 v152, v54, v54
	v_mul_f32_e32 v153, v55, v55
	v_fmac_f32_e32 v152, v56, v56
	v_fmac_f32_e32 v153, v57, v57
	v_fmac_f32_e32 v152, v58, v58
	v_fmac_f32_e32 v153, v59, v59
	v_fmac_f32_e32 v152, v60, v60
	v_fmac_f32_e32 v153, v61, v61
	v_fmac_f32_e32 v152, v62, v62
	v_fmac_f32_e32 v153, v63, v63
	v_fmac_f32_e32 v152, v64, v64
	v_fmac_f32_e32 v153, v65, v65
	v_fmac_f32_e32 v152, v66, v66
	v_fmac_f32_e32 v153, v67, v67
	v_fmac_f32_e32 v152, v68, v68
	v_fmac_f32_e32 v153, v69, v69
	v_add_f32_e32 v152, v152, v153
	s_nop 1
	v_add_f32_dpp v152, v152, v152 row_ror:8 row_mask:0xf bank_mask:0xf
	s_nop 1
	v_add_f32_dpp v152, v152, v152 row_ror:4 row_mask:0xf bank_mask:0xf
	s_nop 1
	v_add_f32_dpp v152, v152, v152 row_ror:2 row_mask:0xf bank_mask:0xf
	s_nop 1
	v_add_f32_dpp v152, v152, v152 row_ror:1 row_mask:0xf bank_mask:0xf
	s_nop 1
	v_readlane_b32 s22, v152, 0
	v_readlane_b32 s23, v152, 16
	v_readlane_b32 s32, v152, 32
	v_readlane_b32 s99, v152, 48
	v_mov_b32_e32 v152, s22
	v_add_f32_e32 v152, s23, v152
	v_add_f32_e32 v152, s32, v152
	v_add_f32_e32 v152, s99, v152
	v_mov_b32_e32 v153, 0x358637bd
	v_fmamk_f32 v152, v152, 0x3a800000, v153
	v_rsq_f32_e32 v152, v152
	s_nop 1
	v_mul_f32_e32 v54, v54, v152
	v_mul_f32_e32 v55, v55, v152
	v_mul_f32_e32 v56, v56, v152
	v_mul_f32_e32 v57, v57, v152
	v_mul_f32_e32 v58, v58, v152
	v_mul_f32_e32 v59, v59, v152
	v_mul_f32_e32 v60, v60, v152
	v_mul_f32_e32 v61, v61, v152
	v_mul_f32_e32 v62, v62, v152
	v_mul_f32_e32 v63, v63, v152
	v_mul_f32_e32 v64, v64, v152
	v_mul_f32_e32 v65, v65, v152
	v_mul_f32_e32 v66, v66, v152
	v_mul_f32_e32 v67, v67, v152
	v_mul_f32_e32 v68, v68, v152
	v_mul_f32_e32 v69, v69, v152
	v_fma_f32 v54, v54, v0, v16
	v_fma_f32 v55, v55, v1, v17
	v_fma_f32 v56, v56, v2, v18
	v_fma_f32 v57, v57, v3, v19
	v_fma_f32 v58, v58, v4, v20
	v_fma_f32 v59, v59, v5, v21
	v_fma_f32 v60, v60, v6, v22
	v_fma_f32 v61, v61, v7, v23
	v_fma_f32 v62, v62, v8, v24
	v_fma_f32 v63, v63, v9, v25
	v_fma_f32 v64, v64, v10, v26
	v_fma_f32 v65, v65, v11, v27
	v_fma_f32 v66, v66, v12, v28
	v_fma_f32 v67, v67, v13, v29
	v_fma_f32 v68, v68, v14, v30
	v_fma_f32 v69, v69, v15, v31
	v_cvt_pk_f16_f32 v70, v54, v55
	v_cvt_pk_f16_f32 v71, v56, v57
	v_cvt_pk_f16_f32 v72, v58, v59
	v_cvt_pk_f16_f32 v73, v60, v61
	v_cvt_pk_f16_f32 v74, v62, v63
	v_cvt_pk_f16_f32 v75, v64, v65
	v_cvt_pk_f16_f32 v76, v66, v67
	v_cvt_pk_f16_f32 v77, v68, v69
	global_store_dwordx2 v151, v[70:71], s[36:37] offset:0 nt
	global_store_dwordx2 v151, v[72:73], s[36:37] offset:512 nt
	global_store_dwordx2 v151, v[74:75], s[36:37] offset:1024 nt
	global_store_dwordx2 v151, v[76:77], s[36:37] offset:1536 nt
	s_add_u32 s5, s5, 1
	s_sub_u32 s98, s98, 1
	s_cmp_lg_u32 s98, 0
	s_cbranch_scc1 .Lr1a_loop
	s_sub_u32 s9, s5, 0x800
	s_lshr_b32 s9, s9, 13
	s_cmp_lt_u32 s5, 0x800
	s_cselect_b32 s9, 8, s9
	s_cmp_eq_u32 s9, s8
	s_cbranch_scc1 .Lr1a_nr5
	s_mov_b32 s8, s9
	s_waitcnt vmcnt(0)
	s_add_u32 s10, s9, 0
	s_mul_i32 s10, s10, 0x6000
	s_add_u32 s38, s56, s10
	s_addc_u32 s39, s57, 0
	global_load_dwordx4 v[54:57], v150, s[58:59] offset:0
	global_load_dwordx4 v[58:61], v150, s[58:59] offset:1024
	global_load_dwordx4 v[62:65], v150, s[58:59] offset:2048
	global_load_dwordx4 v[66:69], v150, s[58:59] offset:3072
	s_add_u32 s44, s38, 0x1000
	s_addc_u32 s45, s39, 0
	global_load_dwordx4 v[70:73], v150, s[44:45] offset:0
	global_load_dwordx4 v[74:77], v150, s[44:45] offset:1024
	global_load_dwordx4 v[78:81], v150, s[44:45] offset:2048
	global_load_dwordx4 v[82:85], v150, s[44:45] offset:3072
	global_load_dwordx4 v[16:19], v150, s[38:39] offset:0
	global_load_dwordx4 v[20:23], v150, s[38:39] offset:1024
	global_load_dwordx4 v[24:27], v150, s[38:39] offset:2048
	global_load_dwordx4 v[28:31], v150, s[38:39] offset:3072
	s_waitcnt vmcnt(0)
	v_add_f32_e32 v70, 1.0, v70
	v_add_f32_e32 v71, 1.0, v71
	v_add_f32_e32 v72, 1.0, v72
	v_add_f32_e32 v73, 1.0, v73
	v_add_f32_e32 v74, 1.0, v74
	v_add_f32_e32 v75, 1.0, v75
	v_add_f32_e32 v76, 1.0, v76
	v_add_f32_e32 v77, 1.0, v77
	v_add_f32_e32 v78, 1.0, v78
	v_add_f32_e32 v79, 1.0, v79
	v_add_f32_e32 v80, 1.0, v80
	v_add_f32_e32 v81, 1.0, v81
	v_add_f32_e32 v82, 1.0, v82
	v_add_f32_e32 v83, 1.0, v83
	v_add_f32_e32 v84, 1.0, v84
	v_add_f32_e32 v85, 1.0, v85
	v_mul_f32_e32 v0, v54, v70
	v_mul_f32_e32 v1, v55, v71
	v_mul_f32_e32 v2, v56, v72
	v_mul_f32_e32 v3, v57, v73
	v_mul_f32_e32 v4, v58, v74
	v_mul_f32_e32 v5, v59, v75
	v_mul_f32_e32 v6, v60, v76
	v_mul_f32_e32 v7, v61, v77
	v_mul_f32_e32 v8, v62, v78
	v_mul_f32_e32 v9, v63, v79
	v_mul_f32_e32 v10, v64, v80
	v_mul_f32_e32 v11, v65, v81
	v_mul_f32_e32 v12, v66, v82
	v_mul_f32_e32 v13, v67, v83
	v_mul_f32_e32 v14, v68, v84
	v_mul_f32_e32 v15, v69, v85

; DI void row1_phase(const Params& P, int combine_l, int norm_l, int r_begin) {
;     ...
;     if (norm_l >= 0) {
;       float ss = 0.f;
; #pragma unroll
;       for (int i = 0; i < 4; i++) ss += xv[i].x * xv[i].x + xv[i].y * xv[i].y + xv[i].z * xv[i].z + xv[i].w * xv[i].w;
;       ss = wave_sum(ss);
;       const float rstd = rsqrtf(ss * (1.f / 1024.f) + EPS);
;       const float* g = P.norm1_g + norm_l * 1024;
;       const float* sh = P.mod + (size_t)(norm_l * 9 + n) * 6144; const float* sc = sh + 1024;
; #pragma unroll
;       for (int i = 0; i < 4; i++) {
;         int c = i * 256 + lane * 4;
;         float4 gg = *(const float4*)(g + c), s1 = *(const float4*)(sc + c), s0 = *(const float4*)(sh + c);
;         h4 o;
;         o[0] = (half_t)(xv[i].x * rstd * gg.x * (1.f + s1.x) + s0.x); o[1] = (half_t)(xv[i].y * rstd * gg.y * (1.f + s1.y) + s0.y);
;         o[2] = (half_t)(xv[i].z * rstd * gg.z * (1.f + s1.z) + s0.z); o[3] = (half_t)(xv[i].w * rstd * gg.w * (1.f + s1.w) + s0.w);
;         *(h4*)(P.hx + (size_t)r * D + c) = o;
;       }
;     }
.Lr1a_nr7:
	s_waitcnt vmcnt(16)
	v_accvgpr_read_b32 v54, a64
	v_accvgpr_read_b32 v55, a65
	v_accvgpr_read_b32 v56, a66
	v_accvgpr_read_b32 v57, a67
	v_accvgpr_read_b32 v58, a68
	v_accvgpr_read_b32 v59, a69
	v_accvgpr_read_b32 v60, a70
	v_accvgpr_read_b32 v61, a71
	v_accvgpr_read_b32 v62, a72
	v_accvgpr_read_b32 v63, a73
	v_accvgpr_read_b32 v64, a74
	v_accvgpr_read_b32 v65, a75
	v_accvgpr_read_b32 v66, a76
	v_accvgpr_read_b32 v67, a77
	v_accvgpr_read_b32 v68, a78
	v_accvgpr_read_b32 v69, a79
	s_lshl_b32 s10, s5, 12
	s_lshr_b32 s10, s10, 1
	s_add_u32 s36, s54, s10
	s_addc_u32 s37, s55, 0
	v_mul_f32_e32 v152, v54, v54
	v_mul_f32_e32 v153, v55, v55
	v_fmac_f32_e32 v152, v56, v56
	v_fmac_f32_e32 v153, v57, v57
	v_fmac_f32_e32 v152, v58, v58
	v_fmac_f32_e32 v153, v59, v59
	v_fmac_f32_e32 v152, v60, v60
	v_fmac_f32_e32 v153, v61, v61
	v_fmac_f32_e32 v152, v62, v62
	v_fmac_f32_e32 v153, v63, v63
	v_fmac_f32_e32 v152, v64, v64
	v_fmac_f32_e32 v153, v65, v65
	v_fmac_f32_e32 v152, v66, v66
	v_fmac_f32_e32 v153, v67, v67
	v_fmac_f32_e32 v152, v68, v68
	v_fmac_f32_e32 v153, v69, v69
	v_add_f32_e32 v152, v152, v153
	s_nop 1
	v_add_f32_dpp v152, v152, v152 row_ror:8 row_mask:0xf bank_mask:0xf
	s_nop 1
	v_add_f32_dpp v152, v152, v152 row_ror:4 row_mask:0xf bank_mask:0xf
	s_nop 1
	v_add_f32_dpp v152, v152, v152 row_ror:2 row_mask:0xf bank_mask:0xf
	s_nop 1
	v_add_f32_dpp v152, v152, v152 row_ror:1 row_mask:0xf bank_mask:0xf
	s_nop 1
	v_readlane_b32 s22, v152, 0
	v_readlane_b32 s23, v152, 16
	v_readlane_b32 s32, v152, 32
	v_readlane_b32 s99, v152, 48
	v_mov_b32_e32 v152, s22
	v_add_f32_e32 v152, s23, v152
	v_add_f32_e32 v152, s32, v152
	v_add_f32_e32 v152, s99, v152
	v_mov_b32_e32 v153, 0x358637bd
	v_fmamk_f32 v152, v152, 0x3a800000, v153
	v_rsq_f32_e32 v152, v152
	s_nop 1
	v_mul_f32_e32 v54, v54, v152
	v_mul_f32_e32 v55, v55, v152
	v_mul_f32_e32 v56, v56, v152
	v_mul_f32_e32 v57, v57, v152
	v_mul_f32_e32 v58, v58, v152
	v_mul_f32_e32 v59, v59, v152
	v_mul_f32_e32 v60, v60, v152
	v_mul_f32_e32 v61, v61, v152
	v_mul_f32_e32 v62, v62, v152
	v_mul_f32_e32 v63, v63, v152
	v_mul_f32_e32 v64, v64, v152
	v_mul_f32_e32 v65, v65, v152
	v_mul_f32_e32 v66, v66, v152
	v_mul_f32_e32 v67, v67, v152
	v_mul_f32_e32 v68, v68, v152
	v_mul_f32_e32 v69, v69, v152
	v_fma_f32 v54, v54, v0, v16
	v_fma_f32 v55, v55, v1, v17
	v_fma_f32 v56, v56, v2, v18
	v_fma_f32 v57, v57, v3, v19
	v_fma_f32 v58, v58, v4, v20
	v_fma_f32 v59, v59, v5, v21
	v_fma_f32 v60, v60, v6, v22
	v_fma_f32 v61, v61, v7, v23
	v_fma_f32 v62, v62, v8, v24
	v_fma_f32 v63, v63, v9, v25
	v_fma_f32 v64, v64, v10, v26
	v_fma_f32 v65, v65, v11, v27
	v_fma_f32 v66, v66, v12, v28
	v_fma_f32 v67, v67, v13, v29
	v_fma_f32 v68, v68, v14, v30
	v_fma_f32 v69, v69, v15, v31
	v_cvt_pk_f16_f32 v70, v54, v55
	v_cvt_pk_f16_f32 v71, v56, v57
	v_cvt_pk_f16_f32 v72, v58, v59
	v_cvt_pk_f16_f32 v73, v60, v61
	v_cvt_pk_f16_f32 v74, v62, v63
	v_cvt_pk_f16_f32 v75, v64, v65
	v_cvt_pk_f16_f32 v76, v66, v67
	v_cvt_pk_f16_f32 v77, v68, v69
	global_store_dwordx2 v151, v[70:71], s[36:37] offset:0 nt
	global_store_dwordx2 v151, v[72:73], s[36:37] offset:512 nt
	global_store_dwordx2 v151, v[74:75], s[36:37] offset:1024 nt
	global_store_dwordx2 v151, v[76:77], s[36:37] offset:1536 nt
	s_add_u32 s5, s5, 1
	s_sub_u32 s9, s5, 0x800
	s_lshr_b32 s9, s9, 13
	s_cmp_lt_u32 s5, 0x800
	s_cselect_b32 s9, 8, s9
	s_cmp_eq_u32 s9, s8
	s_cbranch_scc1 .Lr1a_nr8
	s_mov_b32 s8, s9
	s_waitcnt vmcnt(0)
	s_add_u32 s10, s9, 0
	s_mul_i32 s10, s10, 0x6000
	s_add_u32 s38, s56, s10
	s_addc_u32 s39, s57, 0
	global_load_dwordx4 v[54:57], v150, s[58:59] offset:0
	global_load_dwordx4 v[58:61], v150, s[58:59] offset:1024
	global_load_dwordx4 v[62:65], v150, s[58:59] offset:2048
	global_load_dwordx4 v[66:69], v150, s[58:59] offset:3072
	s_add_u32 s44, s38, 0x1000
	s_addc_u32 s45, s39, 0
	global_load_dwordx4 v[70:73], v150, s[44:45] offset:0
	global_load_dwordx4 v[74:77], v150, s[44:45] offset:1024
	global_load_dwordx4 v[78:81], v150, s[44:45] offset:2048
	global_load_dwordx4 v[82:85], v150, s[44:45] offset:3072
	global_load_dwordx4 v[16:19], v150, s[38:39] offset:0
	global_load_dwordx4 v[20:23], v150, s[38:39] offset:1024
	global_load_dwordx4 v[24:27], v150, s[38:39] offset:2048
	global_load_dwordx4 v[28:31], v150, s[38:39] offset:3072
	s_waitcnt vmcnt(0)
	v_add_f32_e32 v70, 1.0, v70
	v_add_f32_e32 v71, 1.0, v71
	v_add_f32_e32 v72, 1.0, v72
	v_add_f32_e32 v73, 1.0, v73
	v_add_f32_e32 v74, 1.0, v74
	v_add_f32_e32 v75, 1.0, v75
	v_add_f32_e32 v76, 1.0, v76
	v_add_f32_e32 v77, 1.0, v77
	v_add_f32_e32 v78, 1.0, v78
	v_add_f32_e32 v79, 1.0, v79
	v_add_f32_e32 v80, 1.0, v80
	v_add_f32_e32 v81, 1.0, v81
	v_add_f32_e32 v82, 1.0, v82
	v_add_f32_e32 v83, 1.0, v83
	v_add_f32_e32 v84, 1.0, v84
	v_add_f32_e32 v85, 1.0, v85
	v_mul_f32_e32 v0, v54, v70
	v_mul_f32_e32 v1, v55, v71
	v_mul_f32_e32 v2, v56, v72
	v_mul_f32_e32 v3, v57, v73
	v_mul_f32_e32 v4, v58, v74
	v_mul_f32_e32 v5, v59, v75
	v_mul_f32_e32 v6, v60, v76
	v_mul_f32_e32 v7, v61, v77
	v_mul_f32_e32 v8, v62, v78
	v_mul_f32_e32 v9, v63, v79
	v_mul_f32_e32 v10, v64, v80
	v_mul_f32_e32 v11, v65, v81
	v_mul_f32_e32 v12, v66, v82
	v_mul_f32_e32 v13, v67, v83
	v_mul_f32_e32 v14, v68, v84
	v_mul_f32_e32 v15, v69, v85
; DI void row1_phase(const Params& P, int combine_l, int norm_l, int r_begin) {
;     ...
;     if (norm_l >= 0) {
;       float ss = 0.f;
; #pragma unroll
;       for (int i = 0; i < 4; i++) ss += xv[i].x * xv[i].x + xv[i].y * xv[i].y + xv[i].z * xv[i].z + xv[i].w * xv[i].w;
;       ss = wave_sum(ss);
;       const float rstd = rsqrtf(ss * (1.f / 1024.f) + EPS);
;       const float* g = P.norm1_g + norm_l * 1024;
;       const float* sh = P.mod + (size_t)(norm_l * 9 + n) * 6144; const float* sc = sh + 1024;
; #pragma unroll
;       for (int i = 0; i < 4; i++) {
;         int c = i * 256 + lane * 4;
;         float4 gg = *(const float4*)(g + c), s1 = *(const float4*)(sc + c), s0 = *(const float4*)(sh + c);
;         h4 o;
;         o[0] = (half_t)(xv[i].x * rstd * gg.x * (1.f + s1.x) + s0.x); o[1] = (half_t)(xv[i].y * rstd * gg.y * (1.f + s1.y) + s0.y);
;         o[2] = (half_t)(xv[i].z * rstd * gg.z * (1.f + s1.z) + s0.z); o[3] = (half_t)(xv[i].w * rstd * gg.w * (1.f + s1.w) + s0.w);
;         *(h4*)(P.hx + (size_t)r * D + c) = o;
;       }
;     }
.Lr1a_nr8:
	s_waitcnt vmcnt(12)
	v_accvgpr_read_b32 v54, a96
	v_accvgpr_read_b32 v55, a97
	v_accvgpr_read_b32 v56, a98
	v_accvgpr_read_b32 v57, a99
	v_accvgpr_read_b32 v58, a100
	v_accvgpr_read_b32 v59, a101
	v_accvgpr_read_b32 v60, a102
	v_accvgpr_read_b32 v61, a103
	v_accvgpr_read_b32 v62, a104
	v_accvgpr_read_b32 v63, a105
	v_accvgpr_read_b32 v64, a106
	v_accvgpr_read_b32 v65, a107
	v_accvgpr_read_b32 v66, a108
	v_accvgpr_read_b32 v67, a109
	v_accvgpr_read_b32 v68, a110
	v_accvgpr_read_b32 v69, a111
	s_lshl_b32 s10, s5, 12
	s_lshr_b32 s10, s10, 1
	s_add_u32 s36, s54, s10
	s_addc_u32 s37, s55, 0
	v_mul_f32_e32 v152, v54, v54
	v_mul_f32_e32 v153, v55, v55
	v_fmac_f32_e32 v152, v56, v56
	v_fmac_f32_e32 v153, v57, v57
	v_fmac_f32_e32 v152, v58, v58
	v_fmac_f32_e32 v153, v59, v59
	v_fmac_f32_e32 v152, v60, v60
	v_fmac_f32_e32 v153, v61, v61
	v_fmac_f32_e32 v152, v62, v62
	v_fmac_f32_e32 v153, v63, v63
	v_fmac_f32_e32 v152, v64, v64
	v_fmac_f32_e32 v153, v65, v65
	v_fmac_f32_e32 v152, v66, v66
	v_fmac_f32_e32 v153, v67, v67
	v_fmac_f32_e32 v152, v68, v68
	v_fmac_f32_e32 v153, v69, v69
	v_add_f32_e32 v152, v152, v153
	s_nop 1
	v_add_f32_dpp v152, v152, v152 row_ror:8 row_mask:0xf bank_mask:0xf
	s_nop 1
	v_add_f32_dpp v152, v152, v152 row_ror:4 row_mask:0xf bank_mask:0xf
	s_nop 1
	v_add_f32_dpp v152, v152, v152 row_ror:2 row_mask:0xf bank_mask:0xf
	s_nop 1
	v_add_f32_dpp v152, v152, v152 row_ror:1 row_mask:0xf bank_mask:0xf
	s_nop 1
	v_readlane_b32 s22, v152, 0
	v_readlane_b32 s23, v152, 16
	v_readlane_b32 s32, v152, 32
	v_readlane_b32 s99, v152, 48
	v_mov_b32_e32 v152, s22
	v_add_f32_e32 v152, s23, v152
	v_add_f32_e32 v152, s32, v152
	v_add_f32_e32 v152, s99, v152
	v_mov_b32_e32 v153, 0x358637bd
	v_fmamk_f32 v152, v152, 0x3a800000, v153
	v_rsq_f32_e32 v152, v152
	s_nop 1
	v_mul_f32_e32 v54, v54, v152
	v_mul_f32_e32 v55, v55, v152
	v_mul_f32_e32 v56, v56, v152
	v_mul_f32_e32 v57, v57, v152
	v_mul_f32_e32 v58, v58, v152
	v_mul_f32_e32 v59, v59, v152
	v_mul_f32_e32 v60, v60, v152
	v_mul_f32_e32 v61, v61, v152
	v_mul_f32_e32 v62, v62, v152
	v_mul_f32_e32 v63, v63, v152
	v_mul_f32_e32 v64, v64, v152
	v_mul_f32_e32 v65, v65, v152
	v_mul_f32_e32 v66, v66, v152
	v_mul_f32_e32 v67, v67, v152
	v_mul_f32_e32 v68, v68, v152
	v_mul_f32_e32 v69, v69, v152
	v_fma_f32 v54, v54, v0, v16
	v_fma_f32 v55, v55, v1, v17
	v_fma_f32 v56, v56, v2, v18
	v_fma_f32 v57, v57, v3, v19
	v_fma_f32 v58, v58, v4, v20
	v_fma_f32 v59, v59, v5, v21
	v_fma_f32 v60, v60, v6, v22
	v_fma_f32 v61, v61, v7, v23
	v_fma_f32 v62, v62, v8, v24
	v_fma_f32 v63, v63, v9, v25
	v_fma_f32 v64, v64, v10, v26
	v_fma_f32 v65, v65, v11, v27
	v_fma_f32 v66, v66, v12, v28
	v_fma_f32 v67, v67, v13, v29
	v_fma_f32 v68, v68, v14, v30
	v_fma_f32 v69, v69, v15, v31
	v_cvt_pk_f16_f32 v70, v54, v55
	v_cvt_pk_f16_f32 v71, v56, v57
	v_cvt_pk_f16_f32 v72, v58, v59
	v_cvt_pk_f16_f32 v73, v60, v61
	v_cvt_pk_f16_f32 v74, v62, v63
	v_cvt_pk_f16_f32 v75, v64, v65
	v_cvt_pk_f16_f32 v76, v66, v67
	v_cvt_pk_f16_f32 v77, v68, v69
	global_store_dwordx2 v151, v[70:71], s[36:37] offset:0 nt
	global_store_dwordx2 v151, v[72:73], s[36:37] offset:512 nt
	global_store_dwordx2 v151, v[74:75], s[36:37] offset:1024 nt
	global_store_dwordx2 v151, v[76:77], s[36:37] offset:1536 nt
	s_add_u32 s5, s5, 1
	s_sub_u32 s9, s5, 0x800
	s_lshr_b32 s9, s9, 13
	s_cmp_lt_u32 s5, 0x800
	s_cselect_b32 s9, 8, s9
	s_cmp_eq_u32 s9, s8
	s_cbranch_scc1 .Lr1a_nr9
	s_mov_b32 s8, s9
	s_waitcnt vmcnt(0)
	s_add_u32 s10, s9, 0
	s_mul_i32 s10, s10, 0x6000
	s_add_u32 s38, s56, s10
	s_addc_u32 s39, s57, 0
	global_load_dwordx4 v[54:57], v150, s[58:59] offset:0
	global_load_dwordx4 v[58:61], v150, s[58:59] offset:1024
	global_load_dwordx4 v[62:65], v150, s[58:59] offset:2048
	global_load_dwordx4 v[66:69], v150, s[58:59] offset:3072
	s_add_u32 s44, s38, 0x1000
	s_addc_u32 s45, s39, 0
	global_load_dwordx4 v[70:73], v150, s[44:45] offset:0
	global_load_dwordx4 v[74:77], v150, s[44:45] offset:1024
	global_load_dwordx4 v[78:81], v150, s[44:45] offset:2048
	global_load_dwordx4 v[82:85], v150, s[44:45] offset:3072
	global_load_dwordx4 v[16:19], v150, s[38:39] offset:0
	global_load_dwordx4 v[20:23], v150, s[38:39] offset:1024
	global_load_dwordx4 v[24:27], v150, s[38:39] offset:2048
	global_load_dwordx4 v[28:31], v150, s[38:39] offset:3072
	s_waitcnt vmcnt(0)
	v_add_f32_e32 v70, 1.0, v70
	v_add_f32_e32 v71, 1.0, v71
	v_add_f32_e32 v72, 1.0, v72
	v_add_f32_e32 v73, 1.0, v73
	v_add_f32_e32 v74, 1.0, v74
	v_add_f32_e32 v75, 1.0, v75
	v_add_f32_e32 v76, 1.0, v76
	v_add_f32_e32 v77, 1.0, v77
	v_add_f32_e32 v78, 1.0, v78
	v_add_f32_e32 v79, 1.0, v79
	v_add_f32_e32 v80, 1.0, v80
	v_add_f32_e32 v81, 1.0, v81
	v_add_f32_e32 v82, 1.0, v82
	v_add_f32_e32 v83, 1.0, v83
	v_add_f32_e32 v84, 1.0, v84
	v_add_f32_e32 v85, 1.0, v85
	v_mul_f32_e32 v0, v54, v70
	v_mul_f32_e32 v1, v55, v71
	v_mul_f32_e32 v2, v56, v72
	v_mul_f32_e32 v3, v57, v73
	v_mul_f32_e32 v4, v58, v74
	v_mul_f32_e32 v5, v59, v75
	v_mul_f32_e32 v6, v60, v76
	v_mul_f32_e32 v7, v61, v77
	v_mul_f32_e32 v8, v62, v78
	v_mul_f32_e32 v9, v63, v79
	v_mul_f32_e32 v10, v64, v80
	v_mul_f32_e32 v11, v65, v81
	v_mul_f32_e32 v12, v66, v82
	v_mul_f32_e32 v13, v67, v83
	v_mul_f32_e32 v14, v68, v84
	v_mul_f32_e32 v15, v69, v85
; DI void row1_phase(const Params& P, int combine_l, int norm_l, int r_begin) {
;     ...
;     if (norm_l >= 0) {
;       float ss = 0.f;
; #pragma unroll
;       for (int i = 0; i < 4; i++) ss += xv[i].x * xv[i].x + xv[i].y * xv[i].y + xv[i].z * xv[i].z + xv[i].w * xv[i].w;
;       ss = wave_sum(ss);
;       const float rstd = rsqrtf(ss * (1.f / 1024.f) + EPS);
;       const float* g = P.norm1_g + norm_l * 1024;
;       const float* sh = P.mod + (size_t)(norm_l * 9 + n) * 6144; const float* sc = sh + 1024;
; #pragma unroll
;       for (int i = 0; i < 4; i++) {
;         int c = i * 256 + lane * 4;
;         float4 gg = *(const float4*)(g + c), s1 = *(const float4*)(sc + c), s0 = *(const float4*)(sh + c);
;         h4 o;
;         o[0] = (half_t)(xv[i].x * rstd * gg.x * (1.f + s1.x) + s0.x); o[1] = (half_t)(xv[i].y * rstd * gg.y * (1.f + s1.y) + s0.y);
;         o[2] = (half_t)(xv[i].z * rstd * gg.z * (1.f + s1.z) + s0.z); o[3] = (half_t)(xv[i].w * rstd * gg.w * (1.f + s1.w) + s0.w);
;         *(h4*)(P.hx + (size_t)r * D + c) = o;
;       }
;     }
.Lr1a_nr9:
	s_waitcnt vmcnt(8)
	v_accvgpr_read_b32 v54, a0
	v_accvgpr_read_b32 v55, a1
	v_accvgpr_read_b32 v56, a2
	v_accvgpr_read_b32 v57, a3
	v_accvgpr_read_b32 v58, a4
	v_accvgpr_read_b32 v59, a5
	v_accvgpr_read_b32 v60, a6
	v_accvgpr_read_b32 v61, a7
	v_accvgpr_read_b32 v62, a8
	v_accvgpr_read_b32 v63, a9
	v_accvgpr_read_b32 v64, a10
	v_accvgpr_read_b32 v65, a11
	v_accvgpr_read_b32 v66, a12
	v_accvgpr_read_b32 v67, a13
	v_accvgpr_read_b32 v68, a14
	v_accvgpr_read_b32 v69, a15
	s_lshl_b32 s10, s5, 12
	s_lshr_b32 s10, s10, 1
	s_add_u32 s36, s54, s10
	s_addc_u32 s37, s55, 0
	v_mul_f32_e32 v152, v54, v54
	v_mul_f32_e32 v153, v55, v55
	v_fmac_f32_e32 v152, v56, v56
	v_fmac_f32_e32 v153, v57, v57
	v_fmac_f32_e32 v152, v58, v58
	v_fmac_f32_e32 v153, v59, v59
	v_fmac_f32_e32 v152, v60, v60
	v_fmac_f32_e32 v153, v61, v61
	v_fmac_f32_e32 v152, v62, v62
	v_fmac_f32_e32 v153, v63, v63
	v_fmac_f32_e32 v152, v64, v64
	v_fmac_f32_e32 v153, v65, v65
	v_fmac_f32_e32 v152, v66, v66
	v_fmac_f32_e32 v153, v67, v67
	v_fmac_f32_e32 v152, v68, v68
	v_fmac_f32_e32 v153, v69, v69
	v_add_f32_e32 v152, v152, v153
	s_nop 1
	v_add_f32_dpp v152, v152, v152 row_ror:8 row_mask:0xf bank_mask:0xf
	s_nop 1
	v_add_f32_dpp v152, v152, v152 row_ror:4 row_mask:0xf bank_mask:0xf
	s_nop 1
	v_add_f32_dpp v152, v152, v152 row_ror:2 row_mask:0xf bank_mask:0xf
	s_nop 1
	v_add_f32_dpp v152, v152, v152 row_ror:1 row_mask:0xf bank_mask:0xf
	s_nop 1
	v_readlane_b32 s22, v152, 0
	v_readlane_b32 s23, v152, 16
	v_readlane_b32 s32, v152, 32
	v_readlane_b32 s99, v152, 48
	v_mov_b32_e32 v152, s22
	v_add_f32_e32 v152, s23, v152
	v_add_f32_e32 v152, s32, v152
	v_add_f32_e32 v152, s99, v152
	v_mov_b32_e32 v153, 0x358637bd
	v_fmamk_f32 v152, v152, 0x3a800000, v153
	v_rsq_f32_e32 v152, v152
	s_nop 1
	v_mul_f32_e32 v54, v54, v152
	v_mul_f32_e32 v55, v55, v152
	v_mul_f32_e32 v56, v56, v152
	v_mul_f32_e32 v57, v57, v152
	v_mul_f32_e32 v58, v58, v152
	v_mul_f32_e32 v59, v59, v152
	v_mul_f32_e32 v60, v60, v152
	v_mul_f32_e32 v61, v61, v152
	v_mul_f32_e32 v62, v62, v152
	v_mul_f32_e32 v63, v63, v152
	v_mul_f32_e32 v64, v64, v152
	v_mul_f32_e32 v65, v65, v152
	v_mul_f32_e32 v66, v66, v152
	v_mul_f32_e32 v67, v67, v152
	v_mul_f32_e32 v68, v68, v152
	v_mul_f32_e32 v69, v69, v152
	v_fma_f32 v54, v54, v0, v16
	v_fma_f32 v55, v55, v1, v17
	v_fma_f32 v56, v56, v2, v18
	v_fma_f32 v57, v57, v3, v19
	v_fma_f32 v58, v58, v4, v20
	v_fma_f32 v59, v59, v5, v21
	v_fma_f32 v60, v60, v6, v22
	v_fma_f32 v61, v61, v7, v23
	v_fma_f32 v62, v62, v8, v24
	v_fma_f32 v63, v63, v9, v25
	v_fma_f32 v64, v64, v10, v26
	v_fma_f32 v65, v65, v11, v27
	v_fma_f32 v66, v66, v12, v28
	v_fma_f32 v67, v67, v13, v29
	v_fma_f32 v68, v68, v14, v30
	v_fma_f32 v69, v69, v15, v31
	v_cvt_pk_f16_f32 v70, v54, v55
	v_cvt_pk_f16_f32 v71, v56, v57
	v_cvt_pk_f16_f32 v72, v58, v59
	v_cvt_pk_f16_f32 v73, v60, v61
	v_cvt_pk_f16_f32 v74, v62, v63
	v_cvt_pk_f16_f32 v75, v64, v65
	v_cvt_pk_f16_f32 v76, v66, v67
	v_cvt_pk_f16_f32 v77, v68, v69
	global_store_dwordx2 v151, v[70:71], s[36:37] offset:0 nt
	global_store_dwordx2 v151, v[72:73], s[36:37] offset:512 nt
	global_store_dwordx2 v151, v[74:75], s[36:37] offset:1024 nt
	global_store_dwordx2 v151, v[76:77], s[36:37] offset:1536 nt
	s_add_u32 s5, s5, 1
	s_sub_u32 s9, s5, 0x800
	s_lshr_b32 s9, s9, 13
	s_cmp_lt_u32 s5, 0x800
	s_cselect_b32 s9, 8, s9
	s_cmp_eq_u32 s9, s8
	s_cbranch_scc1 .Lr1a_nr10
	s_mov_b32 s8, s9
	s_waitcnt vmcnt(0)
	s_add_u32 s10, s9, 0
	s_mul_i32 s10, s10, 0x6000
	s_add_u32 s38, s56, s10
	s_addc_u32 s39, s57, 0
	global_load_dwordx4 v[54:57], v150, s[58:59] offset:0
	global_load_dwordx4 v[58:61], v150, s[58:59] offset:1024
	global_load_dwordx4 v[62:65], v150, s[58:59] offset:2048
	global_load_dwordx4 v[66:69], v150, s[58:59] offset:3072
	s_add_u32 s44, s38, 0x1000
	s_addc_u32 s45, s39, 0
	global_load_dwordx4 v[70:73], v150, s[44:45] offset:0
	global_load_dwordx4 v[74:77], v150, s[44:45] offset:1024
	global_load_dwordx4 v[78:81], v150, s[44:45] offset:2048
	global_load_dwordx4 v[82:85], v150, s[44:45] offset:3072
	global_load_dwordx4 v[16:19], v150, s[38:39] offset:0
	global_load_dwordx4 v[20:23], v150, s[38:39] offset:1024
	global_load_dwordx4 v[24:27], v150, s[38:39] offset:2048
	global_load_dwordx4 v[28:31], v150, s[38:39] offset:3072
	s_waitcnt vmcnt(0)
	v_add_f32_e32 v70, 1.0, v70
	v_add_f32_e32 v71, 1.0, v71
	v_add_f32_e32 v72, 1.0, v72
	v_add_f32_e32 v73, 1.0, v73
	v_add_f32_e32 v74, 1.0, v74
	v_add_f32_e32 v75, 1.0, v75
	v_add_f32_e32 v76, 1.0, v76
	v_add_f32_e32 v77, 1.0, v77
	v_add_f32_e32 v78, 1.0, v78
	v_add_f32_e32 v79, 1.0, v79
	v_add_f32_e32 v80, 1.0, v80
	v_add_f32_e32 v81, 1.0, v81
	v_add_f32_e32 v82, 1.0, v82
	v_add_f32_e32 v83, 1.0, v83
	v_add_f32_e32 v84, 1.0, v84
	v_add_f32_e32 v85, 1.0, v85
	v_mul_f32_e32 v0, v54, v70
	v_mul_f32_e32 v1, v55, v71
	v_mul_f32_e32 v2, v56, v72
	v_mul_f32_e32 v3, v57, v73
	v_mul_f32_e32 v4, v58, v74
	v_mul_f32_e32 v5, v59, v75
	v_mul_f32_e32 v6, v60, v76
	v_mul_f32_e32 v7, v61, v77
	v_mul_f32_e32 v8, v62, v78
	v_mul_f32_e32 v9, v63, v79
	v_mul_f32_e32 v10, v64, v80
	v_mul_f32_e32 v11, v65, v81
	v_mul_f32_e32 v12, v66, v82
	v_mul_f32_e32 v13, v67, v83
	v_mul_f32_e32 v14, v68, v84
	v_mul_f32_e32 v15, v69, v85
; DI void row1_phase(const Params& P, int combine_l, int norm_l, int r_begin) {
;     ...
;     if (norm_l >= 0) {
;       float ss = 0.f;
; #pragma unroll
;       for (int i = 0; i < 4; i++) ss += xv[i].x * xv[i].x + xv[i].y * xv[i].y + xv[i].z * xv[i].z + xv[i].w * xv[i].w;
;       ss = wave_sum(ss);
;       const float rstd = rsqrtf(ss * (1.f / 1024.f) + EPS);
;       const float* g = P.norm1_g + norm_l * 1024;
;       const float* sh = P.mod + (size_t)(norm_l * 9 + n) * 6144; const float* sc = sh + 1024;
; #pragma unroll
;       for (int i = 0; i < 4; i++) {
;         int c = i * 256 + lane * 4;
;         float4 gg = *(const float4*)(g + c), s1 = *(const float4*)(sc + c), s0 = *(const float4*)(sh + c);
;         h4 o;
;         o[0] = (half_t)(xv[i].x * rstd * gg.x * (1.f + s1.x) + s0.x); o[1] = (half_t)(xv[i].y * rstd * gg.y * (1.f + s1.y) + s0.y);
;         o[2] = (half_t)(xv[i].z * rstd * gg.z * (1.f + s1.z) + s0.z); o[3] = (half_t)(xv[i].w * rstd * gg.w * (1.f + s1.w) + s0.w);
;         *(h4*)(P.hx + (size_t)r * D + c) = o;
;       }
;     }
.Lr1a_nr10:
	s_waitcnt vmcnt(4)
	v_accvgpr_read_b32 v54, a32
	v_accvgpr_read_b32 v55, a33
	v_accvgpr_read_b32 v56, a34
	v_accvgpr_read_b32 v57, a35
	v_accvgpr_read_b32 v58, a36
	v_accvgpr_read_b32 v59, a37
	v_accvgpr_read_b32 v60, a38
	v_accvgpr_read_b32 v61, a39
	v_accvgpr_read_b32 v62, a40
	v_accvgpr_read_b32 v63, a41
	v_accvgpr_read_b32 v64, a42
	v_accvgpr_read_b32 v65, a43
	v_accvgpr_read_b32 v66, a44
	v_accvgpr_read_b32 v67, a45
	v_accvgpr_read_b32 v68, a46
	v_accvgpr_read_b32 v69, a47
	s_lshl_b32 s10, s5, 12
	s_lshr_b32 s10, s10, 1
	s_add_u32 s36, s54, s10
	s_addc_u32 s37, s55, 0
	v_mul_f32_e32 v152, v54, v54
	v_mul_f32_e32 v153, v55, v55
	v_fmac_f32_e32 v152, v56, v56
	v_fmac_f32_e32 v153, v57, v57
	v_fmac_f32_e32 v152, v58, v58
	v_fmac_f32_e32 v153, v59, v59
	v_fmac_f32_e32 v152, v60, v60
	v_fmac_f32_e32 v153, v61, v61
	v_fmac_f32_e32 v152, v62, v62
	v_fmac_f32_e32 v153, v63, v63
	v_fmac_f32_e32 v152, v64, v64
	v_fmac_f32_e32 v153, v65, v65
	v_fmac_f32_e32 v152, v66, v66
	v_fmac_f32_e32 v153, v67, v67
	v_fmac_f32_e32 v152, v68, v68
	v_fmac_f32_e32 v153, v69, v69
	v_add_f32_e32 v152, v152, v153
	s_nop 1
	v_add_f32_dpp v152, v152, v152 row_ror:8 row_mask:0xf bank_mask:0xf
	s_nop 1
	v_add_f32_dpp v152, v152, v152 row_ror:4 row_mask:0xf bank_mask:0xf
	s_nop 1
	v_add_f32_dpp v152, v152, v152 row_ror:2 row_mask:0xf bank_mask:0xf
	s_nop 1
	v_add_f32_dpp v152, v152, v152 row_ror:1 row_mask:0xf bank_mask:0xf
	s_nop 1
	v_readlane_b32 s22, v152, 0
	v_readlane_b32 s23, v152, 16
	v_readlane_b32 s32, v152, 32
	v_readlane_b32 s99, v152, 48
	v_mov_b32_e32 v152, s22
	v_add_f32_e32 v152, s23, v152
	v_add_f32_e32 v152, s32, v152
	v_add_f32_e32 v152, s99, v152
	v_mov_b32_e32 v153, 0x358637bd
	v_fmamk_f32 v152, v152, 0x3a800000, v153
	v_rsq_f32_e32 v152, v152
	s_nop 1
	v_mul_f32_e32 v54, v54, v152
	v_mul_f32_e32 v55, v55, v152
	v_mul_f32_e32 v56, v56, v152
	v_mul_f32_e32 v57, v57, v152
	v_mul_f32_e32 v58, v58, v152
	v_mul_f32_e32 v59, v59, v152
	v_mul_f32_e32 v60, v60, v152
	v_mul_f32_e32 v61, v61, v152
	v_mul_f32_e32 v62, v62, v152
	v_mul_f32_e32 v63, v63, v152
	v_mul_f32_e32 v64, v64, v152
	v_mul_f32_e32 v65, v65, v152
	v_mul_f32_e32 v66, v66, v152
	v_mul_f32_e32 v67, v67, v152
	v_mul_f32_e32 v68, v68, v152
	v_mul_f32_e32 v69, v69, v152
	v_fma_f32 v54, v54, v0, v16
	v_fma_f32 v55, v55, v1, v17
	v_fma_f32 v56, v56, v2, v18
	v_fma_f32 v57, v57, v3, v19
	v_fma_f32 v58, v58, v4, v20
	v_fma_f32 v59, v59, v5, v21
	v_fma_f32 v60, v60, v6, v22
	v_fma_f32 v61, v61, v7, v23
	v_fma_f32 v62, v62, v8, v24
	v_fma_f32 v63, v63, v9, v25
	v_fma_f32 v64, v64, v10, v26
	v_fma_f32 v65, v65, v11, v27
	v_fma_f32 v66, v66, v12, v28
	v_fma_f32 v67, v67, v13, v29
	v_fma_f32 v68, v68, v14, v30
	v_fma_f32 v69, v69, v15, v31
	v_cvt_pk_f16_f32 v70, v54, v55
	v_cvt_pk_f16_f32 v71, v56, v57
	v_cvt_pk_f16_f32 v72, v58, v59
	v_cvt_pk_f16_f32 v73, v60, v61
	v_cvt_pk_f16_f32 v74, v62, v63
	v_cvt_pk_f16_f32 v75, v64, v65
	v_cvt_pk_f16_f32 v76, v66, v67
	v_cvt_pk_f16_f32 v77, v68, v69
	global_store_dwordx2 v151, v[70:71], s[36:37] offset:0 nt
	global_store_dwordx2 v151, v[72:73], s[36:37] offset:512 nt
	global_store_dwordx2 v151, v[74:75], s[36:37] offset:1024 nt
	global_store_dwordx2 v151, v[76:77], s[36:37] offset:1536 nt
	s_add_u32 s5, s5, 1
	s_waitcnt vmcnt(0)
